# prefetch gate_b loads in the P5 GEMM epilogue (both layers) into a register pool, counted vmcnt instead of 16 serialized round trips
# speedup vs baseline: 1.0208x; 1.0208x over previous
; #define PG8_STAGE(bufoff, gbase, voff) do { _Pragma("unroll") for (int _i = 0; _i < 2; ++_i) \
;         __builtin_amdgcn_global_load_lds((const unsigned*)((const char*)(gbase) + (voff)[_i]), (LAS unsigned*)(lds + (bufoff) + ldsw + _i * 8192), 16, 0, 0); } while (0)
; #define PG8_LDA(dst, b, h) do { _Pragma("unroll") for (int m = 0; m < 4; ++m) _Pragma("unroll") for (int k = 0; k < 2; ++k) dst[m][k] = *(const LAS bf16x8*)(lds + PG8_SA(b, h) + aoff + m * 2048 + k * 1024); } while (0)
; #define PG8_LDB(dst, b, h) do { _Pragma("unroll") for (int n = 0; n < 2; ++n) _Pragma("unroll") for (int k = 0; k < 2; ++k) dst[n][k] = *(const LAS bf16x8*)(lds + PG8_SB(b, h) + boff + n * 2048 + k * 1024); } while (0)
; #define PG8_MMA(ai, bj, At, Bt) do { __builtin_amdgcn_s_setprio(1); _Pragma("unroll") for (int m = 0; m < 4; ++m) _Pragma("unroll") for (int n = 0; n < 2; ++n) _Pragma("unroll") for (int k = 0; k < 2; ++k) \
;         acc[ai][bj][m][n] = __builtin_amdgcn_mfma_f32_16x16x32_bf16(Bt[n][k], At[m][k], acc[ai][bj][m][n], 0, 0, 0); __builtin_amdgcn_s_setprio(0); } while (0)
; #define PG8_WAIT_L(n) asm volatile("s_waitcnt lgkmcnt(" #n ")" ::: "memory")
; #define PG8_BAR __builtin_amdgcn_s_barrier()
; #define PG8_SCHED __builtin_amdgcn_sched_barrier(0)
;     ...
;             PG8_LDB(B0, 0, 0); PG8_SCHED; PG8_LDA(At, 0, 0); PG8_STAGE(PG8_SA(1, 1), a1 + hA, voffA);
;             PG8_WAIT_L(8); PG8_BAR; PG8_WAIT_L(0); PG8_MMA(0, 0, At, B0); PG8_BAR; PG8_SCHED;
;             PG8_LDB(B1, 0, 1); PG8_STAGE(PG8_SB(0, 0), b2, voffB);
;             PG8_BAR; PG8_WAIT_L(0); PG8_MMA(0, 1, At, B1); PG8_BAR;
;             PG8_LDA(At, 0, 1); PG8_STAGE(PG8_SA(0, 0), a2, voffA);
;             PG8_BAR; PG8_WAIT_L(0); PG8_MMA(1, 0, At, B0); PG8_BAR; PG8_SCHED;
.LBB0_627:
	ds_read_b128 v[146:149], v157
	ds_read_b128 v[150:153], v157 offset:1024
	ds_read_b128 v[160:163], v157 offset:2048
	ds_read_b128 v[170:173], v157 offset:3072
	s_add_u32 s12, s14, 0x100
	s_addc_u32 s13, s15, 0
	s_cmp_eq_u32 s42, 4
	s_cselect_b32 s19, s31, s13
	s_cselect_b32 s18, s30, s12
	s_cselect_b32 s17, s8, s33
	s_cselect_b32 s16, s9, s29
	v_lshl_add_u64 v[164:165], s[14:15], 0, v[138:139]
	s_add_i32 m0, s39, 0xc000
	ds_read_b128 v[174:177], v158
	ds_read_b128 v[178:181], v158 offset:1024
	ds_read_b128 v[182:185], v158 offset:2048
	ds_read_b128 v[186:189], v158 offset:3072
	ds_read_b128 v[190:193], v158 offset:4096
	ds_read_b128 v[194:197], v158 offset:5120
	ds_read_b128 v[198:201], v158 offset:6144
	ds_read_b128 v[202:205], v158 offset:7168
	global_load_lds_dwordx4 v[164:165], off
	v_lshl_add_u64 v[164:165], s[14:15], 0, v[136:137]
	s_add_i32 m0, s39, 0xe000
	s_nop 0
	global_load_lds_dwordx4 v[164:165], off
	s_waitcnt lgkmcnt(8)
	s_barrier
	s_waitcnt lgkmcnt(0)
	s_setprio 1
	s_waitcnt lgkmcnt(0)
	v_mfma_f32_16x16x32_bf16 v[124:127], v[146:149], v[174:177], v[124:127]
	v_mfma_f32_16x16x32_bf16 v[120:123], v[160:163], v[174:177], v[120:123]
	v_mfma_f32_16x16x32_bf16 v[108:111], v[146:149], v[182:185], v[108:111]
	v_mfma_f32_16x16x32_bf16 v[104:107], v[160:163], v[182:185], v[104:107]
	v_mfma_f32_16x16x32_bf16 v[92:95], v[146:149], v[190:193], v[92:95]
	v_mfma_f32_16x16x32_bf16 v[88:91], v[160:163], v[190:193], v[88:91]
	v_mfma_f32_16x16x32_bf16 v[76:79], v[146:149], v[198:201], v[76:79]
	v_mfma_f32_16x16x32_bf16 v[72:75], v[160:163], v[198:201], v[72:75]
	v_mfma_f32_16x16x32_bf16 v[124:127], v[150:153], v[178:181], v[124:127]
	v_mfma_f32_16x16x32_bf16 v[120:123], v[170:173], v[178:181], v[120:123]
	v_mfma_f32_16x16x32_bf16 v[108:111], v[150:153], v[186:189], v[108:111]
	v_mfma_f32_16x16x32_bf16 v[104:107], v[170:173], v[186:189], v[104:107]
	v_mfma_f32_16x16x32_bf16 v[92:95], v[150:153], v[194:197], v[92:95]
	v_mfma_f32_16x16x32_bf16 v[88:91], v[170:173], v[194:197], v[88:91]
	v_mfma_f32_16x16x32_bf16 v[76:79], v[150:153], v[202:205], v[76:79]
	v_mfma_f32_16x16x32_bf16 v[72:75], v[170:173], v[202:205], v[72:75]
	s_setprio 0
	s_barrier
	s_add_i32 s14, s59, s37
	v_lshl_add_u64 v[164:165], s[16:17], 0, v[132:133]
	s_mov_b32 m0, s14
	ds_read_b128 v[206:209], v159
	ds_read_b128 v[210:213], v159 offset:1024
	ds_read_b128 v[214:217], v159 offset:2048
	ds_read_b128 v[218:221], v159 offset:3072
	global_load_lds_dwordx4 v[164:165], off
	v_lshl_add_u64 v[222:223], s[16:17], 0, v[128:129]
	s_add_i32 m0, s14, 0x2000
	s_nop 0
	global_load_lds_dwordx4 v[222:223], off
	s_barrier
	s_waitcnt lgkmcnt(0)
	s_setprio 1
	s_waitcnt lgkmcnt(0)
	v_mfma_f32_16x16x32_bf16 v[116:119], v[206:209], v[174:177], v[116:119]
	v_mfma_f32_16x16x32_bf16 v[112:115], v[214:217], v[174:177], v[112:115]
	v_mfma_f32_16x16x32_bf16 v[100:103], v[206:209], v[182:185], v[100:103]
	v_mfma_f32_16x16x32_bf16 v[96:99], v[214:217], v[182:185], v[96:99]
	v_mfma_f32_16x16x32_bf16 v[84:87], v[206:209], v[190:193], v[84:87]
	v_mfma_f32_16x16x32_bf16 v[80:83], v[214:217], v[190:193], v[80:83]
	v_mfma_f32_16x16x32_bf16 v[68:71], v[206:209], v[198:201], v[68:71]
	v_mfma_f32_16x16x32_bf16 v[64:67], v[214:217], v[198:201], v[64:67]
	v_mfma_f32_16x16x32_bf16 v[116:119], v[210:213], v[178:181], v[116:119]
	v_mfma_f32_16x16x32_bf16 v[112:115], v[218:221], v[178:181], v[112:115]
	v_mfma_f32_16x16x32_bf16 v[100:103], v[210:213], v[186:189], v[100:103]
	v_mfma_f32_16x16x32_bf16 v[96:99], v[218:221], v[186:189], v[96:99]
	v_mfma_f32_16x16x32_bf16 v[84:87], v[210:213], v[194:197], v[84:87]
	v_mfma_f32_16x16x32_bf16 v[80:83], v[218:221], v[194:197], v[80:83]
	v_mfma_f32_16x16x32_bf16 v[68:71], v[210:213], v[202:205], v[68:71]
	v_mfma_f32_16x16x32_bf16 v[64:67], v[218:221], v[202:205], v[64:67]
	s_setprio 0
	s_mov_b32 m0, s39
	v_lshl_add_u64 v[224:225], s[18:19], 0, v[134:135]
	s_barrier
	ds_read_b128 v[174:177], v158 offset:16384
	ds_read_b128 v[178:181], v158 offset:17408
	ds_read_b128 v[182:185], v158 offset:18432
	ds_read_b128 v[186:189], v158 offset:19456
	ds_read_b128 v[190:193], v158 offset:20480
	ds_read_b128 v[194:197], v158 offset:21504
	ds_read_b128 v[198:201], v158 offset:22528
	ds_read_b128 v[202:205], v158 offset:23552
	global_load_lds_dwordx4 v[224:225], off
	v_lshl_add_u64 v[226:227], s[18:19], 0, v[130:131]
	s_mov_b32 m0, s51
	s_nop 0
	global_load_lds_dwordx4 v[226:227], off
	s_barrier
	s_waitcnt lgkmcnt(0)
	s_setprio 1
	s_waitcnt lgkmcnt(0)
	v_mfma_f32_16x16x32_bf16 v[60:63], v[146:149], v[174:177], v[60:63]
	v_mfma_f32_16x16x32_bf16 v[56:59], v[160:163], v[174:177], v[56:59]
	v_mfma_f32_16x16x32_bf16 v[44:47], v[146:149], v[182:185], v[44:47]
	v_mfma_f32_16x16x32_bf16 v[40:43], v[160:163], v[182:185], v[40:43]
	v_mfma_f32_16x16x32_bf16 v[28:31], v[146:149], v[190:193], v[28:31]
	v_mfma_f32_16x16x32_bf16 v[24:27], v[160:163], v[190:193], v[24:27]
	v_mfma_f32_16x16x32_bf16 v[12:15], v[146:149], v[198:201], v[12:15]
	v_mfma_f32_16x16x32_bf16 v[8:11], v[160:163], v[198:201], v[8:11]
	v_mfma_f32_16x16x32_bf16 v[60:63], v[150:153], v[178:181], v[60:63]
	v_mfma_f32_16x16x32_bf16 v[56:59], v[170:173], v[178:181], v[56:59]
	v_mfma_f32_16x16x32_bf16 v[44:47], v[150:153], v[186:189], v[44:47]
	v_mfma_f32_16x16x32_bf16 v[40:43], v[170:173], v[186:189], v[40:43]
	v_mfma_f32_16x16x32_bf16 v[28:31], v[150:153], v[194:197], v[28:31]
	v_mfma_f32_16x16x32_bf16 v[24:27], v[170:173], v[194:197], v[24:27]
	v_mfma_f32_16x16x32_bf16 v[12:15], v[150:153], v[202:205], v[12:15]
	v_mfma_f32_16x16x32_bf16 v[8:11], v[170:173], v[202:205], v[8:11]
	s_setprio 0
	s_barrier
; #define PG8_STAGE(bufoff, gbase, voff) do { _Pragma("unroll") for (int _i = 0; _i < 2; ++_i) \
;         __builtin_amdgcn_global_load_lds((const unsigned*)((const char*)(gbase) + (voff)[_i]), (LAS unsigned*)(lds + (bufoff) + ldsw + _i * 8192), 16, 0, 0); } while (0)
; #define PG8_LDA(dst, b, h) do { _Pragma("unroll") for (int m = 0; m < 4; ++m) _Pragma("unroll") for (int k = 0; k < 2; ++k) dst[m][k] = *(const LAS bf16x8*)(lds + PG8_SA(b, h) + aoff + m * 2048 + k * 1024); } while (0)
; #define PG8_LDB(dst, b, h) do { _Pragma("unroll") for (int n = 0; n < 2; ++n) _Pragma("unroll") for (int k = 0; k < 2; ++k) dst[n][k] = *(const LAS bf16x8*)(lds + PG8_SB(b, h) + boff + n * 2048 + k * 1024); } while (0)
; #define PG8_MMA(ai, bj, At, Bt) do { __builtin_amdgcn_s_setprio(1); _Pragma("unroll") for (int m = 0; m < 4; ++m) _Pragma("unroll") for (int n = 0; n < 2; ++n) _Pragma("unroll") for (int k = 0; k < 2; ++k) \
;         acc[ai][bj][m][n] = __builtin_amdgcn_mfma_f32_16x16x32_bf16(Bt[n][k], At[m][k], acc[ai][bj][m][n], 0, 0, 0); __builtin_amdgcn_s_setprio(0); } while (0)
; #define PG8_WAIT_V(n) asm volatile("s_waitcnt vmcnt(" #n ")" ::: "memory")
; #define PG8_WAIT_L(n) asm volatile("s_waitcnt lgkmcnt(" #n ")" ::: "memory")
; #define PG8_BAR __builtin_amdgcn_s_barrier()
; #define PG8_SCHED __builtin_amdgcn_sched_barrier(0)
;     ...
;             PG8_STAGE(PG8_SB(0, 1), b2 + hB, voffB);
;             PG8_WAIT_V(6); PG8_BAR; PG8_MMA(1, 1, At, B1); PG8_BAR;
;             PG8_LDB(B0, 1, 0); PG8_SCHED; PG8_LDA(At, 1, 0); PG8_STAGE(PG8_SA(0, 1), a2 + hA, voffA);
;             PG8_WAIT_L(8); PG8_BAR; PG8_WAIT_L(0); PG8_MMA(0, 0, At, B0); PG8_BAR; PG8_SCHED;
;             PG8_LDB(B1, 1, 1); PG8_STAGE(PG8_SB(1, 0), b3, voffB);
;             PG8_BAR; PG8_WAIT_L(0); PG8_MMA(0, 1, At, B1); PG8_BAR;
;             PG8_LDA(At, 1, 1); PG8_STAGE(PG8_SA(1, 0), a3, voffA);
	s_add_u32 s14, s16, 0x20000
	s_addc_u32 s15, s17, 0
	s_add_i32 s43, s60, s37
	v_lshl_add_u64 v[146:147], s[14:15], 0, v[132:133]
	s_mov_b32 m0, s43
	s_nop 0
	global_load_lds_dwordx4 v[146:147], off
	v_lshl_add_u64 v[146:147], s[14:15], 0, v[128:129]
	s_add_i32 m0, s43, 0x2000
	s_nop 0
	global_load_lds_dwordx4 v[146:147], off
	s_waitcnt vmcnt(6)
	s_barrier
	s_setprio 1
	v_mfma_f32_16x16x32_bf16 v[52:55], v[206:209], v[174:177], v[52:55]
	v_mfma_f32_16x16x32_bf16 v[48:51], v[214:217], v[174:177], v[48:51]
	v_mfma_f32_16x16x32_bf16 v[36:39], v[206:209], v[182:185], v[36:39]
	v_mfma_f32_16x16x32_bf16 v[32:35], v[214:217], v[182:185], v[32:35]
	v_mfma_f32_16x16x32_bf16 v[20:23], v[206:209], v[190:193], v[20:23]
	v_mfma_f32_16x16x32_bf16 v[16:19], v[214:217], v[190:193], v[16:19]
	v_mfma_f32_16x16x32_bf16 v[4:7], v[206:209], v[198:201], v[4:7]
	v_mfma_f32_16x16x32_bf16 v[0:3], v[214:217], v[198:201], v[0:3]
	v_mfma_f32_16x16x32_bf16 v[52:55], v[210:213], v[178:181], v[52:55]
	v_mfma_f32_16x16x32_bf16 v[48:51], v[218:221], v[178:181], v[48:51]
	v_mfma_f32_16x16x32_bf16 v[36:39], v[210:213], v[186:189], v[36:39]
	v_mfma_f32_16x16x32_bf16 v[32:35], v[218:221], v[186:189], v[32:35]
	v_mfma_f32_16x16x32_bf16 v[20:23], v[210:213], v[194:197], v[20:23]
	v_mfma_f32_16x16x32_bf16 v[16:19], v[218:221], v[194:197], v[16:19]
	v_mfma_f32_16x16x32_bf16 v[4:7], v[210:213], v[202:205], v[4:7]
	v_mfma_f32_16x16x32_bf16 v[0:3], v[218:221], v[202:205], v[0:3]
	s_setprio 0
	s_add_i32 s43, 0, 0x18000
	v_add_u32_e32 v170, s43, v155
	s_barrier
	ds_read_b128 v[146:149], v170
	ds_read_b128 v[150:153], v170 offset:1024
	ds_read_b128 v[160:163], v170 offset:2048
	ds_read_b128 v[170:173], v170 offset:3072
	s_add_u32 s14, s18, 0x110000
	s_addc_u32 s15, s19, 0
	s_mov_b32 m0, s53
	v_lshl_add_u64 v[206:207], s[14:15], 0, v[134:135]
	ds_read_b128 v[174:177], v158 offset:32768
	ds_read_b128 v[178:181], v158 offset:33792
	ds_read_b128 v[182:185], v158 offset:34816
	ds_read_b128 v[186:189], v158 offset:35840
	ds_read_b128 v[190:193], v158 offset:36864
	ds_read_b128 v[194:197], v158 offset:37888
	ds_read_b128 v[198:201], v158 offset:38912
	ds_read_b128 v[202:205], v158 offset:39936
	global_load_lds_dwordx4 v[206:207], off
	v_lshl_add_u64 v[206:207], s[14:15], 0, v[130:131]
	s_mov_b32 m0, s54
	s_nop 0
	global_load_lds_dwordx4 v[206:207], off
	s_waitcnt lgkmcnt(8)
	s_barrier
	s_waitcnt lgkmcnt(0)
	s_setprio 1
	s_waitcnt lgkmcnt(0)
	v_mfma_f32_16x16x32_bf16 v[124:127], v[146:149], v[174:177], v[124:127]
	v_mfma_f32_16x16x32_bf16 v[120:123], v[160:163], v[174:177], v[120:123]
	v_mfma_f32_16x16x32_bf16 v[108:111], v[146:149], v[182:185], v[108:111]
	v_mfma_f32_16x16x32_bf16 v[104:107], v[160:163], v[182:185], v[104:107]
	v_mfma_f32_16x16x32_bf16 v[92:95], v[146:149], v[190:193], v[92:95]
	v_mfma_f32_16x16x32_bf16 v[88:91], v[160:163], v[190:193], v[88:91]
	v_mfma_f32_16x16x32_bf16 v[76:79], v[146:149], v[198:201], v[76:79]
	v_mfma_f32_16x16x32_bf16 v[72:75], v[160:163], v[198:201], v[72:75]
	v_mfma_f32_16x16x32_bf16 v[124:127], v[150:153], v[178:181], v[124:127]
	v_mfma_f32_16x16x32_bf16 v[120:123], v[170:173], v[178:181], v[120:123]
	v_mfma_f32_16x16x32_bf16 v[108:111], v[150:153], v[186:189], v[108:111]
	v_mfma_f32_16x16x32_bf16 v[104:107], v[170:173], v[186:189], v[104:107]
	v_mfma_f32_16x16x32_bf16 v[92:95], v[150:153], v[194:197], v[92:95]
	v_mfma_f32_16x16x32_bf16 v[88:91], v[170:173], v[194:197], v[88:91]
	v_mfma_f32_16x16x32_bf16 v[76:79], v[150:153], v[202:205], v[76:79]
	v_mfma_f32_16x16x32_bf16 v[72:75], v[170:173], v[202:205], v[72:75]
	s_setprio 0
	s_barrier
	s_add_i32 s18, 0, 0x1c000
	s_add_i32 s14, s43, s37
	v_add_u32_e32 v218, s18, v155
	v_lshl_add_u64 v[164:165], v[164:165], 0, s[26:27]
	s_mov_b32 m0, s14
	ds_read_b128 v[206:209], v218
	ds_read_b128 v[210:213], v218 offset:1024
	ds_read_b128 v[214:217], v218 offset:2048
	ds_read_b128 v[218:221], v218 offset:3072
	global_load_lds_dwordx4 v[164:165], off
	v_lshl_add_u64 v[164:165], v[222:223], 0, s[26:27]
	s_add_i32 m0, s14, 0x2000
	s_nop 0
	global_load_lds_dwordx4 v[164:165], off
	s_barrier
	s_waitcnt lgkmcnt(0)
	s_setprio 1
	s_waitcnt lgkmcnt(0)
	v_mfma_f32_16x16x32_bf16 v[116:119], v[206:209], v[174:177], v[116:119]
	v_mfma_f32_16x16x32_bf16 v[112:115], v[214:217], v[174:177], v[112:115]
	v_mfma_f32_16x16x32_bf16 v[100:103], v[206:209], v[182:185], v[100:103]
	v_mfma_f32_16x16x32_bf16 v[96:99], v[214:217], v[182:185], v[96:99]
	v_mfma_f32_16x16x32_bf16 v[84:87], v[206:209], v[190:193], v[84:87]
	v_mfma_f32_16x16x32_bf16 v[80:83], v[214:217], v[190:193], v[80:83]
	v_mfma_f32_16x16x32_bf16 v[68:71], v[206:209], v[198:201], v[68:71]
	v_mfma_f32_16x16x32_bf16 v[64:67], v[214:217], v[198:201], v[64:67]
	v_mfma_f32_16x16x32_bf16 v[116:119], v[210:213], v[178:181], v[116:119]
	v_mfma_f32_16x16x32_bf16 v[112:115], v[218:221], v[178:181], v[112:115]
	v_mfma_f32_16x16x32_bf16 v[100:103], v[210:213], v[186:189], v[100:103]
	v_mfma_f32_16x16x32_bf16 v[96:99], v[218:221], v[186:189], v[96:99]
	v_mfma_f32_16x16x32_bf16 v[84:87], v[210:213], v[194:197], v[84:87]
	v_mfma_f32_16x16x32_bf16 v[80:83], v[218:221], v[194:197], v[80:83]
	v_mfma_f32_16x16x32_bf16 v[68:71], v[210:213], v[202:205], v[68:71]
	v_mfma_f32_16x16x32_bf16 v[64:67], v[218:221], v[202:205], v[64:67]
	s_setprio 0
	s_mov_b32 m0, s56
	v_lshl_add_u64 v[164:165], v[224:225], 0, s[26:27]
	s_barrier
	ds_read_b128 v[174:177], v158 offset:49152
	ds_read_b128 v[178:181], v158 offset:50176
	ds_read_b128 v[182:185], v158 offset:51200
	ds_read_b128 v[186:189], v158 offset:52224
	ds_read_b128 v[190:193], v158 offset:53248
	ds_read_b128 v[194:197], v158 offset:54272
	ds_read_b128 v[198:201], v158 offset:55296
	ds_read_b128 v[202:205], v158 offset:56320
	global_load_lds_dwordx4 v[164:165], off
	v_lshl_add_u64 v[164:165], v[226:227], 0, s[26:27]
	s_mov_b32 m0, s57
	s_nop 0
	global_load_lds_dwordx4 v[164:165], off
	s_barrier
; __device__ __forceinline__ float sigmoidf_(float x) { return 1.0f / (1.0f + __expf(-x)); }
; #define PG8_STAGE(bufoff, gbase, voff) do { _Pragma("unroll") for (int _i = 0; _i < 2; ++_i) \
;         __builtin_amdgcn_global_load_lds((const unsigned*)((const char*)(gbase) + (voff)[_i]), (LAS unsigned*)(lds + (bufoff) + ldsw + _i * 8192), 16, 0, 0); } while (0)
; #define PG8_MMA(ai, bj, At, Bt) do { __builtin_amdgcn_s_setprio(1); _Pragma("unroll") for (int m = 0; m < 4; ++m) _Pragma("unroll") for (int n = 0; n < 2; ++n) _Pragma("unroll") for (int k = 0; k < 2; ++k) \
;         acc[ai][bj][m][n] = __builtin_amdgcn_mfma_f32_16x16x32_bf16(Bt[n][k], At[m][k], acc[ai][bj][m][n], 0, 0, 0); __builtin_amdgcn_s_setprio(0); } while (0)
; #define PG8_WAIT_V(n) asm volatile("s_waitcnt vmcnt(" #n ")" ::: "memory")
; #define PG8_WAIT_L(n) asm volatile("s_waitcnt lgkmcnt(" #n ")" ::: "memory")
; #define PG8_BAR __builtin_amdgcn_s_barrier()
; #define PG8_SCHED __builtin_amdgcn_sched_barrier(0)
; __device__ __forceinline__ void unpack8(const u32x4 w, f32x4& v0, f32x4& v1) { v0 = (f32x4){bflo(w.x), bfhi(w.x), bflo(w.y), bfhi(w.y)}; v1 = (f32x4){bflo(w.z), bfhi(w.z), bflo(w.w), bfhi(w.w)}; }
;     ...
;             PG8_BAR; PG8_WAIT_L(0); PG8_MMA(1, 0, At, B0); PG8_BAR; PG8_SCHED;
;             PG8_STAGE(PG8_SB(1, 1), b3 + hB, voffB);
;             PG8_WAIT_V(6); PG8_BAR; PG8_MMA(1, 1, At, B1); PG8_BAR;
;         }
;         E(acc, cur, wr, wc, fr, fq);
;     __device__ __forceinline__ void operator()(const f32x4 (&acc)[2][2][4][2], const Unit& u, int wr, int wc, int fr, int fq) const {
;         const int row0 = u.pm * 256 + wr * 64 + fr, col0 = u.pn * 256 + wc * 32 + 8 * fq;
; #pragma unroll
;         for (int ai = 0; ai < 2; ++ai)
; #pragma unroll
;             for (int m = 0; m < 4; ++m) {
;                 bf16_t* rowp = z + (size_t)(row0 + ai * 128 + m * 16) * DIN + col0;
; #pragma unroll
;                 for (int bj = 0; bj < 2; ++bj) {
;                     const u32x4 gw = *(const u32x4*)(rowp + (MODE == 0 ? O_GB : O_GA) + bj * 128);
;                     f32x4 g0, g1; unpack8(gw, g0, g1);
;                     f32x4 v0, v1;
; #pragma unroll
;                     for (int j = 0; j < 4; ++j) { v0[j] = sigmoidf_(g0[j]) * acc[ai][bj][m][0][j]; v1[j] = sigmoidf_(g1[j]) * acc[ai][bj][m][1][j]; }
	s_waitcnt lgkmcnt(0)
	s_setprio 1
	s_waitcnt lgkmcnt(0)
	v_mfma_f32_16x16x32_bf16 v[60:63], v[146:149], v[174:177], v[60:63]
	v_mfma_f32_16x16x32_bf16 v[56:59], v[160:163], v[174:177], v[56:59]
	v_mfma_f32_16x16x32_bf16 v[44:47], v[146:149], v[182:185], v[44:47]
	v_mfma_f32_16x16x32_bf16 v[40:43], v[160:163], v[182:185], v[40:43]
	v_mfma_f32_16x16x32_bf16 v[28:31], v[146:149], v[190:193], v[28:31]
	v_mfma_f32_16x16x32_bf16 v[24:27], v[160:163], v[190:193], v[24:27]
	v_mfma_f32_16x16x32_bf16 v[12:15], v[146:149], v[198:201], v[12:15]
	v_mfma_f32_16x16x32_bf16 v[8:11], v[160:163], v[198:201], v[8:11]
	v_mfma_f32_16x16x32_bf16 v[60:63], v[150:153], v[178:181], v[60:63]
	v_mfma_f32_16x16x32_bf16 v[56:59], v[170:173], v[178:181], v[56:59]
	v_mfma_f32_16x16x32_bf16 v[44:47], v[150:153], v[186:189], v[44:47]
	v_mfma_f32_16x16x32_bf16 v[40:43], v[170:173], v[186:189], v[40:43]
	v_mfma_f32_16x16x32_bf16 v[28:31], v[150:153], v[194:197], v[28:31]
	v_mfma_f32_16x16x32_bf16 v[24:27], v[170:173], v[194:197], v[24:27]
	v_mfma_f32_16x16x32_bf16 v[12:15], v[150:153], v[202:205], v[12:15]
	v_mfma_f32_16x16x32_bf16 v[8:11], v[170:173], v[202:205], v[8:11]
	s_setprio 0
	s_barrier
	s_add_u32 s14, s16, 0x20080
	s_addc_u32 s15, s17, 0
	s_add_i32 s16, s18, s37
	v_lshl_add_u64 v[146:147], s[14:15], 0, v[132:133]
	s_mov_b32 m0, s16
	s_nop 0
	global_load_lds_dwordx4 v[146:147], off
	v_lshl_add_u64 v[146:147], s[14:15], 0, v[128:129]
	s_add_i32 m0, s16, 0x2000
	s_nop 0
	global_load_lds_dwordx4 v[146:147], off
	s_waitcnt vmcnt(6)
	s_barrier
	s_setprio 1
	v_mfma_f32_16x16x32_bf16 v[52:55], v[206:209], v[174:177], v[52:55]
	v_mfma_f32_16x16x32_bf16 v[48:51], v[214:217], v[174:177], v[48:51]
	v_mfma_f32_16x16x32_bf16 v[36:39], v[206:209], v[182:185], v[36:39]
	v_mfma_f32_16x16x32_bf16 v[32:35], v[214:217], v[182:185], v[32:35]
	v_mfma_f32_16x16x32_bf16 v[20:23], v[206:209], v[190:193], v[20:23]
	v_mfma_f32_16x16x32_bf16 v[16:19], v[214:217], v[190:193], v[16:19]
	v_mfma_f32_16x16x32_bf16 v[4:7], v[206:209], v[198:201], v[4:7]
	v_mfma_f32_16x16x32_bf16 v[0:3], v[214:217], v[198:201], v[0:3]
	v_mfma_f32_16x16x32_bf16 v[52:55], v[210:213], v[178:181], v[52:55]
	v_mfma_f32_16x16x32_bf16 v[48:51], v[218:221], v[178:181], v[48:51]
	v_mfma_f32_16x16x32_bf16 v[36:39], v[210:213], v[186:189], v[36:39]
	v_mfma_f32_16x16x32_bf16 v[32:35], v[218:221], v[186:189], v[32:35]
	v_mfma_f32_16x16x32_bf16 v[20:23], v[210:213], v[194:197], v[20:23]
	v_mfma_f32_16x16x32_bf16 v[16:19], v[218:221], v[194:197], v[16:19]
	v_mfma_f32_16x16x32_bf16 v[4:7], v[210:213], v[202:205], v[4:7]
	v_mfma_f32_16x16x32_bf16 v[0:3], v[218:221], v[202:205], v[0:3]
	s_setprio 0
	s_add_i32 s42, s42, 2
	s_add_u32 s29, s29, 0x100
	s_addc_u32 s33, s33, 0
	s_cmp_gt_u32 s42, 5
	s_mov_b64 s[14:15], s[12:13]
	s_barrier
	s_cbranch_scc0 .LBB0_627
	v_lshl_or_b32 v148, s7, 8, v156
	v_lshl_add_u32 v160, s6, 8, v154
	v_ashrrev_i32_e32 v149, 31, v148
	v_mov_b64_e32 v[146:147], s[24:25]
	v_mad_i64_i32 v[150:151], s[6:7], v160, s61, v[146:147]
	v_lshlrev_b64 v[148:149], 1, v[148:149]
	v_lshl_add_u64 v[150:151], v[150:151], 0, v[148:149]
	v_add_co_u32_e32 v152, vcc, 0x1000, v150
	s_nop 1
	v_addc_co_u32_e32 v153, vcc, 0, v151, vcc
	v_subrev_u32_e32 v198, s24, v150
	v_add_u32_e32 v199, 0x1a00, v198
	global_load_dwordx4 v[200:203], v199, s[24:25]
	v_add_u32_e32 v199, 0x1b00, v198
	global_load_dwordx4 v[204:207], v199, s[24:25]
	v_add_u32_e32 v199, 0x23a00, v198
	global_load_dwordx4 v[208:211], v199, s[24:25]
	v_add_u32_e32 v199, 0x23b00, v198
	global_load_dwordx4 v[212:215], v199, s[24:25]
	v_add_u32_e32 v199, 0x45a00, v198
	global_load_dwordx4 v[216:219], v199, s[24:25]
	v_add_u32_e32 v199, 0x45b00, v198
	global_load_dwordx4 v[232:235], v199, s[24:25]
	v_add_u32_e32 v199, 0x67a00, v198
	global_load_dwordx4 v[236:239], v199, s[24:25]
	v_add_u32_e32 v199, 0x67b00, v198
	global_load_dwordx4 v[240:243], v199, s[24:25]
	v_add_u32_e32 v199, 0x111a00, v198
	global_load_dwordx4 v[244:247], v199, s[24:25]
	v_add_u32_e32 v199, 0x111b00, v198
	global_load_dwordx4 v[248:251], v199, s[24:25]
	v_add_u32_e32 v199, 0x133a00, v198
	global_load_dwordx4 v[252:255], v199, s[24:25]
	s_waitcnt vmcnt(10)
	v_mov_b32_e32 v162, v200
	v_mov_b32_e32 v163, v201
	v_mov_b32_e32 v164, v202
	v_mov_b32_e32 v165, v203
	v_add_u32_e32 v199, 0x133b00, v198
	global_load_dwordx4 v[200:203], v199, s[24:25]
	v_lshlrev_b32_e32 v161, 16, v162
	v_lshlrev_b32_e32 v171, 16, v164
	v_mul_f32_e32 v161, 0xbfb8aa3b, v161
	v_and_b32_e32 v162, 0xffff0000, v162
	v_mul_f32_e32 v171, 0xbfb8aa3b, v171
	v_exp_f32_e32 v161, v161
	v_and_b32_e32 v164, 0xffff0000, v164
	v_mul_f32_e32 v162, 0xbfb8aa3b, v162
	v_exp_f32_e32 v171, v171
	v_mul_f32_e32 v164, 0xbfb8aa3b, v164
	v_exp_f32_e32 v162, v162
	v_exp_f32_e32 v164, v164
	v_add_f32_e32 v161, 1.0, v161
	v_add_f32_e32 v171, 1.0, v171
	v_div_scale_f32 v173, s[6:7], v161, v161, 1.0
	v_add_f32_e32 v162, 1.0, v162
	v_div_scale_f32 v175, s[6:7], v171, v171, 1.0
	v_rcp_f32_e32 v183, v173
	v_lshlrev_b32_e32 v170, 16, v163
	v_add_f32_e32 v164, 1.0, v164
	v_div_scale_f32 v177, s[6:7], v162, v162, 1.0
	v_rcp_f32_e32 v184, v175
	v_mul_f32_e32 v170, 0xbfb8aa3b, v170
	v_div_scale_f32 v179, s[6:7], v164, v164, 1.0
	v_rcp_f32_e32 v185, v177
	v_exp_f32_e32 v170, v170
	v_rcp_f32_e32 v186, v179
	v_fma_f32 v188, -v173, v183, 1.0
	v_div_scale_f32 v174, vcc, 1.0, v161, 1.0
	v_fma_f32 v189, -v175, v184, 1.0
	v_fmac_f32_e32 v183, v188, v183
	v_div_scale_f32 v176, s[12:13], 1.0, v171, 1.0
	v_fma_f32 v190, -v177, v185, 1.0
	v_fmac_f32_e32 v184, v189, v184
	v_mul_f32_e32 v188, v174, v183
	v_add_f32_e32 v170, 1.0, v170
	v_div_scale_f32 v178, s[14:15], 1.0, v162, 1.0
; __device__ __forceinline__ float sigmoidf_(float x) { return 1.0f / (1.0f + __expf(-x)); }
; __device__ __forceinline__ u32x4 pack8(const f32x4 v0, const f32x4 v1) { u32x4 w; w.x = pk2(v0[0], v0[1]); w.y = pk2(v0[2], v0[3]); w.z = pk2(v1[0], v1[1]); w.w = pk2(v1[2], v1[3]); return w; }
; __device__ __forceinline__ void unpack8(const u32x4 w, f32x4& v0, f32x4& v1) { v0 = (f32x4){bflo(w.x), bfhi(w.x), bflo(w.y), bfhi(w.y)}; v1 = (f32x4){bflo(w.z), bfhi(w.z), bflo(w.w), bfhi(w.w)}; }
;     __device__ __forceinline__ void operator()(const f32x4 (&acc)[2][2][4][2], const Unit& u, int wr, int wc, int fr, int fq) const {
;     ...
;         for (int ai = 0; ai < 2; ++ai)
; #pragma unroll
;             for (int m = 0; m < 4; ++m) {
;                 bf16_t* rowp = z + (size_t)(row0 + ai * 128 + m * 16) * DIN + col0;
; #pragma unroll
;                 for (int bj = 0; bj < 2; ++bj) {
;                     const u32x4 gw = *(const u32x4*)(rowp + (MODE == 0 ? O_GB : O_GA) + bj * 128);
;                     f32x4 g0, g1; unpack8(gw, g0, g1);
;                     f32x4 v0, v1;
; #pragma unroll
;                     for (int j = 0; j < 4; ++j) { v0[j] = sigmoidf_(g0[j]) * acc[ai][bj][m][0][j]; v1[j] = sigmoidf_(g1[j]) * acc[ai][bj][m][1][j]; }
;                     if (MODE == 1) { const u32x4 mw = *(const u32x4*)(rowp + bj * 128); f32x4 m0, m1; unpack8(mw, m0, m1); v0 += m0; v1 += m1; }
;                     *(u32x4*)(rowp + bj * 128) = pack8(v0, v1); }
	v_fma_f32 v191, -v179, v186, 1.0
	v_fmac_f32_e32 v185, v190, v185
	v_mul_f32_e32 v189, v176, v184
	v_fma_f32 v193, -v173, v188, v174
	v_div_scale_f32 v180, s[16:17], 1.0, v164, 1.0
	v_div_scale_f32 v181, s[6:7], v170, v170, 1.0
	v_fmac_f32_e32 v186, v191, v186
	v_mul_f32_e32 v190, v178, v185
	v_fma_f32 v194, -v175, v189, v176
	v_fmac_f32_e32 v188, v193, v183
	v_lshlrev_b32_e32 v172, 16, v165
	v_rcp_f32_e32 v187, v181
	v_mul_f32_e32 v191, v180, v186
	v_fma_f32 v195, -v177, v190, v178
	v_fmac_f32_e32 v189, v194, v184
	v_fma_f32 v173, -v173, v188, v174
	v_mul_f32_e32 v172, 0xbfb8aa3b, v172
	v_fma_f32 v196, -v179, v191, v180
	v_fmac_f32_e32 v190, v195, v185
	v_fma_f32 v174, -v175, v189, v176
	v_div_fmas_f32 v173, v173, v183, v188
	s_mov_b64 vcc, s[12:13]
	v_exp_f32_e32 v172, v172
	v_fmac_f32_e32 v191, v196, v186
	v_fma_f32 v175, -v177, v190, v178
	v_div_fixup_f32 v161, v173, v161, 1.0
	v_div_fmas_f32 v173, v174, v184, v189
	s_mov_b64 vcc, s[14:15]
	v_fma_f32 v176, -v179, v191, v180
	v_mul_f32_e32 v124, v124, v161
	v_div_fixup_f32 v161, v173, v171, 1.0
	v_div_fmas_f32 v171, v175, v185, v190
	s_mov_b64 vcc, s[16:17]
	v_fma_f32 v192, -v181, v187, 1.0
	v_mul_f32_e32 v161, v120, v161
	v_div_fixup_f32 v120, v171, v162, 1.0
	v_div_fmas_f32 v162, v176, v186, v191
	v_div_scale_f32 v182, s[18:19], 1.0, v170, 1.0
	v_fmac_f32_e32 v187, v192, v187
	v_mul_f32_e32 v120, v125, v120
	v_div_fixup_f32 v125, v162, v164, 1.0
	v_mul_f32_e32 v192, v182, v187
	v_mul_f32_e32 v125, v121, v125
	v_add_f32_e32 v121, 1.0, v172
	v_fma_f32 v197, -v181, v192, v182
	v_div_scale_f32 v162, s[6:7], v121, v121, 1.0
	v_fmac_f32_e32 v192, v197, v187
	v_rcp_f32_e32 v164, v162
	v_fma_f32 v177, -v181, v192, v182
	s_mov_b64 vcc, s[18:19]
	v_and_b32_e32 v163, 0xffff0000, v163
	v_div_fmas_f32 v171, v177, v187, v192
	v_div_fixup_f32 v170, v171, v170, 1.0
	v_mul_f32_e32 v163, 0xbfb8aa3b, v163
	v_mul_f32_e32 v126, v126, v170
	v_fma_f32 v170, -v162, v164, 1.0
	v_exp_f32_e32 v163, v163
	v_fmac_f32_e32 v164, v170, v164
	v_div_scale_f32 v170, vcc, 1.0, v121, 1.0
	v_mul_f32_e32 v171, v170, v164
	v_fma_f32 v172, -v162, v171, v170
	v_fmac_f32_e32 v171, v172, v164
	v_add_f32_e32 v163, 1.0, v163
	v_fma_f32 v162, -v162, v171, v170
	v_div_scale_f32 v170, s[6:7], v163, v163, 1.0
	v_rcp_f32_e32 v172, v170
	v_and_b32_e32 v165, 0xffff0000, v165
	v_div_fmas_f32 v162, v162, v164, v171
	v_mul_f32_e32 v164, 0xbfb8aa3b, v165
	v_div_fixup_f32 v121, v162, v121, 1.0
	v_exp_f32_e32 v164, v164
	v_mul_f32_e32 v162, v122, v121
	v_fma_f32 v121, -v170, v172, 1.0
	v_fmac_f32_e32 v172, v121, v172
	v_div_scale_f32 v121, vcc, 1.0, v163, 1.0
	v_mul_f32_e32 v122, v121, v172
	v_fma_f32 v165, -v170, v122, v121
	v_add_f32_e32 v164, 1.0, v164
	v_fmac_f32_e32 v122, v165, v172
	v_div_scale_f32 v165, s[6:7], v164, v164, 1.0
	v_fma_f32 v121, -v170, v122, v121
	v_rcp_f32_e32 v170, v165
	v_div_fmas_f32 v121, v121, v172, v122
	v_div_fixup_f32 v121, v121, v163, 1.0
	v_mul_f32_e32 v121, v127, v121
	v_fma_f32 v122, -v165, v170, 1.0
	v_fmac_f32_e32 v170, v122, v170
	v_div_scale_f32 v122, vcc, 1.0, v164, 1.0
	v_mul_f32_e32 v127, v122, v170
	v_fma_f32 v163, -v165, v127, v122
	v_fmac_f32_e32 v127, v163, v170
	v_fma_f32 v122, -v165, v127, v122
	v_div_fmas_f32 v122, v122, v170, v127
	v_div_fixup_f32 v122, v122, v164, 1.0
	v_mul_f32_e32 v123, v123, v122
	v_cvt_pk_bf16_f32 v120, v124, v120
	v_cvt_pk_bf16_f32 v121, v126, v121
	v_cvt_pk_bf16_f32 v122, v161, v125
	v_cvt_pk_bf16_f32 v123, v162, v123
	s_mov_b64 s[16:17], s[34:35]
	global_store_dwordx4 v[150:151], v[120:123], off
	s_mov_b64 s[14:15], s[30:31]
	s_waitcnt vmcnt(11)
	v_mov_b32_e32 v124, v204
	v_mov_b32_e32 v125, v205
	v_mov_b32_e32 v126, v206
	v_mov_b32_e32 v127, v207
	v_add_u32_e32 v199, 0x155a00, v198
	global_load_dwordx4 v[204:207], v199, s[24:25]
	v_lshlrev_b32_e32 v120, 16, v124
	v_mul_f32_e32 v120, 0xbfb8aa3b, v120
	v_exp_f32_e32 v120, v120
	v_and_b32_e32 v121, 0xffff0000, v124
	v_lshlrev_b32_e32 v124, 16, v126
	v_mul_f32_e32 v124, 0xbfb8aa3b, v124
	v_add_f32_e32 v120, 1.0, v120
	v_exp_f32_e32 v124, v124
	v_div_scale_f32 v152, s[6:7], v120, v120, 1.0
	v_rcp_f32_e32 v162, v152
	v_add_f32_e32 v124, 1.0, v124
	v_div_scale_f32 v161, s[6:7], v124, v124, 1.0
	v_fma_f32 v165, -v152, v162, 1.0
	v_div_scale_f32 v153, vcc, 1.0, v120, 1.0
	v_rcp_f32_e32 v163, v161
	v_fmac_f32_e32 v162, v165, v162
	v_mul_f32_e32 v121, 0xbfb8aa3b, v121
	v_mul_f32_e32 v165, v153, v162
	v_exp_f32_e32 v121, v121
	v_fma_f32 v171, -v152, v165, v153
	v_fmac_f32_e32 v165, v171, v162
	v_fma_f32 v170, -v161, v163, 1.0
	v_fma_f32 v152, -v152, v165, v153
	v_div_scale_f32 v164, s[12:13], 1.0, v124, 1.0
	v_fmac_f32_e32 v163, v170, v163
	v_div_fmas_f32 v152, v152, v162, v165
	v_add_f32_e32 v121, 1.0, v121
	v_mul_f32_e32 v170, v164, v163
	v_div_fixup_f32 v120, v152, v120, 1.0
	v_fma_f32 v172, -v161, v170, v164
	v_mul_f32_e32 v116, v116, v120
	v_div_scale_f32 v120, s[6:7], v121, v121, 1.0
	v_fmac_f32_e32 v170, v172, v163
	v_rcp_f32_e32 v152, v120
	v_fma_f32 v153, -v161, v170, v164
	s_mov_b64 vcc, s[12:13]
	v_div_fmas_f32 v153, v153, v163, v170
	v_lshlrev_b32_e32 v122, 16, v125
	v_and_b32_e32 v123, 0xffff0000, v125
	v_and_b32_e32 v125, 0xffff0000, v126
	v_div_fixup_f32 v124, v153, v124, 1.0
	v_mul_f32_e32 v112, v112, v124
	v_fma_f32 v124, -v120, v152, 1.0
	v_mul_f32_e32 v125, 0xbfb8aa3b, v125
	v_fmac_f32_e32 v152, v124, v152
	v_div_scale_f32 v124, vcc, 1.0, v121, 1.0
	v_exp_f32_e32 v125, v125
	v_mul_f32_e32 v153, v124, v152
	v_fma_f32 v161, -v120, v153, v124
	v_fmac_f32_e32 v153, v161, v152
	v_fma_f32 v120, -v120, v153, v124
	v_add_f32_e32 v124, 1.0, v125
	v_div_scale_f32 v125, s[6:7], v124, v124, 1.0
	v_rcp_f32_e32 v161, v125
; __device__ __forceinline__ float sigmoidf_(float x) { return 1.0f / (1.0f + __expf(-x)); }
; __device__ __forceinline__ u32x4 pack8(const f32x4 v0, const f32x4 v1) { u32x4 w; w.x = pk2(v0[0], v0[1]); w.y = pk2(v0[2], v0[3]); w.z = pk2(v1[0], v1[1]); w.w = pk2(v1[2], v1[3]); return w; }
; __device__ __forceinline__ void unpack8(const u32x4 w, f32x4& v0, f32x4& v1) { v0 = (f32x4){bflo(w.x), bfhi(w.x), bflo(w.y), bfhi(w.y)}; v1 = (f32x4){bflo(w.z), bfhi(w.z), bflo(w.w), bfhi(w.w)}; }
;     __device__ __forceinline__ void operator()(const f32x4 (&acc)[2][2][4][2], const Unit& u, int wr, int wc, int fr, int fq) const {
;     ...
;         for (int ai = 0; ai < 2; ++ai)
; #pragma unroll
;             for (int m = 0; m < 4; ++m) {
;                 bf16_t* rowp = z + (size_t)(row0 + ai * 128 + m * 16) * DIN + col0;
; #pragma unroll
;                 for (int bj = 0; bj < 2; ++bj) {
;                     const u32x4 gw = *(const u32x4*)(rowp + (MODE == 0 ? O_GB : O_GA) + bj * 128);
;                     f32x4 g0, g1; unpack8(gw, g0, g1);
;                     f32x4 v0, v1;
; #pragma unroll
;                     for (int j = 0; j < 4; ++j) { v0[j] = sigmoidf_(g0[j]) * acc[ai][bj][m][0][j]; v1[j] = sigmoidf_(g1[j]) * acc[ai][bj][m][1][j]; }
;                     if (MODE == 1) { const u32x4 mw = *(const u32x4*)(rowp + bj * 128); f32x4 m0, m1; unpack8(mw, m0, m1); v0 += m0; v1 += m1; }
;                     *(u32x4*)(rowp + bj * 128) = pack8(v0, v1); }
	v_div_fmas_f32 v120, v120, v152, v153
	v_div_fixup_f32 v120, v120, v121, 1.0
	v_mul_f32_e32 v122, 0xbfb8aa3b, v122
	v_mul_f32_e32 v117, v117, v120
	v_fma_f32 v120, -v125, v161, 1.0
	v_exp_f32_e32 v122, v122
	v_fmac_f32_e32 v161, v120, v161
	v_div_scale_f32 v120, vcc, 1.0, v124, 1.0
	v_mul_f32_e32 v121, v120, v161
	v_fma_f32 v152, -v125, v121, v120
	v_fmac_f32_e32 v121, v152, v161
	v_add_f32_e32 v122, 1.0, v122
	v_fma_f32 v120, -v125, v121, v120
	v_div_scale_f32 v125, s[6:7], v122, v122, 1.0
	v_rcp_f32_e32 v152, v125
	v_lshlrev_b32_e32 v126, 16, v127
	v_div_fmas_f32 v120, v120, v161, v121
	v_div_fixup_f32 v120, v120, v124, 1.0
	v_mul_f32_e32 v124, 0xbfb8aa3b, v126
	v_mul_f32_e32 v113, v113, v120
	v_fma_f32 v120, -v125, v152, 1.0
	v_exp_f32_e32 v124, v124
	v_fmac_f32_e32 v152, v120, v152
	v_div_scale_f32 v120, vcc, 1.0, v122, 1.0
	v_mul_f32_e32 v121, v120, v152
	v_fma_f32 v126, -v125, v121, v120
	v_fmac_f32_e32 v121, v126, v152
	v_add_f32_e32 v124, 1.0, v124
	v_fma_f32 v120, -v125, v121, v120
	v_div_scale_f32 v125, s[6:7], v124, v124, 1.0
	v_rcp_f32_e32 v126, v125
	v_div_fmas_f32 v120, v120, v152, v121
	v_div_fixup_f32 v120, v120, v122, 1.0
	v_mul_f32_e32 v122, 0xbfb8aa3b, v123
	v_exp_f32_e32 v122, v122
	v_mul_f32_e32 v118, v118, v120
	v_fma_f32 v120, -v125, v126, 1.0
	v_fmac_f32_e32 v126, v120, v126
	v_div_scale_f32 v120, vcc, 1.0, v124, 1.0
	v_mul_f32_e32 v121, v120, v126
	v_fma_f32 v123, -v125, v121, v120
	v_add_f32_e32 v122, 1.0, v122
	v_fmac_f32_e32 v121, v123, v126
	v_div_scale_f32 v123, s[6:7], v122, v122, 1.0
	v_fma_f32 v120, -v125, v121, v120
	v_rcp_f32_e32 v125, v123
	v_div_fmas_f32 v120, v120, v126, v121
	v_and_b32_e32 v127, 0xffff0000, v127
	v_div_fixup_f32 v120, v120, v124, 1.0
	v_mul_f32_e32 v120, v114, v120
	v_fma_f32 v114, -v123, v125, 1.0
	v_mul_f32_e32 v124, 0xbfb8aa3b, v127
	v_fmac_f32_e32 v125, v114, v125
	v_div_scale_f32 v114, vcc, 1.0, v122, 1.0
	v_exp_f32_e32 v124, v124
	v_mul_f32_e32 v121, v114, v125
	v_fma_f32 v126, -v123, v121, v114
	v_fmac_f32_e32 v121, v126, v125
	v_fma_f32 v114, -v123, v121, v114
	v_add_f32_e32 v123, 1.0, v124
	v_div_scale_f32 v124, s[6:7], v123, v123, 1.0
	v_rcp_f32_e32 v126, v124
	v_div_fmas_f32 v114, v114, v125, v121
	v_div_fixup_f32 v114, v114, v122, 1.0
	v_mul_f32_e32 v119, v119, v114
	v_fma_f32 v114, -v124, v126, 1.0
	v_fmac_f32_e32 v126, v114, v126
	v_div_scale_f32 v114, vcc, 1.0, v123, 1.0
	v_mul_f32_e32 v121, v114, v126
	v_fma_f32 v122, -v124, v121, v114
	v_fmac_f32_e32 v121, v122, v126
	v_fma_f32 v114, -v124, v121, v114
	v_div_fmas_f32 v114, v114, v126, v121
	v_div_fixup_f32 v114, v114, v123, 1.0
	v_mul_f32_e32 v121, v115, v114
	v_cvt_pk_bf16_f32 v114, v116, v117
	v_cvt_pk_bf16_f32 v115, v118, v119
	v_cvt_pk_bf16_f32 v116, v112, v113
	v_or_b32_e32 v112, 16, v160
	v_mad_i64_i32 v[112:113], s[6:7], v112, s61, v[146:147]
	v_lshl_add_u64 v[112:113], v[112:113], 0, v[148:149]
	v_add_co_u32_e32 v122, vcc, s62, v112
	v_cvt_pk_bf16_f32 v117, v120, v121
	global_store_dwordx4 v[150:151], v[114:117], off offset:256
	s_nop 0
	v_addc_co_u32_e32 v123, vcc, 0, v113, vcc
	s_waitcnt vmcnt(12)
	v_mov_b32_e32 v118, v208
	v_mov_b32_e32 v119, v209
	v_mov_b32_e32 v120, v210
	v_mov_b32_e32 v121, v211
	v_add_u32_e32 v199, 0x155b00, v198
	global_load_dwordx4 v[208:211], v199, s[24:25]
	v_lshlrev_b32_e32 v114, 16, v118
	v_mul_f32_e32 v114, 0xbfb8aa3b, v114
	v_exp_f32_e32 v114, v114
	v_lshlrev_b32_e32 v116, 16, v119
	v_and_b32_e32 v117, 0xffff0000, v119
	v_and_b32_e32 v115, 0xffff0000, v118
	v_add_f32_e32 v114, 1.0, v114
	v_div_scale_f32 v119, s[6:7], v114, v114, 1.0
	v_rcp_f32_e32 v124, v119
	v_lshlrev_b32_e32 v118, 16, v120
	v_mul_f32_e32 v118, 0xbfb8aa3b, v118
	v_exp_f32_e32 v118, v118
	v_fma_f32 v126, -v119, v124, 1.0
	v_fmac_f32_e32 v124, v126, v124
	v_div_scale_f32 v126, vcc, 1.0, v114, 1.0
	v_mul_f32_e32 v127, v126, v124
	v_fma_f32 v150, -v119, v127, v126
	v_fmac_f32_e32 v127, v150, v124
	v_add_f32_e32 v118, 1.0, v118
	v_fma_f32 v119, -v119, v127, v126
	v_div_scale_f32 v126, s[6:7], v118, v118, 1.0
	v_rcp_f32_e32 v150, v126
	v_div_fmas_f32 v119, v119, v124, v127
	v_mul_f32_e32 v115, 0xbfb8aa3b, v115
	v_div_fixup_f32 v114, v119, v114, 1.0
	v_exp_f32_e32 v115, v115
	v_mul_f32_e32 v108, v108, v114
	v_fma_f32 v114, -v126, v150, 1.0
	v_fmac_f32_e32 v150, v114, v150
	v_div_scale_f32 v114, vcc, 1.0, v118, 1.0
	v_mul_f32_e32 v119, v114, v150
	v_fma_f32 v124, -v126, v119, v114
	v_add_f32_e32 v115, 1.0, v115
	v_fmac_f32_e32 v119, v124, v150
	v_div_scale_f32 v124, s[6:7], v115, v115, 1.0
	v_fma_f32 v114, -v126, v119, v114
	v_rcp_f32_e32 v126, v124
	v_and_b32_e32 v120, 0xffff0000, v120
	v_div_fmas_f32 v114, v114, v150, v119
	v_mul_f32_e32 v119, 0xbfb8aa3b, v120
	v_div_fixup_f32 v114, v114, v118, 1.0
	v_exp_f32_e32 v119, v119
	v_mul_f32_e32 v114, v104, v114
	v_fma_f32 v104, -v124, v126, 1.0
	v_fmac_f32_e32 v126, v104, v126
	v_div_scale_f32 v104, vcc, 1.0, v115, 1.0
	v_mul_f32_e32 v118, v104, v126
	v_fma_f32 v120, -v124, v118, v104
	v_add_f32_e32 v119, 1.0, v119
	v_fmac_f32_e32 v118, v120, v126
	v_div_scale_f32 v120, s[6:7], v119, v119, 1.0
	v_fma_f32 v104, -v124, v118, v104
	v_rcp_f32_e32 v124, v120
	v_div_fmas_f32 v104, v104, v126, v118
	v_mul_f32_e32 v116, 0xbfb8aa3b, v116
	v_div_fixup_f32 v104, v104, v115, 1.0
	v_exp_f32_e32 v116, v116
	v_mul_f32_e32 v104, v109, v104
	v_fma_f32 v109, -v120, v124, 1.0
	v_fmac_f32_e32 v124, v109, v124
	v_div_scale_f32 v109, vcc, 1.0, v119, 1.0
	v_mul_f32_e32 v115, v109, v124
	v_fma_f32 v118, -v120, v115, v109
	v_add_f32_e32 v116, 1.0, v116
	v_fmac_f32_e32 v115, v118, v124
	v_div_scale_f32 v118, s[6:7], v116, v116, 1.0
	v_fma_f32 v109, -v120, v115, v109
	v_rcp_f32_e32 v120, v118
; __device__ __forceinline__ float sigmoidf_(float x) { return 1.0f / (1.0f + __expf(-x)); }
; __device__ __forceinline__ u32x4 pack8(const f32x4 v0, const f32x4 v1) { u32x4 w; w.x = pk2(v0[0], v0[1]); w.y = pk2(v0[2], v0[3]); w.z = pk2(v1[0], v1[1]); w.w = pk2(v1[2], v1[3]); return w; }
; __device__ __forceinline__ void unpack8(const u32x4 w, f32x4& v0, f32x4& v1) { v0 = (f32x4){bflo(w.x), bfhi(w.x), bflo(w.y), bfhi(w.y)}; v1 = (f32x4){bflo(w.z), bfhi(w.z), bflo(w.w), bfhi(w.w)}; }
;     __device__ __forceinline__ void operator()(const f32x4 (&acc)[2][2][4][2], const Unit& u, int wr, int wc, int fr, int fq) const {
;     ...
;         for (int ai = 0; ai < 2; ++ai)
; #pragma unroll
;             for (int m = 0; m < 4; ++m) {
;                 bf16_t* rowp = z + (size_t)(row0 + ai * 128 + m * 16) * DIN + col0;
; #pragma unroll
;                 for (int bj = 0; bj < 2; ++bj) {
;                     const u32x4 gw = *(const u32x4*)(rowp + (MODE == 0 ? O_GB : O_GA) + bj * 128);
;                     f32x4 g0, g1; unpack8(gw, g0, g1);
;                     f32x4 v0, v1;
; #pragma unroll
;                     for (int j = 0; j < 4; ++j) { v0[j] = sigmoidf_(g0[j]) * acc[ai][bj][m][0][j]; v1[j] = sigmoidf_(g1[j]) * acc[ai][bj][m][1][j]; }
;                     if (MODE == 1) { const u32x4 mw = *(const u32x4*)(rowp + bj * 128); f32x4 m0, m1; unpack8(mw, m0, m1); v0 += m0; v1 += m1; }
;                     *(u32x4*)(rowp + bj * 128) = pack8(v0, v1); }
	v_div_fmas_f32 v109, v109, v124, v115
	v_lshlrev_b32_e32 v125, 16, v121
	v_div_fixup_f32 v109, v109, v119, 1.0
	v_mul_f32_e32 v109, v105, v109
	v_fma_f32 v105, -v118, v120, 1.0
	v_mul_f32_e32 v119, 0xbfb8aa3b, v125
	v_fmac_f32_e32 v120, v105, v120
	v_div_scale_f32 v105, vcc, 1.0, v116, 1.0
	v_exp_f32_e32 v119, v119
	v_mul_f32_e32 v115, v105, v120
	v_fma_f32 v124, -v118, v115, v105
	v_fmac_f32_e32 v115, v124, v120
	v_fma_f32 v105, -v118, v115, v105
	v_add_f32_e32 v118, 1.0, v119
	v_div_scale_f32 v119, s[6:7], v118, v118, 1.0
	v_rcp_f32_e32 v124, v119
	v_div_fmas_f32 v105, v105, v120, v115
	v_div_fixup_f32 v105, v105, v116, 1.0
	v_mul_f32_e32 v116, 0xbfb8aa3b, v117
	v_exp_f32_e32 v116, v116
	v_mul_f32_e32 v105, v110, v105
	v_fma_f32 v110, -v119, v124, 1.0
	v_fmac_f32_e32 v124, v110, v124
	v_div_scale_f32 v110, vcc, 1.0, v118, 1.0
	v_mul_f32_e32 v115, v110, v124
	v_fma_f32 v117, -v119, v115, v110
	v_add_f32_e32 v116, 1.0, v116
	v_fmac_f32_e32 v115, v117, v124
	v_div_scale_f32 v117, s[6:7], v116, v116, 1.0
	v_fma_f32 v110, -v119, v115, v110
	v_rcp_f32_e32 v119, v117
	v_div_fmas_f32 v110, v110, v124, v115
	v_and_b32_e32 v121, 0xffff0000, v121
	v_div_fixup_f32 v110, v110, v118, 1.0
	v_mul_f32_e32 v110, v106, v110
	v_fma_f32 v106, -v117, v119, 1.0
	v_mul_f32_e32 v118, 0xbfb8aa3b, v121
	v_fmac_f32_e32 v119, v106, v119
	v_div_scale_f32 v106, vcc, 1.0, v116, 1.0
	v_exp_f32_e32 v118, v118
	v_mul_f32_e32 v115, v106, v119
	v_fma_f32 v120, -v117, v115, v106
	v_fmac_f32_e32 v115, v120, v119
	v_fma_f32 v106, -v117, v115, v106
	v_add_f32_e32 v117, 1.0, v118
	v_div_scale_f32 v118, s[6:7], v117, v117, 1.0
	v_rcp_f32_e32 v120, v118
	v_div_fmas_f32 v106, v106, v119, v115
	v_div_fixup_f32 v106, v106, v116, 1.0
	v_mul_f32_e32 v106, v111, v106
	v_fma_f32 v111, -v118, v120, 1.0
	v_fmac_f32_e32 v120, v111, v120
	v_div_scale_f32 v111, vcc, 1.0, v117, 1.0
	v_mul_f32_e32 v115, v111, v120
	v_fma_f32 v116, -v118, v115, v111
	v_fmac_f32_e32 v115, v116, v120
	v_fma_f32 v111, -v118, v115, v111
	v_div_fmas_f32 v111, v111, v120, v115
	v_div_fixup_f32 v111, v111, v117, 1.0
	v_mul_f32_e32 v107, v107, v111
	v_cvt_pk_bf16_f32 v104, v108, v104
	v_cvt_pk_bf16_f32 v105, v105, v106
	v_cvt_pk_bf16_f32 v106, v114, v109
	v_cvt_pk_bf16_f32 v107, v110, v107
	s_waitcnt vmcnt(12)
	v_mov_b32_e32 v108, v212
	v_mov_b32_e32 v109, v213
	v_mov_b32_e32 v110, v214
	v_mov_b32_e32 v111, v215
	v_add_u32_e32 v199, 0x177a00, v198
	global_load_dwordx4 v[212:215], v199, s[24:25]
	v_lshlrev_b32_e32 v115, 16, v111
	global_store_dwordx4 v[112:113], v[104:107], off
	v_and_b32_e32 v111, 0xffff0000, v111
	s_nop 0
	v_lshlrev_b32_e32 v104, 16, v108
	v_mul_f32_e32 v104, 0xbfb8aa3b, v104
	v_exp_f32_e32 v104, v104
	v_lshlrev_b32_e32 v106, 16, v109
	v_and_b32_e32 v107, 0xffff0000, v109
	v_and_b32_e32 v105, 0xffff0000, v108
	v_add_f32_e32 v104, 1.0, v104
	v_div_scale_f32 v109, s[6:7], v104, v104, 1.0
	v_rcp_f32_e32 v114, v109
	v_lshlrev_b32_e32 v108, 16, v110
	v_mul_f32_e32 v108, 0xbfb8aa3b, v108
	v_exp_f32_e32 v108, v108
	v_fma_f32 v116, -v109, v114, 1.0
	v_fmac_f32_e32 v114, v116, v114
	v_div_scale_f32 v116, vcc, 1.0, v104, 1.0
	v_mul_f32_e32 v117, v116, v114
	v_fma_f32 v118, -v109, v117, v116
	v_fmac_f32_e32 v117, v118, v114
	v_add_f32_e32 v108, 1.0, v108
	v_fma_f32 v109, -v109, v117, v116
	v_div_scale_f32 v116, s[6:7], v108, v108, 1.0
	v_rcp_f32_e32 v118, v116
	v_div_fmas_f32 v109, v109, v114, v117
	v_mul_f32_e32 v105, 0xbfb8aa3b, v105
	v_div_fixup_f32 v104, v109, v104, 1.0
	v_exp_f32_e32 v105, v105
	v_mul_f32_e32 v100, v100, v104
	v_fma_f32 v104, -v116, v118, 1.0
	v_fmac_f32_e32 v118, v104, v118
	v_div_scale_f32 v104, vcc, 1.0, v108, 1.0
	v_mul_f32_e32 v109, v104, v118
	v_fma_f32 v114, -v116, v109, v104
	v_add_f32_e32 v105, 1.0, v105
	v_fmac_f32_e32 v109, v114, v118
	v_div_scale_f32 v114, s[6:7], v105, v105, 1.0
	v_fma_f32 v104, -v116, v109, v104
	v_rcp_f32_e32 v116, v114
	v_and_b32_e32 v110, 0xffff0000, v110
	v_div_fmas_f32 v104, v104, v118, v109
	v_mul_f32_e32 v109, 0xbfb8aa3b, v110
	v_div_fixup_f32 v104, v104, v108, 1.0
	v_exp_f32_e32 v109, v109
	v_mul_f32_e32 v96, v96, v104
	v_fma_f32 v104, -v114, v116, 1.0
	v_fmac_f32_e32 v116, v104, v116
	v_div_scale_f32 v104, vcc, 1.0, v105, 1.0
	v_mul_f32_e32 v108, v104, v116
	v_fma_f32 v110, -v114, v108, v104
	v_add_f32_e32 v109, 1.0, v109
	v_fmac_f32_e32 v108, v110, v116
	v_div_scale_f32 v110, s[6:7], v109, v109, 1.0
	v_fma_f32 v104, -v114, v108, v104
	v_rcp_f32_e32 v114, v110
	v_div_fmas_f32 v104, v104, v116, v108
	v_mul_f32_e32 v106, 0xbfb8aa3b, v106
	v_div_fixup_f32 v104, v104, v105, 1.0
	v_exp_f32_e32 v106, v106
	v_mul_f32_e32 v101, v101, v104
	v_fma_f32 v104, -v110, v114, 1.0
	v_fmac_f32_e32 v114, v104, v114
	v_div_scale_f32 v104, vcc, 1.0, v109, 1.0
	v_mul_f32_e32 v105, v104, v114
	v_fma_f32 v108, -v110, v105, v104
	v_add_f32_e32 v106, 1.0, v106
	v_fmac_f32_e32 v105, v108, v114
	v_div_scale_f32 v108, s[6:7], v106, v106, 1.0
	v_fma_f32 v104, -v110, v105, v104
	v_rcp_f32_e32 v110, v108
	v_div_fmas_f32 v104, v104, v114, v105
	v_div_fixup_f32 v104, v104, v109, 1.0
	v_mul_f32_e32 v97, v97, v104
	v_fma_f32 v104, -v108, v110, 1.0
	v_mul_f32_e32 v109, 0xbfb8aa3b, v115
	v_fmac_f32_e32 v110, v104, v110
	v_div_scale_f32 v104, vcc, 1.0, v106, 1.0
	v_exp_f32_e32 v109, v109
	v_mul_f32_e32 v105, v104, v110
	v_fma_f32 v114, -v108, v105, v104
	v_fmac_f32_e32 v105, v114, v110
	v_fma_f32 v104, -v108, v105, v104
	v_add_f32_e32 v108, 1.0, v109
	v_div_scale_f32 v109, s[6:7], v108, v108, 1.0
	v_rcp_f32_e32 v114, v109
	v_div_fmas_f32 v104, v104, v110, v105
	v_div_fixup_f32 v104, v104, v106, 1.0
	v_mul_f32_e32 v106, 0xbfb8aa3b, v107
	v_exp_f32_e32 v106, v106
	v_mul_f32_e32 v102, v102, v104
; __device__ __forceinline__ float sigmoidf_(float x) { return 1.0f / (1.0f + __expf(-x)); }
; __device__ __forceinline__ u32x4 pack8(const f32x4 v0, const f32x4 v1) { u32x4 w; w.x = pk2(v0[0], v0[1]); w.y = pk2(v0[2], v0[3]); w.z = pk2(v1[0], v1[1]); w.w = pk2(v1[2], v1[3]); return w; }
; __device__ __forceinline__ void unpack8(const u32x4 w, f32x4& v0, f32x4& v1) { v0 = (f32x4){bflo(w.x), bfhi(w.x), bflo(w.y), bfhi(w.y)}; v1 = (f32x4){bflo(w.z), bfhi(w.z), bflo(w.w), bfhi(w.w)}; }
;     __device__ __forceinline__ void operator()(const f32x4 (&acc)[2][2][4][2], const Unit& u, int wr, int wc, int fr, int fq) const {
;     ...
;         for (int ai = 0; ai < 2; ++ai)
; #pragma unroll
;             for (int m = 0; m < 4; ++m) {
;                 bf16_t* rowp = z + (size_t)(row0 + ai * 128 + m * 16) * DIN + col0;
; #pragma unroll
;                 for (int bj = 0; bj < 2; ++bj) {
;                     const u32x4 gw = *(const u32x4*)(rowp + (MODE == 0 ? O_GB : O_GA) + bj * 128);
;                     f32x4 g0, g1; unpack8(gw, g0, g1);
;                     f32x4 v0, v1;
; #pragma unroll
;                     for (int j = 0; j < 4; ++j) { v0[j] = sigmoidf_(g0[j]) * acc[ai][bj][m][0][j]; v1[j] = sigmoidf_(g1[j]) * acc[ai][bj][m][1][j]; }
;                     if (MODE == 1) { const u32x4 mw = *(const u32x4*)(rowp + bj * 128); f32x4 m0, m1; unpack8(mw, m0, m1); v0 += m0; v1 += m1; }
;                     *(u32x4*)(rowp + bj * 128) = pack8(v0, v1); }
	v_fma_f32 v104, -v109, v114, 1.0
	v_fmac_f32_e32 v114, v104, v114
	v_div_scale_f32 v104, vcc, 1.0, v108, 1.0
	v_mul_f32_e32 v105, v104, v114
	v_fma_f32 v107, -v109, v105, v104
	v_add_f32_e32 v106, 1.0, v106
	v_fmac_f32_e32 v105, v107, v114
	v_div_scale_f32 v107, s[6:7], v106, v106, 1.0
	v_fma_f32 v104, -v109, v105, v104
	v_rcp_f32_e32 v109, v107
	v_div_fmas_f32 v104, v104, v114, v105
	v_div_fixup_f32 v104, v104, v108, 1.0
	v_mul_f32_e32 v104, v98, v104
	v_fma_f32 v98, -v107, v109, 1.0
	v_mul_f32_e32 v108, 0xbfb8aa3b, v111
	v_fmac_f32_e32 v109, v98, v109
	v_div_scale_f32 v98, vcc, 1.0, v106, 1.0
	v_exp_f32_e32 v108, v108
	v_mul_f32_e32 v105, v98, v109
	v_fma_f32 v110, -v107, v105, v98
	v_fmac_f32_e32 v105, v110, v109
	v_fma_f32 v98, -v107, v105, v98
	v_add_f32_e32 v107, 1.0, v108
	v_div_scale_f32 v108, s[6:7], v107, v107, 1.0
	v_rcp_f32_e32 v110, v108
	v_div_fmas_f32 v98, v98, v109, v105
	v_div_fixup_f32 v98, v98, v106, 1.0
	v_mul_f32_e32 v103, v103, v98
	v_fma_f32 v98, -v108, v110, 1.0
	v_fmac_f32_e32 v110, v98, v110
	v_div_scale_f32 v98, vcc, 1.0, v107, 1.0
	v_mul_f32_e32 v105, v98, v110
	v_fma_f32 v106, -v108, v105, v98
	v_fmac_f32_e32 v105, v106, v110
	v_fma_f32 v98, -v108, v105, v98
	v_div_fmas_f32 v98, v98, v110, v105
	v_div_fixup_f32 v98, v98, v107, 1.0
	v_mul_f32_e32 v105, v99, v98
	v_cvt_pk_bf16_f32 v98, v100, v101
	v_cvt_pk_bf16_f32 v99, v102, v103
	v_cvt_pk_bf16_f32 v100, v96, v97
	v_or_b32_e32 v96, 32, v160
	v_mad_i64_i32 v[96:97], s[6:7], v96, s61, v[146:147]
	v_lshl_add_u64 v[96:97], v[96:97], 0, v[148:149]
	v_add_co_u32_e32 v106, vcc, s62, v96
	v_cvt_pk_bf16_f32 v101, v104, v105
	global_store_dwordx4 v[112:113], v[98:101], off offset:256
	s_nop 0
	v_addc_co_u32_e32 v107, vcc, 0, v97, vcc
	s_waitcnt vmcnt(14)
	v_mov_b32_e32 v102, v216
	v_mov_b32_e32 v103, v217
	v_mov_b32_e32 v104, v218
	v_mov_b32_e32 v105, v219
	v_add_u32_e32 v199, 0x177b00, v198
	global_load_dwordx4 v[216:219], v199, s[24:25]
	v_lshlrev_b32_e32 v98, 16, v102
	v_mul_f32_e32 v98, 0xbfb8aa3b, v98
	v_exp_f32_e32 v98, v98
	v_lshlrev_b32_e32 v100, 16, v103
	v_and_b32_e32 v101, 0xffff0000, v103
	v_and_b32_e32 v99, 0xffff0000, v102
	v_add_f32_e32 v98, 1.0, v98
	v_div_scale_f32 v103, s[6:7], v98, v98, 1.0
	v_rcp_f32_e32 v108, v103
	v_lshlrev_b32_e32 v102, 16, v104
	v_mul_f32_e32 v102, 0xbfb8aa3b, v102
	v_exp_f32_e32 v102, v102
	v_fma_f32 v110, -v103, v108, 1.0
	v_fmac_f32_e32 v108, v110, v108
	v_div_scale_f32 v110, vcc, 1.0, v98, 1.0
	v_mul_f32_e32 v111, v110, v108
	v_fma_f32 v112, -v103, v111, v110
	v_fmac_f32_e32 v111, v112, v108
	v_add_f32_e32 v102, 1.0, v102
	v_fma_f32 v103, -v103, v111, v110
	v_div_scale_f32 v110, s[6:7], v102, v102, 1.0
	v_rcp_f32_e32 v112, v110
	v_div_fmas_f32 v103, v103, v108, v111
	v_mul_f32_e32 v99, 0xbfb8aa3b, v99
	v_div_fixup_f32 v98, v103, v98, 1.0
	v_exp_f32_e32 v99, v99
	v_mul_f32_e32 v92, v92, v98
	v_fma_f32 v98, -v110, v112, 1.0
	v_fmac_f32_e32 v112, v98, v112
	v_div_scale_f32 v98, vcc, 1.0, v102, 1.0
	v_mul_f32_e32 v103, v98, v112
	v_fma_f32 v108, -v110, v103, v98
	v_add_f32_e32 v99, 1.0, v99
	v_fmac_f32_e32 v103, v108, v112
	v_div_scale_f32 v108, s[6:7], v99, v99, 1.0
	v_fma_f32 v98, -v110, v103, v98
	v_rcp_f32_e32 v110, v108
	v_and_b32_e32 v104, 0xffff0000, v104
	v_div_fmas_f32 v98, v98, v112, v103
	v_mul_f32_e32 v103, 0xbfb8aa3b, v104
	v_div_fixup_f32 v98, v98, v102, 1.0
	v_exp_f32_e32 v103, v103
	v_mul_f32_e32 v98, v88, v98
	v_fma_f32 v88, -v108, v110, 1.0
	v_fmac_f32_e32 v110, v88, v110
	v_div_scale_f32 v88, vcc, 1.0, v99, 1.0
	v_mul_f32_e32 v102, v88, v110
	v_fma_f32 v104, -v108, v102, v88
	v_add_f32_e32 v103, 1.0, v103
	v_fmac_f32_e32 v102, v104, v110
	v_div_scale_f32 v104, s[6:7], v103, v103, 1.0
	v_fma_f32 v88, -v108, v102, v88
	v_rcp_f32_e32 v108, v104
	v_div_fmas_f32 v88, v88, v110, v102
	v_mul_f32_e32 v100, 0xbfb8aa3b, v100
	v_div_fixup_f32 v88, v88, v99, 1.0
	v_exp_f32_e32 v100, v100
	v_mul_f32_e32 v88, v93, v88
	v_fma_f32 v93, -v104, v108, 1.0
	v_fmac_f32_e32 v108, v93, v108
	v_div_scale_f32 v93, vcc, 1.0, v103, 1.0
	v_mul_f32_e32 v99, v93, v108
	v_fma_f32 v102, -v104, v99, v93
	v_add_f32_e32 v100, 1.0, v100
	v_fmac_f32_e32 v99, v102, v108
	v_div_scale_f32 v102, s[6:7], v100, v100, 1.0
	v_fma_f32 v93, -v104, v99, v93
	v_rcp_f32_e32 v104, v102
	v_div_fmas_f32 v93, v93, v108, v99
	v_lshlrev_b32_e32 v109, 16, v105
	v_div_fixup_f32 v93, v93, v103, 1.0
	v_mul_f32_e32 v93, v89, v93
	v_fma_f32 v89, -v102, v104, 1.0
	v_mul_f32_e32 v103, 0xbfb8aa3b, v109
	v_fmac_f32_e32 v104, v89, v104
	v_div_scale_f32 v89, vcc, 1.0, v100, 1.0
	v_exp_f32_e32 v103, v103
	v_mul_f32_e32 v99, v89, v104
	v_fma_f32 v108, -v102, v99, v89
	v_fmac_f32_e32 v99, v108, v104
	v_fma_f32 v89, -v102, v99, v89
	v_add_f32_e32 v102, 1.0, v103
	v_div_scale_f32 v103, s[6:7], v102, v102, 1.0
	v_rcp_f32_e32 v108, v103
	v_div_fmas_f32 v89, v89, v104, v99
	v_div_fixup_f32 v89, v89, v100, 1.0
	v_mul_f32_e32 v100, 0xbfb8aa3b, v101
	v_exp_f32_e32 v100, v100
	v_mul_f32_e32 v89, v94, v89
	v_fma_f32 v94, -v103, v108, 1.0
	v_fmac_f32_e32 v108, v94, v108
	v_div_scale_f32 v94, vcc, 1.0, v102, 1.0
	v_mul_f32_e32 v99, v94, v108
	v_fma_f32 v101, -v103, v99, v94
	v_add_f32_e32 v100, 1.0, v100
	v_fmac_f32_e32 v99, v101, v108
	v_div_scale_f32 v101, s[6:7], v100, v100, 1.0
	v_fma_f32 v94, -v103, v99, v94
	v_rcp_f32_e32 v103, v101
	v_div_fmas_f32 v94, v94, v108, v99
	v_and_b32_e32 v105, 0xffff0000, v105
	v_div_fixup_f32 v94, v94, v102, 1.0
	v_mul_f32_e32 v94, v90, v94
	v_fma_f32 v90, -v101, v103, 1.0
	v_mul_f32_e32 v102, 0xbfb8aa3b, v105
	v_fmac_f32_e32 v103, v90, v103
	v_div_scale_f32 v90, vcc, 1.0, v100, 1.0
	v_exp_f32_e32 v102, v102
	v_mul_f32_e32 v99, v90, v103
	v_fma_f32 v104, -v101, v99, v90
	v_fmac_f32_e32 v99, v104, v103
	v_fma_f32 v90, -v101, v99, v90
	v_add_f32_e32 v101, 1.0, v102
	v_div_scale_f32 v102, s[6:7], v101, v101, 1.0
	v_rcp_f32_e32 v104, v102
	v_div_fmas_f32 v90, v90, v103, v99
	v_div_fixup_f32 v90, v90, v100, 1.0
	v_mul_f32_e32 v90, v95, v90
	v_fma_f32 v95, -v102, v104, 1.0
	v_fmac_f32_e32 v104, v95, v104
	v_div_scale_f32 v95, vcc, 1.0, v101, 1.0
	v_mul_f32_e32 v99, v95, v104
	v_fma_f32 v100, -v102, v99, v95
	v_fmac_f32_e32 v99, v100, v104
	v_fma_f32 v95, -v102, v99, v95
	v_div_fmas_f32 v95, v95, v104, v99
	v_div_fixup_f32 v95, v95, v101, 1.0
	v_mul_f32_e32 v91, v91, v95
	v_cvt_pk_bf16_f32 v88, v92, v88
	v_cvt_pk_bf16_f32 v89, v89, v90
	v_cvt_pk_bf16_f32 v90, v98, v93
	v_cvt_pk_bf16_f32 v91, v94, v91
	s_waitcnt vmcnt(14)
; __device__ __forceinline__ float sigmoidf_(float x) { return 1.0f / (1.0f + __expf(-x)); }
; __device__ __forceinline__ u32x4 pack8(const f32x4 v0, const f32x4 v1) { u32x4 w; w.x = pk2(v0[0], v0[1]); w.y = pk2(v0[2], v0[3]); w.z = pk2(v1[0], v1[1]); w.w = pk2(v1[2], v1[3]); return w; }
; __device__ __forceinline__ void unpack8(const u32x4 w, f32x4& v0, f32x4& v1) { v0 = (f32x4){bflo(w.x), bfhi(w.x), bflo(w.y), bfhi(w.y)}; v1 = (f32x4){bflo(w.z), bfhi(w.z), bflo(w.w), bfhi(w.w)}; }
;     __device__ __forceinline__ void operator()(const f32x4 (&acc)[2][2][4][2], const Unit& u, int wr, int wc, int fr, int fq) const {
;     ...
;         for (int ai = 0; ai < 2; ++ai)
; #pragma unroll
;             for (int m = 0; m < 4; ++m) {
;                 bf16_t* rowp = z + (size_t)(row0 + ai * 128 + m * 16) * DIN + col0;
; #pragma unroll
;                 for (int bj = 0; bj < 2; ++bj) {
;                     const u32x4 gw = *(const u32x4*)(rowp + (MODE == 0 ? O_GB : O_GA) + bj * 128);
;                     f32x4 g0, g1; unpack8(gw, g0, g1);
;                     f32x4 v0, v1;
; #pragma unroll
;                     for (int j = 0; j < 4; ++j) { v0[j] = sigmoidf_(g0[j]) * acc[ai][bj][m][0][j]; v1[j] = sigmoidf_(g1[j]) * acc[ai][bj][m][1][j]; }
;                     if (MODE == 1) { const u32x4 mw = *(const u32x4*)(rowp + bj * 128); f32x4 m0, m1; unpack8(mw, m0, m1); v0 += m0; v1 += m1; }
;                     *(u32x4*)(rowp + bj * 128) = pack8(v0, v1); }
	v_mov_b32_e32 v92, v232
	v_mov_b32_e32 v93, v233
	v_mov_b32_e32 v94, v234
	v_mov_b32_e32 v95, v235
	v_lshlrev_b32_e32 v99, 16, v95
	global_store_dwordx4 v[96:97], v[88:91], off
	v_and_b32_e32 v95, 0xffff0000, v95
	s_nop 0
	v_lshlrev_b32_e32 v88, 16, v92
	v_mul_f32_e32 v88, 0xbfb8aa3b, v88
	v_exp_f32_e32 v88, v88
	v_lshlrev_b32_e32 v90, 16, v93
	v_and_b32_e32 v91, 0xffff0000, v93
	v_and_b32_e32 v89, 0xffff0000, v92
	v_add_f32_e32 v88, 1.0, v88
	v_div_scale_f32 v93, s[6:7], v88, v88, 1.0
	v_rcp_f32_e32 v98, v93
	v_lshlrev_b32_e32 v92, 16, v94
	v_mul_f32_e32 v92, 0xbfb8aa3b, v92
	v_exp_f32_e32 v92, v92
	v_fma_f32 v100, -v93, v98, 1.0
	v_fmac_f32_e32 v98, v100, v98
	v_div_scale_f32 v100, vcc, 1.0, v88, 1.0
	v_mul_f32_e32 v101, v100, v98
	v_fma_f32 v102, -v93, v101, v100
	v_fmac_f32_e32 v101, v102, v98
	v_add_f32_e32 v92, 1.0, v92
	v_fma_f32 v93, -v93, v101, v100
	v_div_scale_f32 v100, s[6:7], v92, v92, 1.0
	v_rcp_f32_e32 v102, v100
	v_div_fmas_f32 v93, v93, v98, v101
	v_mul_f32_e32 v89, 0xbfb8aa3b, v89
	v_div_fixup_f32 v88, v93, v88, 1.0
	v_exp_f32_e32 v89, v89
	v_mul_f32_e32 v84, v84, v88
	v_fma_f32 v88, -v100, v102, 1.0
	v_fmac_f32_e32 v102, v88, v102
	v_div_scale_f32 v88, vcc, 1.0, v92, 1.0
	v_mul_f32_e32 v93, v88, v102
	v_fma_f32 v98, -v100, v93, v88
	v_add_f32_e32 v89, 1.0, v89
	v_fmac_f32_e32 v93, v98, v102
	v_div_scale_f32 v98, s[6:7], v89, v89, 1.0
	v_fma_f32 v88, -v100, v93, v88
	v_rcp_f32_e32 v100, v98
	v_and_b32_e32 v94, 0xffff0000, v94
	v_div_fmas_f32 v88, v88, v102, v93
	v_mul_f32_e32 v93, 0xbfb8aa3b, v94
	v_div_fixup_f32 v88, v88, v92, 1.0
	v_exp_f32_e32 v93, v93
	v_mul_f32_e32 v80, v80, v88
	v_fma_f32 v88, -v98, v100, 1.0
	v_fmac_f32_e32 v100, v88, v100
	v_div_scale_f32 v88, vcc, 1.0, v89, 1.0
	v_mul_f32_e32 v92, v88, v100
	v_fma_f32 v94, -v98, v92, v88
	v_add_f32_e32 v93, 1.0, v93
	v_fmac_f32_e32 v92, v94, v100
	v_div_scale_f32 v94, s[6:7], v93, v93, 1.0
	v_fma_f32 v88, -v98, v92, v88
	v_rcp_f32_e32 v98, v94
	v_div_fmas_f32 v88, v88, v100, v92
	v_mul_f32_e32 v90, 0xbfb8aa3b, v90
	v_div_fixup_f32 v88, v88, v89, 1.0
	v_exp_f32_e32 v90, v90
	v_mul_f32_e32 v85, v85, v88
	v_fma_f32 v88, -v94, v98, 1.0
	v_fmac_f32_e32 v98, v88, v98
	v_div_scale_f32 v88, vcc, 1.0, v93, 1.0
	v_mul_f32_e32 v89, v88, v98
	v_fma_f32 v92, -v94, v89, v88
	v_add_f32_e32 v90, 1.0, v90
	v_fmac_f32_e32 v89, v92, v98
	v_div_scale_f32 v92, s[6:7], v90, v90, 1.0
	v_fma_f32 v88, -v94, v89, v88
	v_rcp_f32_e32 v94, v92
	v_div_fmas_f32 v88, v88, v98, v89
	v_div_fixup_f32 v88, v88, v93, 1.0
	v_mul_f32_e32 v81, v81, v88
	v_fma_f32 v88, -v92, v94, 1.0
	v_mul_f32_e32 v93, 0xbfb8aa3b, v99
	v_fmac_f32_e32 v94, v88, v94
	v_div_scale_f32 v88, vcc, 1.0, v90, 1.0
	v_exp_f32_e32 v93, v93
	v_mul_f32_e32 v89, v88, v94
	v_fma_f32 v98, -v92, v89, v88
	v_fmac_f32_e32 v89, v98, v94
	v_fma_f32 v88, -v92, v89, v88
	v_add_f32_e32 v92, 1.0, v93
	v_div_scale_f32 v93, s[6:7], v92, v92, 1.0
	v_rcp_f32_e32 v98, v93
	v_div_fmas_f32 v88, v88, v94, v89
	v_div_fixup_f32 v88, v88, v90, 1.0
	v_mul_f32_e32 v90, 0xbfb8aa3b, v91
	v_exp_f32_e32 v90, v90
	v_mul_f32_e32 v86, v86, v88
	v_fma_f32 v88, -v93, v98, 1.0
	v_fmac_f32_e32 v98, v88, v98
	v_div_scale_f32 v88, vcc, 1.0, v92, 1.0
	v_mul_f32_e32 v89, v88, v98
	v_fma_f32 v91, -v93, v89, v88
	v_add_f32_e32 v90, 1.0, v90
	v_fmac_f32_e32 v89, v91, v98
	v_div_scale_f32 v91, s[6:7], v90, v90, 1.0
	v_fma_f32 v88, -v93, v89, v88
	v_rcp_f32_e32 v93, v91
	v_div_fmas_f32 v88, v88, v98, v89
	v_div_fixup_f32 v88, v88, v92, 1.0
	v_mul_f32_e32 v88, v82, v88
	v_fma_f32 v82, -v91, v93, 1.0
	v_mul_f32_e32 v92, 0xbfb8aa3b, v95
	v_fmac_f32_e32 v93, v82, v93
	v_div_scale_f32 v82, vcc, 1.0, v90, 1.0
	v_exp_f32_e32 v92, v92
	v_mul_f32_e32 v89, v82, v93
	v_fma_f32 v94, -v91, v89, v82
	v_fmac_f32_e32 v89, v94, v93
	v_fma_f32 v82, -v91, v89, v82
	v_add_f32_e32 v91, 1.0, v92
	v_div_scale_f32 v92, s[6:7], v91, v91, 1.0
	v_rcp_f32_e32 v94, v92
	v_div_fmas_f32 v82, v82, v93, v89
	v_div_fixup_f32 v82, v82, v90, 1.0
	v_mul_f32_e32 v87, v87, v82
	v_fma_f32 v82, -v92, v94, 1.0
	v_fmac_f32_e32 v94, v82, v94
	v_div_scale_f32 v82, vcc, 1.0, v91, 1.0
	v_mul_f32_e32 v89, v82, v94
	v_fma_f32 v90, -v92, v89, v82
	v_fmac_f32_e32 v89, v90, v94
	v_fma_f32 v82, -v92, v89, v82
	v_div_fmas_f32 v82, v82, v94, v89
	v_div_fixup_f32 v82, v82, v91, 1.0
	v_mul_f32_e32 v89, v83, v82
	v_cvt_pk_bf16_f32 v82, v84, v85
	v_cvt_pk_bf16_f32 v83, v86, v87
	v_cvt_pk_bf16_f32 v84, v80, v81
	v_or_b32_e32 v80, 48, v160
	v_mad_i64_i32 v[80:81], s[6:7], v80, s61, v[146:147]
	v_lshl_add_u64 v[80:81], v[80:81], 0, v[148:149]
	v_add_co_u32_e32 v90, vcc, s62, v80
	v_cvt_pk_bf16_f32 v85, v88, v89
	global_store_dwordx4 v[96:97], v[82:85], off offset:256
	s_nop 0
	v_addc_co_u32_e32 v91, vcc, 0, v81, vcc
	s_waitcnt vmcnt(15)
; __device__ __forceinline__ float sigmoidf_(float x) { return 1.0f / (1.0f + __expf(-x)); }
; __device__ __forceinline__ u32x4 pack8(const f32x4 v0, const f32x4 v1) { u32x4 w; w.x = pk2(v0[0], v0[1]); w.y = pk2(v0[2], v0[3]); w.z = pk2(v1[0], v1[1]); w.w = pk2(v1[2], v1[3]); return w; }
; __device__ __forceinline__ void unpack8(const u32x4 w, f32x4& v0, f32x4& v1) { v0 = (f32x4){bflo(w.x), bfhi(w.x), bflo(w.y), bfhi(w.y)}; v1 = (f32x4){bflo(w.z), bfhi(w.z), bflo(w.w), bfhi(w.w)}; }
;     __device__ __forceinline__ void operator()(const f32x4 (&acc)[2][2][4][2], const Unit& u, int wr, int wc, int fr, int fq) const {
;     ...
;         for (int ai = 0; ai < 2; ++ai)
; #pragma unroll
;             for (int m = 0; m < 4; ++m) {
;                 bf16_t* rowp = z + (size_t)(row0 + ai * 128 + m * 16) * DIN + col0;
; #pragma unroll
;                 for (int bj = 0; bj < 2; ++bj) {
;                     const u32x4 gw = *(const u32x4*)(rowp + (MODE == 0 ? O_GB : O_GA) + bj * 128);
;                     f32x4 g0, g1; unpack8(gw, g0, g1);
;                     f32x4 v0, v1;
; #pragma unroll
;                     for (int j = 0; j < 4; ++j) { v0[j] = sigmoidf_(g0[j]) * acc[ai][bj][m][0][j]; v1[j] = sigmoidf_(g1[j]) * acc[ai][bj][m][1][j]; }
;                     if (MODE == 1) { const u32x4 mw = *(const u32x4*)(rowp + bj * 128); f32x4 m0, m1; unpack8(mw, m0, m1); v0 += m0; v1 += m1; }
;                     *(u32x4*)(rowp + bj * 128) = pack8(v0, v1); }
	v_mov_b32_e32 v86, v236
	v_mov_b32_e32 v87, v237
	v_mov_b32_e32 v88, v238
	v_mov_b32_e32 v89, v239
	v_lshlrev_b32_e32 v82, 16, v86
	v_mul_f32_e32 v82, 0xbfb8aa3b, v82
	v_exp_f32_e32 v82, v82
	v_lshlrev_b32_e32 v84, 16, v87
	v_and_b32_e32 v85, 0xffff0000, v87
	v_and_b32_e32 v83, 0xffff0000, v86
	v_add_f32_e32 v82, 1.0, v82
	v_div_scale_f32 v87, s[6:7], v82, v82, 1.0
	v_rcp_f32_e32 v92, v87
	v_lshlrev_b32_e32 v86, 16, v88
	v_mul_f32_e32 v86, 0xbfb8aa3b, v86
	v_exp_f32_e32 v86, v86
	v_fma_f32 v94, -v87, v92, 1.0
	v_fmac_f32_e32 v92, v94, v92
	v_div_scale_f32 v94, vcc, 1.0, v82, 1.0
	v_mul_f32_e32 v95, v94, v92
	v_fma_f32 v96, -v87, v95, v94
	v_fmac_f32_e32 v95, v96, v92
	v_add_f32_e32 v86, 1.0, v86
	v_fma_f32 v87, -v87, v95, v94
	v_div_scale_f32 v94, s[6:7], v86, v86, 1.0
	v_rcp_f32_e32 v96, v94
	v_div_fmas_f32 v87, v87, v92, v95
	v_mul_f32_e32 v83, 0xbfb8aa3b, v83
	v_div_fixup_f32 v82, v87, v82, 1.0
	v_exp_f32_e32 v83, v83
	v_mul_f32_e32 v76, v76, v82
	v_fma_f32 v82, -v94, v96, 1.0
	v_fmac_f32_e32 v96, v82, v96
	v_div_scale_f32 v82, vcc, 1.0, v86, 1.0
	v_mul_f32_e32 v87, v82, v96
	v_fma_f32 v92, -v94, v87, v82
	v_add_f32_e32 v83, 1.0, v83
	v_fmac_f32_e32 v87, v92, v96
	v_div_scale_f32 v92, s[6:7], v83, v83, 1.0
	v_fma_f32 v82, -v94, v87, v82
	v_rcp_f32_e32 v94, v92
	v_and_b32_e32 v88, 0xffff0000, v88
	v_div_fmas_f32 v82, v82, v96, v87
	v_mul_f32_e32 v87, 0xbfb8aa3b, v88
	v_div_fixup_f32 v82, v82, v86, 1.0
	v_exp_f32_e32 v87, v87
	v_mul_f32_e32 v82, v72, v82
	v_fma_f32 v72, -v92, v94, 1.0
	v_fmac_f32_e32 v94, v72, v94
	v_div_scale_f32 v72, vcc, 1.0, v83, 1.0
	v_mul_f32_e32 v86, v72, v94
	v_fma_f32 v88, -v92, v86, v72
	v_add_f32_e32 v87, 1.0, v87
	v_fmac_f32_e32 v86, v88, v94
	v_div_scale_f32 v88, s[6:7], v87, v87, 1.0
	v_fma_f32 v72, -v92, v86, v72
	v_rcp_f32_e32 v92, v88
	v_div_fmas_f32 v72, v72, v94, v86
	v_mul_f32_e32 v84, 0xbfb8aa3b, v84
	v_div_fixup_f32 v72, v72, v83, 1.0
	v_exp_f32_e32 v84, v84
	v_mul_f32_e32 v72, v77, v72
	v_fma_f32 v77, -v88, v92, 1.0
	v_fmac_f32_e32 v92, v77, v92
	v_div_scale_f32 v77, vcc, 1.0, v87, 1.0
	v_mul_f32_e32 v83, v77, v92
	v_fma_f32 v86, -v88, v83, v77
	v_add_f32_e32 v84, 1.0, v84
	v_fmac_f32_e32 v83, v86, v92
	v_div_scale_f32 v86, s[6:7], v84, v84, 1.0
	v_fma_f32 v77, -v88, v83, v77
	v_rcp_f32_e32 v88, v86
	v_div_fmas_f32 v77, v77, v92, v83
	v_lshlrev_b32_e32 v93, 16, v89
	v_div_fixup_f32 v77, v77, v87, 1.0
	v_mul_f32_e32 v77, v73, v77
	v_fma_f32 v73, -v86, v88, 1.0
	v_mul_f32_e32 v87, 0xbfb8aa3b, v93
	v_fmac_f32_e32 v88, v73, v88
	v_div_scale_f32 v73, vcc, 1.0, v84, 1.0
	v_exp_f32_e32 v87, v87
	v_mul_f32_e32 v83, v73, v88
	v_fma_f32 v92, -v86, v83, v73
	v_fmac_f32_e32 v83, v92, v88
	v_fma_f32 v73, -v86, v83, v73
	v_add_f32_e32 v86, 1.0, v87
	v_div_scale_f32 v87, s[6:7], v86, v86, 1.0
	v_rcp_f32_e32 v92, v87
	v_div_fmas_f32 v73, v73, v88, v83
	v_div_fixup_f32 v73, v73, v84, 1.0
	v_mul_f32_e32 v84, 0xbfb8aa3b, v85
	v_exp_f32_e32 v84, v84
	v_mul_f32_e32 v73, v78, v73
	v_fma_f32 v78, -v87, v92, 1.0
	v_fmac_f32_e32 v92, v78, v92
	v_div_scale_f32 v78, vcc, 1.0, v86, 1.0
	v_mul_f32_e32 v83, v78, v92
	v_fma_f32 v85, -v87, v83, v78
	v_add_f32_e32 v84, 1.0, v84
	v_fmac_f32_e32 v83, v85, v92
	v_div_scale_f32 v85, s[6:7], v84, v84, 1.0
	v_fma_f32 v78, -v87, v83, v78
	v_rcp_f32_e32 v87, v85
	v_div_fmas_f32 v78, v78, v92, v83
	v_and_b32_e32 v89, 0xffff0000, v89
	v_div_fixup_f32 v78, v78, v86, 1.0
	v_mul_f32_e32 v78, v74, v78
	v_fma_f32 v74, -v85, v87, 1.0
	v_mul_f32_e32 v86, 0xbfb8aa3b, v89
	v_fmac_f32_e32 v87, v74, v87
	v_div_scale_f32 v74, vcc, 1.0, v84, 1.0
	v_exp_f32_e32 v86, v86
	v_mul_f32_e32 v83, v74, v87
	v_fma_f32 v88, -v85, v83, v74
	v_fmac_f32_e32 v83, v88, v87
	v_fma_f32 v74, -v85, v83, v74
	v_add_f32_e32 v85, 1.0, v86
	v_div_scale_f32 v86, s[6:7], v85, v85, 1.0
	v_rcp_f32_e32 v88, v86
	v_div_fmas_f32 v74, v74, v87, v83
	v_div_fixup_f32 v74, v74, v84, 1.0
	v_mul_f32_e32 v74, v79, v74
	v_fma_f32 v79, -v86, v88, 1.0
	v_fmac_f32_e32 v88, v79, v88
	v_div_scale_f32 v79, vcc, 1.0, v85, 1.0
	v_mul_f32_e32 v83, v79, v88
	v_fma_f32 v84, -v86, v83, v79
	v_fmac_f32_e32 v83, v84, v88
	v_fma_f32 v79, -v86, v83, v79
	v_div_fmas_f32 v79, v79, v88, v83
	v_div_fixup_f32 v79, v79, v85, 1.0
	v_mul_f32_e32 v75, v75, v79
	v_cvt_pk_bf16_f32 v72, v76, v72
	v_cvt_pk_bf16_f32 v73, v73, v74
	v_cvt_pk_bf16_f32 v74, v82, v77
	v_cvt_pk_bf16_f32 v75, v78, v75
	s_waitcnt vmcnt(14)
; __device__ __forceinline__ float sigmoidf_(float x) { return 1.0f / (1.0f + __expf(-x)); }
; __device__ __forceinline__ u32x4 pack8(const f32x4 v0, const f32x4 v1) { u32x4 w; w.x = pk2(v0[0], v0[1]); w.y = pk2(v0[2], v0[3]); w.z = pk2(v1[0], v1[1]); w.w = pk2(v1[2], v1[3]); return w; }
; __device__ __forceinline__ void unpack8(const u32x4 w, f32x4& v0, f32x4& v1) { v0 = (f32x4){bflo(w.x), bfhi(w.x), bflo(w.y), bfhi(w.y)}; v1 = (f32x4){bflo(w.z), bfhi(w.z), bflo(w.w), bfhi(w.w)}; }
;     __device__ __forceinline__ void operator()(const f32x4 (&acc)[2][2][4][2], const Unit& u, int wr, int wc, int fr, int fq) const {
;     ...
;         for (int ai = 0; ai < 2; ++ai)
; #pragma unroll
;             for (int m = 0; m < 4; ++m) {
;                 bf16_t* rowp = z + (size_t)(row0 + ai * 128 + m * 16) * DIN + col0;
; #pragma unroll
;                 for (int bj = 0; bj < 2; ++bj) {
;                     const u32x4 gw = *(const u32x4*)(rowp + (MODE == 0 ? O_GB : O_GA) + bj * 128);
;                     f32x4 g0, g1; unpack8(gw, g0, g1);
;                     f32x4 v0, v1;
; #pragma unroll
;                     for (int j = 0; j < 4; ++j) { v0[j] = sigmoidf_(g0[j]) * acc[ai][bj][m][0][j]; v1[j] = sigmoidf_(g1[j]) * acc[ai][bj][m][1][j]; }
;                     if (MODE == 1) { const u32x4 mw = *(const u32x4*)(rowp + bj * 128); f32x4 m0, m1; unpack8(mw, m0, m1); v0 += m0; v1 += m1; }
;                     *(u32x4*)(rowp + bj * 128) = pack8(v0, v1); }
	v_mov_b32_e32 v76, v240
	v_mov_b32_e32 v77, v241
	v_mov_b32_e32 v78, v242
	v_mov_b32_e32 v79, v243
	v_lshlrev_b32_e32 v83, 16, v79
	global_store_dwordx4 v[80:81], v[72:75], off
	v_and_b32_e32 v79, 0xffff0000, v79
	s_nop 0
	v_lshlrev_b32_e32 v72, 16, v76
	v_mul_f32_e32 v72, 0xbfb8aa3b, v72
	v_exp_f32_e32 v72, v72
	v_lshlrev_b32_e32 v74, 16, v77
	v_and_b32_e32 v75, 0xffff0000, v77
	v_and_b32_e32 v73, 0xffff0000, v76
	v_add_f32_e32 v72, 1.0, v72
	v_div_scale_f32 v77, s[6:7], v72, v72, 1.0
	v_rcp_f32_e32 v82, v77
	v_lshlrev_b32_e32 v76, 16, v78
	v_mul_f32_e32 v76, 0xbfb8aa3b, v76
	v_exp_f32_e32 v76, v76
	v_fma_f32 v84, -v77, v82, 1.0
	v_fmac_f32_e32 v82, v84, v82
	v_div_scale_f32 v84, vcc, 1.0, v72, 1.0
	v_mul_f32_e32 v85, v84, v82
	v_fma_f32 v86, -v77, v85, v84
	v_fmac_f32_e32 v85, v86, v82
	v_add_f32_e32 v76, 1.0, v76
	v_fma_f32 v77, -v77, v85, v84
	v_div_scale_f32 v84, s[6:7], v76, v76, 1.0
	v_rcp_f32_e32 v86, v84
	v_div_fmas_f32 v77, v77, v82, v85
	v_mul_f32_e32 v73, 0xbfb8aa3b, v73
	v_div_fixup_f32 v72, v77, v72, 1.0
	v_exp_f32_e32 v73, v73
	v_mul_f32_e32 v68, v68, v72
	v_fma_f32 v72, -v84, v86, 1.0
	v_fmac_f32_e32 v86, v72, v86
	v_div_scale_f32 v72, vcc, 1.0, v76, 1.0
	v_mul_f32_e32 v77, v72, v86
	v_fma_f32 v82, -v84, v77, v72
	v_add_f32_e32 v73, 1.0, v73
	v_fmac_f32_e32 v77, v82, v86
	v_div_scale_f32 v82, s[6:7], v73, v73, 1.0
	v_fma_f32 v72, -v84, v77, v72
	v_rcp_f32_e32 v84, v82
	v_and_b32_e32 v78, 0xffff0000, v78
	v_div_fmas_f32 v72, v72, v86, v77
	v_mul_f32_e32 v77, 0xbfb8aa3b, v78
	v_div_fixup_f32 v72, v72, v76, 1.0
	v_exp_f32_e32 v77, v77
	v_mul_f32_e32 v64, v64, v72
	v_fma_f32 v72, -v82, v84, 1.0
	v_fmac_f32_e32 v84, v72, v84
	v_div_scale_f32 v72, vcc, 1.0, v73, 1.0
	v_mul_f32_e32 v76, v72, v84
	v_fma_f32 v78, -v82, v76, v72
	v_add_f32_e32 v77, 1.0, v77
	v_fmac_f32_e32 v76, v78, v84
	v_div_scale_f32 v78, s[6:7], v77, v77, 1.0
	v_fma_f32 v72, -v82, v76, v72
	v_rcp_f32_e32 v82, v78
	v_div_fmas_f32 v72, v72, v84, v76
	v_mul_f32_e32 v74, 0xbfb8aa3b, v74
	v_div_fixup_f32 v72, v72, v73, 1.0
	v_exp_f32_e32 v74, v74
	v_mul_f32_e32 v69, v69, v72
	v_fma_f32 v72, -v78, v82, 1.0
	v_fmac_f32_e32 v82, v72, v82
	v_div_scale_f32 v72, vcc, 1.0, v77, 1.0
	v_mul_f32_e32 v73, v72, v82
	v_fma_f32 v76, -v78, v73, v72
	v_add_f32_e32 v74, 1.0, v74
	v_fmac_f32_e32 v73, v76, v82
	v_div_scale_f32 v76, s[6:7], v74, v74, 1.0
	v_fma_f32 v72, -v78, v73, v72
	v_rcp_f32_e32 v78, v76
	v_div_fmas_f32 v72, v72, v82, v73
	v_div_fixup_f32 v72, v72, v77, 1.0
	v_mul_f32_e32 v65, v65, v72
	v_fma_f32 v72, -v76, v78, 1.0
	v_mul_f32_e32 v77, 0xbfb8aa3b, v83
	v_fmac_f32_e32 v78, v72, v78
	v_div_scale_f32 v72, vcc, 1.0, v74, 1.0
	v_exp_f32_e32 v77, v77
	v_mul_f32_e32 v73, v72, v78
	v_fma_f32 v82, -v76, v73, v72
	v_fmac_f32_e32 v73, v82, v78
	v_fma_f32 v72, -v76, v73, v72
	v_add_f32_e32 v76, 1.0, v77
	v_div_scale_f32 v77, s[6:7], v76, v76, 1.0
	v_rcp_f32_e32 v82, v77
	v_div_fmas_f32 v72, v72, v78, v73
	v_div_fixup_f32 v72, v72, v74, 1.0
	v_mul_f32_e32 v74, 0xbfb8aa3b, v75
	v_exp_f32_e32 v74, v74
	v_mul_f32_e32 v70, v70, v72
	v_fma_f32 v72, -v77, v82, 1.0
	v_fmac_f32_e32 v82, v72, v82
	v_div_scale_f32 v72, vcc, 1.0, v76, 1.0
	v_mul_f32_e32 v73, v72, v82
	v_fma_f32 v75, -v77, v73, v72
	v_add_f32_e32 v74, 1.0, v74
	v_fmac_f32_e32 v73, v75, v82
	v_div_scale_f32 v75, s[6:7], v74, v74, 1.0
	v_fma_f32 v72, -v77, v73, v72
	v_rcp_f32_e32 v77, v75
	v_div_fmas_f32 v72, v72, v82, v73
	v_div_fixup_f32 v72, v72, v76, 1.0
	v_mul_f32_e32 v72, v66, v72
	v_fma_f32 v66, -v75, v77, 1.0
	v_mul_f32_e32 v76, 0xbfb8aa3b, v79
	v_fmac_f32_e32 v77, v66, v77
	v_div_scale_f32 v66, vcc, 1.0, v74, 1.0
	v_exp_f32_e32 v76, v76
	v_mul_f32_e32 v73, v66, v77
	v_fma_f32 v78, -v75, v73, v66
	v_fmac_f32_e32 v73, v78, v77
	v_fma_f32 v66, -v75, v73, v66
	v_add_f32_e32 v75, 1.0, v76
	v_div_scale_f32 v76, s[6:7], v75, v75, 1.0
	v_rcp_f32_e32 v78, v76
	v_div_fmas_f32 v66, v66, v77, v73
	v_div_fixup_f32 v66, v66, v74, 1.0
	v_mul_f32_e32 v71, v71, v66
	v_fma_f32 v66, -v76, v78, 1.0
	v_fmac_f32_e32 v78, v66, v78
	v_div_scale_f32 v66, vcc, 1.0, v75, 1.0
	v_mul_f32_e32 v73, v66, v78
	v_fma_f32 v74, -v76, v73, v66
	v_fmac_f32_e32 v73, v74, v78
	v_fma_f32 v66, -v76, v73, v66
	v_div_fmas_f32 v66, v66, v78, v73
	v_div_fixup_f32 v66, v66, v75, 1.0
	v_mul_f32_e32 v73, v67, v66
	v_cvt_pk_bf16_f32 v66, v68, v69
	v_cvt_pk_bf16_f32 v67, v70, v71
	v_cvt_pk_bf16_f32 v68, v64, v65
	v_add_u32_e32 v64, 0x80, v160
	v_mad_i64_i32 v[64:65], s[6:7], v64, s61, v[146:147]
	v_lshl_add_u64 v[64:65], v[64:65], 0, v[148:149]
	v_add_co_u32_e32 v74, vcc, s62, v64
	v_cvt_pk_bf16_f32 v69, v72, v73
	global_store_dwordx4 v[80:81], v[66:69], off offset:256
	s_nop 0
	v_addc_co_u32_e32 v75, vcc, 0, v65, vcc
	s_waitcnt vmcnt(15)
; __device__ __forceinline__ float sigmoidf_(float x) { return 1.0f / (1.0f + __expf(-x)); }
; __device__ __forceinline__ u32x4 pack8(const f32x4 v0, const f32x4 v1) { u32x4 w; w.x = pk2(v0[0], v0[1]); w.y = pk2(v0[2], v0[3]); w.z = pk2(v1[0], v1[1]); w.w = pk2(v1[2], v1[3]); return w; }
; __device__ __forceinline__ void unpack8(const u32x4 w, f32x4& v0, f32x4& v1) { v0 = (f32x4){bflo(w.x), bfhi(w.x), bflo(w.y), bfhi(w.y)}; v1 = (f32x4){bflo(w.z), bfhi(w.z), bflo(w.w), bfhi(w.w)}; }
;     __device__ __forceinline__ void operator()(const f32x4 (&acc)[2][2][4][2], const Unit& u, int wr, int wc, int fr, int fq) const {
;     ...
;         for (int ai = 0; ai < 2; ++ai)
; #pragma unroll
;             for (int m = 0; m < 4; ++m) {
;                 bf16_t* rowp = z + (size_t)(row0 + ai * 128 + m * 16) * DIN + col0;
; #pragma unroll
;                 for (int bj = 0; bj < 2; ++bj) {
;                     const u32x4 gw = *(const u32x4*)(rowp + (MODE == 0 ? O_GB : O_GA) + bj * 128);
;                     f32x4 g0, g1; unpack8(gw, g0, g1);
;                     f32x4 v0, v1;
; #pragma unroll
;                     for (int j = 0; j < 4; ++j) { v0[j] = sigmoidf_(g0[j]) * acc[ai][bj][m][0][j]; v1[j] = sigmoidf_(g1[j]) * acc[ai][bj][m][1][j]; }
;                     if (MODE == 1) { const u32x4 mw = *(const u32x4*)(rowp + bj * 128); f32x4 m0, m1; unpack8(mw, m0, m1); v0 += m0; v1 += m1; }
;                     *(u32x4*)(rowp + bj * 128) = pack8(v0, v1); }
	v_mov_b32_e32 v70, v244
	v_mov_b32_e32 v71, v245
	v_mov_b32_e32 v72, v246
	v_mov_b32_e32 v73, v247
	v_lshlrev_b32_e32 v66, 16, v70
	v_mul_f32_e32 v66, 0xbfb8aa3b, v66
	v_exp_f32_e32 v66, v66
	v_lshlrev_b32_e32 v68, 16, v71
	v_and_b32_e32 v69, 0xffff0000, v71
	v_and_b32_e32 v67, 0xffff0000, v70
	v_add_f32_e32 v66, 1.0, v66
	v_div_scale_f32 v71, s[6:7], v66, v66, 1.0
	v_rcp_f32_e32 v76, v71
	v_lshlrev_b32_e32 v70, 16, v72
	v_mul_f32_e32 v70, 0xbfb8aa3b, v70
	v_exp_f32_e32 v70, v70
	v_fma_f32 v78, -v71, v76, 1.0
	v_fmac_f32_e32 v76, v78, v76
	v_div_scale_f32 v78, vcc, 1.0, v66, 1.0
	v_mul_f32_e32 v79, v78, v76
	v_fma_f32 v80, -v71, v79, v78
	v_fmac_f32_e32 v79, v80, v76
	v_add_f32_e32 v70, 1.0, v70
	v_fma_f32 v71, -v71, v79, v78
	v_div_scale_f32 v78, s[6:7], v70, v70, 1.0
	v_rcp_f32_e32 v80, v78
	v_div_fmas_f32 v71, v71, v76, v79
	v_mul_f32_e32 v67, 0xbfb8aa3b, v67
	v_div_fixup_f32 v66, v71, v66, 1.0
	v_exp_f32_e32 v67, v67
	v_mul_f32_e32 v60, v60, v66
	v_fma_f32 v66, -v78, v80, 1.0
	v_fmac_f32_e32 v80, v66, v80
	v_div_scale_f32 v66, vcc, 1.0, v70, 1.0
	v_mul_f32_e32 v71, v66, v80
	v_fma_f32 v76, -v78, v71, v66
	v_add_f32_e32 v67, 1.0, v67
	v_fmac_f32_e32 v71, v76, v80
	v_div_scale_f32 v76, s[6:7], v67, v67, 1.0
	v_fma_f32 v66, -v78, v71, v66
	v_rcp_f32_e32 v78, v76
	v_and_b32_e32 v72, 0xffff0000, v72
	v_div_fmas_f32 v66, v66, v80, v71
	v_mul_f32_e32 v71, 0xbfb8aa3b, v72
	v_div_fixup_f32 v66, v66, v70, 1.0
	v_exp_f32_e32 v71, v71
	v_mul_f32_e32 v66, v56, v66
	v_fma_f32 v56, -v76, v78, 1.0
	v_fmac_f32_e32 v78, v56, v78
	v_div_scale_f32 v56, vcc, 1.0, v67, 1.0
	v_mul_f32_e32 v70, v56, v78
	v_fma_f32 v72, -v76, v70, v56
	v_add_f32_e32 v71, 1.0, v71
	v_fmac_f32_e32 v70, v72, v78
	v_div_scale_f32 v72, s[6:7], v71, v71, 1.0
	v_fma_f32 v56, -v76, v70, v56
	v_rcp_f32_e32 v76, v72
	v_div_fmas_f32 v56, v56, v78, v70
	v_mul_f32_e32 v68, 0xbfb8aa3b, v68
	v_div_fixup_f32 v56, v56, v67, 1.0
	v_exp_f32_e32 v68, v68
	v_mul_f32_e32 v56, v61, v56
	v_fma_f32 v61, -v72, v76, 1.0
	v_fmac_f32_e32 v76, v61, v76
	v_div_scale_f32 v61, vcc, 1.0, v71, 1.0
	v_mul_f32_e32 v67, v61, v76
	v_fma_f32 v70, -v72, v67, v61
	v_add_f32_e32 v68, 1.0, v68
	v_fmac_f32_e32 v67, v70, v76
	v_div_scale_f32 v70, s[6:7], v68, v68, 1.0
	v_fma_f32 v61, -v72, v67, v61
	v_rcp_f32_e32 v72, v70
	v_div_fmas_f32 v61, v61, v76, v67
	v_lshlrev_b32_e32 v77, 16, v73
	v_div_fixup_f32 v61, v61, v71, 1.0
	v_mul_f32_e32 v61, v57, v61
	v_fma_f32 v57, -v70, v72, 1.0
	v_mul_f32_e32 v71, 0xbfb8aa3b, v77
	v_fmac_f32_e32 v72, v57, v72
	v_div_scale_f32 v57, vcc, 1.0, v68, 1.0
	v_exp_f32_e32 v71, v71
	v_mul_f32_e32 v67, v57, v72
	v_fma_f32 v76, -v70, v67, v57
	v_fmac_f32_e32 v67, v76, v72
	v_fma_f32 v57, -v70, v67, v57
	v_add_f32_e32 v70, 1.0, v71
	v_div_scale_f32 v71, s[6:7], v70, v70, 1.0
	v_rcp_f32_e32 v76, v71
	v_div_fmas_f32 v57, v57, v72, v67
	v_div_fixup_f32 v57, v57, v68, 1.0
	v_mul_f32_e32 v68, 0xbfb8aa3b, v69
	v_exp_f32_e32 v68, v68
	v_mul_f32_e32 v57, v62, v57
	v_fma_f32 v62, -v71, v76, 1.0
	v_fmac_f32_e32 v76, v62, v76
	v_div_scale_f32 v62, vcc, 1.0, v70, 1.0
	v_mul_f32_e32 v67, v62, v76
	v_fma_f32 v69, -v71, v67, v62
	v_add_f32_e32 v68, 1.0, v68
	v_fmac_f32_e32 v67, v69, v76
	v_div_scale_f32 v69, s[6:7], v68, v68, 1.0
	v_fma_f32 v62, -v71, v67, v62
	v_rcp_f32_e32 v71, v69
	v_div_fmas_f32 v62, v62, v76, v67
	v_and_b32_e32 v73, 0xffff0000, v73
	v_div_fixup_f32 v62, v62, v70, 1.0
	v_mul_f32_e32 v62, v58, v62
	v_fma_f32 v58, -v69, v71, 1.0
	v_mul_f32_e32 v70, 0xbfb8aa3b, v73
	v_fmac_f32_e32 v71, v58, v71
	v_div_scale_f32 v58, vcc, 1.0, v68, 1.0
	v_exp_f32_e32 v70, v70
	v_mul_f32_e32 v67, v58, v71
	v_fma_f32 v72, -v69, v67, v58
	v_fmac_f32_e32 v67, v72, v71
	v_fma_f32 v58, -v69, v67, v58
	v_add_f32_e32 v69, 1.0, v70
	v_div_scale_f32 v70, s[6:7], v69, v69, 1.0
	v_rcp_f32_e32 v72, v70
	v_div_fmas_f32 v58, v58, v71, v67
	v_div_fixup_f32 v58, v58, v68, 1.0
	v_mul_f32_e32 v58, v63, v58
	v_fma_f32 v63, -v70, v72, 1.0
	v_fmac_f32_e32 v72, v63, v72
	v_div_scale_f32 v63, vcc, 1.0, v69, 1.0
	v_mul_f32_e32 v67, v63, v72
	v_fma_f32 v68, -v70, v67, v63
	v_fmac_f32_e32 v67, v68, v72
	v_fma_f32 v63, -v70, v67, v63
	v_div_fmas_f32 v63, v63, v72, v67
	v_div_fixup_f32 v63, v63, v69, 1.0
	v_mul_f32_e32 v59, v59, v63
	v_cvt_pk_bf16_f32 v56, v60, v56
	v_cvt_pk_bf16_f32 v57, v57, v58
	v_cvt_pk_bf16_f32 v58, v66, v61
	v_cvt_pk_bf16_f32 v59, v62, v59
	s_waitcnt vmcnt(14)
; __device__ __forceinline__ float sigmoidf_(float x) { return 1.0f / (1.0f + __expf(-x)); }
; __device__ __forceinline__ u32x4 pack8(const f32x4 v0, const f32x4 v1) { u32x4 w; w.x = pk2(v0[0], v0[1]); w.y = pk2(v0[2], v0[3]); w.z = pk2(v1[0], v1[1]); w.w = pk2(v1[2], v1[3]); return w; }
; __device__ __forceinline__ void unpack8(const u32x4 w, f32x4& v0, f32x4& v1) { v0 = (f32x4){bflo(w.x), bfhi(w.x), bflo(w.y), bfhi(w.y)}; v1 = (f32x4){bflo(w.z), bfhi(w.z), bflo(w.w), bfhi(w.w)}; }
;     __device__ __forceinline__ void operator()(const f32x4 (&acc)[2][2][4][2], const Unit& u, int wr, int wc, int fr, int fq) const {
;     ...
;         for (int ai = 0; ai < 2; ++ai)
; #pragma unroll
;             for (int m = 0; m < 4; ++m) {
;                 bf16_t* rowp = z + (size_t)(row0 + ai * 128 + m * 16) * DIN + col0;
; #pragma unroll
;                 for (int bj = 0; bj < 2; ++bj) {
;                     const u32x4 gw = *(const u32x4*)(rowp + (MODE == 0 ? O_GB : O_GA) + bj * 128);
;                     f32x4 g0, g1; unpack8(gw, g0, g1);
;                     f32x4 v0, v1;
; #pragma unroll
;                     for (int j = 0; j < 4; ++j) { v0[j] = sigmoidf_(g0[j]) * acc[ai][bj][m][0][j]; v1[j] = sigmoidf_(g1[j]) * acc[ai][bj][m][1][j]; }
;                     if (MODE == 1) { const u32x4 mw = *(const u32x4*)(rowp + bj * 128); f32x4 m0, m1; unpack8(mw, m0, m1); v0 += m0; v1 += m1; }
;                     *(u32x4*)(rowp + bj * 128) = pack8(v0, v1); }
	v_mov_b32_e32 v60, v248
	v_mov_b32_e32 v61, v249
	v_mov_b32_e32 v62, v250
	v_mov_b32_e32 v63, v251
	v_lshlrev_b32_e32 v67, 16, v63
	global_store_dwordx4 v[64:65], v[56:59], off
	v_and_b32_e32 v63, 0xffff0000, v63
	s_nop 0
	v_lshlrev_b32_e32 v56, 16, v60
	v_mul_f32_e32 v56, 0xbfb8aa3b, v56
	v_exp_f32_e32 v56, v56
	v_lshlrev_b32_e32 v58, 16, v61
	v_and_b32_e32 v59, 0xffff0000, v61
	v_and_b32_e32 v57, 0xffff0000, v60
	v_add_f32_e32 v56, 1.0, v56
	v_div_scale_f32 v61, s[6:7], v56, v56, 1.0
	v_rcp_f32_e32 v66, v61
	v_lshlrev_b32_e32 v60, 16, v62
	v_mul_f32_e32 v60, 0xbfb8aa3b, v60
	v_exp_f32_e32 v60, v60
	v_fma_f32 v68, -v61, v66, 1.0
	v_fmac_f32_e32 v66, v68, v66
	v_div_scale_f32 v68, vcc, 1.0, v56, 1.0
	v_mul_f32_e32 v69, v68, v66
	v_fma_f32 v70, -v61, v69, v68
	v_fmac_f32_e32 v69, v70, v66
	v_add_f32_e32 v60, 1.0, v60
	v_fma_f32 v61, -v61, v69, v68
	v_div_scale_f32 v68, s[6:7], v60, v60, 1.0
	v_rcp_f32_e32 v70, v68
	v_div_fmas_f32 v61, v61, v66, v69
	v_mul_f32_e32 v57, 0xbfb8aa3b, v57
	v_div_fixup_f32 v56, v61, v56, 1.0
	v_exp_f32_e32 v57, v57
	v_mul_f32_e32 v52, v52, v56
	v_fma_f32 v56, -v68, v70, 1.0
	v_fmac_f32_e32 v70, v56, v70
	v_div_scale_f32 v56, vcc, 1.0, v60, 1.0
	v_mul_f32_e32 v61, v56, v70
	v_fma_f32 v66, -v68, v61, v56
	v_add_f32_e32 v57, 1.0, v57
	v_fmac_f32_e32 v61, v66, v70
	v_div_scale_f32 v66, s[6:7], v57, v57, 1.0
	v_fma_f32 v56, -v68, v61, v56
	v_rcp_f32_e32 v68, v66
	v_and_b32_e32 v62, 0xffff0000, v62
	v_div_fmas_f32 v56, v56, v70, v61
	v_mul_f32_e32 v61, 0xbfb8aa3b, v62
	v_div_fixup_f32 v56, v56, v60, 1.0
	v_exp_f32_e32 v61, v61
	v_mul_f32_e32 v48, v48, v56
	v_fma_f32 v56, -v66, v68, 1.0
	v_fmac_f32_e32 v68, v56, v68
	v_div_scale_f32 v56, vcc, 1.0, v57, 1.0
	v_mul_f32_e32 v60, v56, v68
	v_fma_f32 v62, -v66, v60, v56
	v_add_f32_e32 v61, 1.0, v61
	v_fmac_f32_e32 v60, v62, v68
	v_div_scale_f32 v62, s[6:7], v61, v61, 1.0
	v_fma_f32 v56, -v66, v60, v56
	v_rcp_f32_e32 v66, v62
	v_div_fmas_f32 v56, v56, v68, v60
	v_mul_f32_e32 v58, 0xbfb8aa3b, v58
	v_div_fixup_f32 v56, v56, v57, 1.0
	v_exp_f32_e32 v58, v58
	v_mul_f32_e32 v53, v53, v56
	v_fma_f32 v56, -v62, v66, 1.0
	v_fmac_f32_e32 v66, v56, v66
	v_div_scale_f32 v56, vcc, 1.0, v61, 1.0
	v_mul_f32_e32 v57, v56, v66
	v_fma_f32 v60, -v62, v57, v56
	v_add_f32_e32 v58, 1.0, v58
	v_fmac_f32_e32 v57, v60, v66
	v_div_scale_f32 v60, s[6:7], v58, v58, 1.0
	v_fma_f32 v56, -v62, v57, v56
	v_rcp_f32_e32 v62, v60
	v_div_fmas_f32 v56, v56, v66, v57
	v_div_fixup_f32 v56, v56, v61, 1.0
	v_mul_f32_e32 v49, v49, v56
	v_fma_f32 v56, -v60, v62, 1.0
	v_mul_f32_e32 v61, 0xbfb8aa3b, v67
	v_fmac_f32_e32 v62, v56, v62
	v_div_scale_f32 v56, vcc, 1.0, v58, 1.0
	v_exp_f32_e32 v61, v61
	v_mul_f32_e32 v57, v56, v62
	v_fma_f32 v66, -v60, v57, v56
	v_fmac_f32_e32 v57, v66, v62
	v_fma_f32 v56, -v60, v57, v56
	v_add_f32_e32 v60, 1.0, v61
	v_div_scale_f32 v61, s[6:7], v60, v60, 1.0
	v_rcp_f32_e32 v66, v61
	v_div_fmas_f32 v56, v56, v62, v57
	v_div_fixup_f32 v56, v56, v58, 1.0
	v_mul_f32_e32 v58, 0xbfb8aa3b, v59
	v_exp_f32_e32 v58, v58
	v_mul_f32_e32 v54, v54, v56
	v_fma_f32 v56, -v61, v66, 1.0
	v_fmac_f32_e32 v66, v56, v66
	v_div_scale_f32 v56, vcc, 1.0, v60, 1.0
	v_mul_f32_e32 v57, v56, v66
	v_fma_f32 v59, -v61, v57, v56
	v_add_f32_e32 v58, 1.0, v58
	v_fmac_f32_e32 v57, v59, v66
	v_div_scale_f32 v59, s[6:7], v58, v58, 1.0
	v_fma_f32 v56, -v61, v57, v56
	v_rcp_f32_e32 v61, v59
	v_div_fmas_f32 v56, v56, v66, v57
	v_div_fixup_f32 v56, v56, v60, 1.0
	v_mul_f32_e32 v56, v50, v56
	v_fma_f32 v50, -v59, v61, 1.0
	v_mul_f32_e32 v60, 0xbfb8aa3b, v63
	v_fmac_f32_e32 v61, v50, v61
	v_div_scale_f32 v50, vcc, 1.0, v58, 1.0
	v_exp_f32_e32 v60, v60
	v_mul_f32_e32 v57, v50, v61
	v_fma_f32 v62, -v59, v57, v50
	v_fmac_f32_e32 v57, v62, v61
	v_fma_f32 v50, -v59, v57, v50
	v_add_f32_e32 v59, 1.0, v60
	v_div_scale_f32 v60, s[6:7], v59, v59, 1.0
	v_rcp_f32_e32 v62, v60
	v_div_fmas_f32 v50, v50, v61, v57
	v_div_fixup_f32 v50, v50, v58, 1.0
	v_mul_f32_e32 v55, v55, v50
	v_fma_f32 v50, -v60, v62, 1.0
	v_fmac_f32_e32 v62, v50, v62
	v_div_scale_f32 v50, vcc, 1.0, v59, 1.0
	v_mul_f32_e32 v57, v50, v62
	v_fma_f32 v58, -v60, v57, v50
	v_fmac_f32_e32 v57, v58, v62
	v_fma_f32 v50, -v60, v57, v50
	v_div_fmas_f32 v50, v50, v62, v57
	v_div_fixup_f32 v50, v50, v59, 1.0
	v_mul_f32_e32 v57, v51, v50
	v_cvt_pk_bf16_f32 v50, v52, v53
	v_cvt_pk_bf16_f32 v51, v54, v55
	v_cvt_pk_bf16_f32 v52, v48, v49
	v_add_u32_e32 v48, 0x90, v160
	v_mad_i64_i32 v[48:49], s[6:7], v48, s61, v[146:147]
	v_lshl_add_u64 v[48:49], v[48:49], 0, v[148:149]
	v_add_co_u32_e32 v58, vcc, s62, v48
	v_cvt_pk_bf16_f32 v53, v56, v57
	global_store_dwordx4 v[64:65], v[50:53], off offset:256
	s_nop 0
	v_addc_co_u32_e32 v59, vcc, 0, v49, vcc
	s_waitcnt vmcnt(15)
; __device__ __forceinline__ float sigmoidf_(float x) { return 1.0f / (1.0f + __expf(-x)); }
; __device__ __forceinline__ u32x4 pack8(const f32x4 v0, const f32x4 v1) { u32x4 w; w.x = pk2(v0[0], v0[1]); w.y = pk2(v0[2], v0[3]); w.z = pk2(v1[0], v1[1]); w.w = pk2(v1[2], v1[3]); return w; }
; __device__ __forceinline__ void unpack8(const u32x4 w, f32x4& v0, f32x4& v1) { v0 = (f32x4){bflo(w.x), bfhi(w.x), bflo(w.y), bfhi(w.y)}; v1 = (f32x4){bflo(w.z), bfhi(w.z), bflo(w.w), bfhi(w.w)}; }
;     __device__ __forceinline__ void operator()(const f32x4 (&acc)[2][2][4][2], const Unit& u, int wr, int wc, int fr, int fq) const {
;     ...
;         for (int ai = 0; ai < 2; ++ai)
; #pragma unroll
;             for (int m = 0; m < 4; ++m) {
;                 bf16_t* rowp = z + (size_t)(row0 + ai * 128 + m * 16) * DIN + col0;
; #pragma unroll
;                 for (int bj = 0; bj < 2; ++bj) {
;                     const u32x4 gw = *(const u32x4*)(rowp + (MODE == 0 ? O_GB : O_GA) + bj * 128);
;                     f32x4 g0, g1; unpack8(gw, g0, g1);
;                     f32x4 v0, v1;
; #pragma unroll
;                     for (int j = 0; j < 4; ++j) { v0[j] = sigmoidf_(g0[j]) * acc[ai][bj][m][0][j]; v1[j] = sigmoidf_(g1[j]) * acc[ai][bj][m][1][j]; }
;                     if (MODE == 1) { const u32x4 mw = *(const u32x4*)(rowp + bj * 128); f32x4 m0, m1; unpack8(mw, m0, m1); v0 += m0; v1 += m1; }
;                     *(u32x4*)(rowp + bj * 128) = pack8(v0, v1); }
	v_mov_b32_e32 v54, v252
	v_mov_b32_e32 v55, v253
	v_mov_b32_e32 v56, v254
	v_mov_b32_e32 v57, v255
	v_lshlrev_b32_e32 v50, 16, v54
	v_mul_f32_e32 v50, 0xbfb8aa3b, v50
	v_exp_f32_e32 v50, v50
	v_lshlrev_b32_e32 v52, 16, v55
	v_and_b32_e32 v53, 0xffff0000, v55
	v_and_b32_e32 v51, 0xffff0000, v54
	v_add_f32_e32 v50, 1.0, v50
	v_div_scale_f32 v55, s[6:7], v50, v50, 1.0
	v_rcp_f32_e32 v60, v55
	v_lshlrev_b32_e32 v54, 16, v56
	v_mul_f32_e32 v54, 0xbfb8aa3b, v54
	v_exp_f32_e32 v54, v54
	v_fma_f32 v62, -v55, v60, 1.0
	v_fmac_f32_e32 v60, v62, v60
	v_div_scale_f32 v62, vcc, 1.0, v50, 1.0
	v_mul_f32_e32 v63, v62, v60
	v_fma_f32 v64, -v55, v63, v62
	v_fmac_f32_e32 v63, v64, v60
	v_add_f32_e32 v54, 1.0, v54
	v_fma_f32 v55, -v55, v63, v62
	v_div_scale_f32 v62, s[6:7], v54, v54, 1.0
	v_rcp_f32_e32 v64, v62
	v_div_fmas_f32 v55, v55, v60, v63
	v_mul_f32_e32 v51, 0xbfb8aa3b, v51
	v_div_fixup_f32 v50, v55, v50, 1.0
	v_exp_f32_e32 v51, v51
	v_mul_f32_e32 v44, v44, v50
	v_fma_f32 v50, -v62, v64, 1.0
	v_fmac_f32_e32 v64, v50, v64
	v_div_scale_f32 v50, vcc, 1.0, v54, 1.0
	v_mul_f32_e32 v55, v50, v64
	v_fma_f32 v60, -v62, v55, v50
	v_add_f32_e32 v51, 1.0, v51
	v_fmac_f32_e32 v55, v60, v64
	v_div_scale_f32 v60, s[6:7], v51, v51, 1.0
	v_fma_f32 v50, -v62, v55, v50
	v_rcp_f32_e32 v62, v60
	v_and_b32_e32 v56, 0xffff0000, v56
	v_div_fmas_f32 v50, v50, v64, v55
	v_mul_f32_e32 v55, 0xbfb8aa3b, v56
	v_div_fixup_f32 v50, v50, v54, 1.0
	v_exp_f32_e32 v55, v55
	v_mul_f32_e32 v50, v40, v50
	v_fma_f32 v40, -v60, v62, 1.0
	v_fmac_f32_e32 v62, v40, v62
	v_div_scale_f32 v40, vcc, 1.0, v51, 1.0
	v_mul_f32_e32 v54, v40, v62
	v_fma_f32 v56, -v60, v54, v40
	v_add_f32_e32 v55, 1.0, v55
	v_fmac_f32_e32 v54, v56, v62
	v_div_scale_f32 v56, s[6:7], v55, v55, 1.0
	v_fma_f32 v40, -v60, v54, v40
	v_rcp_f32_e32 v60, v56
	v_div_fmas_f32 v40, v40, v62, v54
	v_mul_f32_e32 v52, 0xbfb8aa3b, v52
	v_div_fixup_f32 v40, v40, v51, 1.0
	v_exp_f32_e32 v52, v52
	v_mul_f32_e32 v40, v45, v40
	v_fma_f32 v45, -v56, v60, 1.0
	v_fmac_f32_e32 v60, v45, v60
	v_div_scale_f32 v45, vcc, 1.0, v55, 1.0
	v_mul_f32_e32 v51, v45, v60
	v_fma_f32 v54, -v56, v51, v45
	v_add_f32_e32 v52, 1.0, v52
	v_fmac_f32_e32 v51, v54, v60
	v_div_scale_f32 v54, s[6:7], v52, v52, 1.0
	v_fma_f32 v45, -v56, v51, v45
	v_rcp_f32_e32 v56, v54
	v_div_fmas_f32 v45, v45, v60, v51
	v_lshlrev_b32_e32 v61, 16, v57
	v_div_fixup_f32 v45, v45, v55, 1.0
	v_mul_f32_e32 v45, v41, v45
	v_fma_f32 v41, -v54, v56, 1.0
	v_mul_f32_e32 v55, 0xbfb8aa3b, v61
	v_fmac_f32_e32 v56, v41, v56
	v_div_scale_f32 v41, vcc, 1.0, v52, 1.0
	v_exp_f32_e32 v55, v55
	v_mul_f32_e32 v51, v41, v56
	v_fma_f32 v60, -v54, v51, v41
	v_fmac_f32_e32 v51, v60, v56
	v_fma_f32 v41, -v54, v51, v41
	v_add_f32_e32 v54, 1.0, v55
	v_div_scale_f32 v55, s[6:7], v54, v54, 1.0
	v_rcp_f32_e32 v60, v55
	v_div_fmas_f32 v41, v41, v56, v51
	v_div_fixup_f32 v41, v41, v52, 1.0
	v_mul_f32_e32 v52, 0xbfb8aa3b, v53
	v_exp_f32_e32 v52, v52
	v_mul_f32_e32 v41, v46, v41
	v_fma_f32 v46, -v55, v60, 1.0
	v_fmac_f32_e32 v60, v46, v60
	v_div_scale_f32 v46, vcc, 1.0, v54, 1.0
	v_mul_f32_e32 v51, v46, v60
	v_fma_f32 v53, -v55, v51, v46
	v_add_f32_e32 v52, 1.0, v52
	v_fmac_f32_e32 v51, v53, v60
	v_div_scale_f32 v53, s[6:7], v52, v52, 1.0
	v_fma_f32 v46, -v55, v51, v46
	v_rcp_f32_e32 v55, v53
	v_div_fmas_f32 v46, v46, v60, v51
	v_and_b32_e32 v57, 0xffff0000, v57
	v_div_fixup_f32 v46, v46, v54, 1.0
	v_mul_f32_e32 v46, v42, v46
	v_fma_f32 v42, -v53, v55, 1.0
	v_mul_f32_e32 v54, 0xbfb8aa3b, v57
	v_fmac_f32_e32 v55, v42, v55
	v_div_scale_f32 v42, vcc, 1.0, v52, 1.0
	v_exp_f32_e32 v54, v54
	v_mul_f32_e32 v51, v42, v55
	v_fma_f32 v56, -v53, v51, v42
	v_fmac_f32_e32 v51, v56, v55
	v_fma_f32 v42, -v53, v51, v42
	v_add_f32_e32 v53, 1.0, v54
	v_div_scale_f32 v54, s[6:7], v53, v53, 1.0
	v_rcp_f32_e32 v56, v54
	v_div_fmas_f32 v42, v42, v55, v51
	v_div_fixup_f32 v42, v42, v52, 1.0
	v_mul_f32_e32 v42, v47, v42
	v_fma_f32 v47, -v54, v56, 1.0
	v_fmac_f32_e32 v56, v47, v56
	v_div_scale_f32 v47, vcc, 1.0, v53, 1.0
	v_mul_f32_e32 v51, v47, v56
	v_fma_f32 v52, -v54, v51, v47
	v_fmac_f32_e32 v51, v52, v56
	v_fma_f32 v47, -v54, v51, v47
	v_div_fmas_f32 v47, v47, v56, v51
	v_div_fixup_f32 v47, v47, v53, 1.0
	v_mul_f32_e32 v43, v43, v47
	v_cvt_pk_bf16_f32 v40, v44, v40
	v_cvt_pk_bf16_f32 v41, v41, v42
	v_cvt_pk_bf16_f32 v42, v50, v45
	v_cvt_pk_bf16_f32 v43, v46, v43
	s_waitcnt vmcnt(14)
; __device__ __forceinline__ float sigmoidf_(float x) { return 1.0f / (1.0f + __expf(-x)); }
; __device__ __forceinline__ u32x4 pack8(const f32x4 v0, const f32x4 v1) { u32x4 w; w.x = pk2(v0[0], v0[1]); w.y = pk2(v0[2], v0[3]); w.z = pk2(v1[0], v1[1]); w.w = pk2(v1[2], v1[3]); return w; }
; __device__ __forceinline__ void unpack8(const u32x4 w, f32x4& v0, f32x4& v1) { v0 = (f32x4){bflo(w.x), bfhi(w.x), bflo(w.y), bfhi(w.y)}; v1 = (f32x4){bflo(w.z), bfhi(w.z), bflo(w.w), bfhi(w.w)}; }
;     __device__ __forceinline__ void operator()(const f32x4 (&acc)[2][2][4][2], const Unit& u, int wr, int wc, int fr, int fq) const {
;     ...
;         for (int ai = 0; ai < 2; ++ai)
; #pragma unroll
;             for (int m = 0; m < 4; ++m) {
;                 bf16_t* rowp = z + (size_t)(row0 + ai * 128 + m * 16) * DIN + col0;
; #pragma unroll
;                 for (int bj = 0; bj < 2; ++bj) {
;                     const u32x4 gw = *(const u32x4*)(rowp + (MODE == 0 ? O_GB : O_GA) + bj * 128);
;                     f32x4 g0, g1; unpack8(gw, g0, g1);
;                     f32x4 v0, v1;
; #pragma unroll
;                     for (int j = 0; j < 4; ++j) { v0[j] = sigmoidf_(g0[j]) * acc[ai][bj][m][0][j]; v1[j] = sigmoidf_(g1[j]) * acc[ai][bj][m][1][j]; }
;                     if (MODE == 1) { const u32x4 mw = *(const u32x4*)(rowp + bj * 128); f32x4 m0, m1; unpack8(mw, m0, m1); v0 += m0; v1 += m1; }
;                     *(u32x4*)(rowp + bj * 128) = pack8(v0, v1); }
	v_mov_b32_e32 v44, v200
	v_mov_b32_e32 v45, v201
	v_mov_b32_e32 v46, v202
	v_mov_b32_e32 v47, v203
	v_lshlrev_b32_e32 v51, 16, v47
	global_store_dwordx4 v[48:49], v[40:43], off
	v_and_b32_e32 v47, 0xffff0000, v47
	s_nop 0
	v_lshlrev_b32_e32 v40, 16, v44
	v_mul_f32_e32 v40, 0xbfb8aa3b, v40
	v_exp_f32_e32 v40, v40
	v_lshlrev_b32_e32 v42, 16, v45
	v_and_b32_e32 v43, 0xffff0000, v45
	v_and_b32_e32 v41, 0xffff0000, v44
	v_add_f32_e32 v40, 1.0, v40
	v_div_scale_f32 v45, s[6:7], v40, v40, 1.0
	v_rcp_f32_e32 v50, v45
	v_lshlrev_b32_e32 v44, 16, v46
	v_mul_f32_e32 v44, 0xbfb8aa3b, v44
	v_exp_f32_e32 v44, v44
	v_fma_f32 v52, -v45, v50, 1.0
	v_fmac_f32_e32 v50, v52, v50
	v_div_scale_f32 v52, vcc, 1.0, v40, 1.0
	v_mul_f32_e32 v53, v52, v50
	v_fma_f32 v54, -v45, v53, v52
	v_fmac_f32_e32 v53, v54, v50
	v_add_f32_e32 v44, 1.0, v44
	v_fma_f32 v45, -v45, v53, v52
	v_div_scale_f32 v52, s[6:7], v44, v44, 1.0
	v_rcp_f32_e32 v54, v52
	v_div_fmas_f32 v45, v45, v50, v53
	v_mul_f32_e32 v41, 0xbfb8aa3b, v41
	v_div_fixup_f32 v40, v45, v40, 1.0
	v_exp_f32_e32 v41, v41
	v_mul_f32_e32 v36, v36, v40
	v_fma_f32 v40, -v52, v54, 1.0
	v_fmac_f32_e32 v54, v40, v54
	v_div_scale_f32 v40, vcc, 1.0, v44, 1.0
	v_mul_f32_e32 v45, v40, v54
	v_fma_f32 v50, -v52, v45, v40
	v_add_f32_e32 v41, 1.0, v41
	v_fmac_f32_e32 v45, v50, v54
	v_div_scale_f32 v50, s[6:7], v41, v41, 1.0
	v_fma_f32 v40, -v52, v45, v40
	v_rcp_f32_e32 v52, v50
	v_and_b32_e32 v46, 0xffff0000, v46
	v_div_fmas_f32 v40, v40, v54, v45
	v_mul_f32_e32 v45, 0xbfb8aa3b, v46
	v_div_fixup_f32 v40, v40, v44, 1.0
	v_exp_f32_e32 v45, v45
	v_mul_f32_e32 v32, v32, v40
	v_fma_f32 v40, -v50, v52, 1.0
	v_fmac_f32_e32 v52, v40, v52
	v_div_scale_f32 v40, vcc, 1.0, v41, 1.0
	v_mul_f32_e32 v44, v40, v52
	v_fma_f32 v46, -v50, v44, v40
	v_add_f32_e32 v45, 1.0, v45
	v_fmac_f32_e32 v44, v46, v52
	v_div_scale_f32 v46, s[6:7], v45, v45, 1.0
	v_fma_f32 v40, -v50, v44, v40
	v_rcp_f32_e32 v50, v46
	v_div_fmas_f32 v40, v40, v52, v44
	v_mul_f32_e32 v42, 0xbfb8aa3b, v42
	v_div_fixup_f32 v40, v40, v41, 1.0
	v_exp_f32_e32 v42, v42
	v_mul_f32_e32 v37, v37, v40
	v_fma_f32 v40, -v46, v50, 1.0
	v_fmac_f32_e32 v50, v40, v50
	v_div_scale_f32 v40, vcc, 1.0, v45, 1.0
	v_mul_f32_e32 v41, v40, v50
	v_fma_f32 v44, -v46, v41, v40
	v_add_f32_e32 v42, 1.0, v42
	v_fmac_f32_e32 v41, v44, v50
	v_div_scale_f32 v44, s[6:7], v42, v42, 1.0
	v_fma_f32 v40, -v46, v41, v40
	v_rcp_f32_e32 v46, v44
	v_div_fmas_f32 v40, v40, v50, v41
	v_div_fixup_f32 v40, v40, v45, 1.0
	v_mul_f32_e32 v33, v33, v40
	v_fma_f32 v40, -v44, v46, 1.0
	v_mul_f32_e32 v45, 0xbfb8aa3b, v51
	v_fmac_f32_e32 v46, v40, v46
	v_div_scale_f32 v40, vcc, 1.0, v42, 1.0
	v_exp_f32_e32 v45, v45
	v_mul_f32_e32 v41, v40, v46
	v_fma_f32 v50, -v44, v41, v40
	v_fmac_f32_e32 v41, v50, v46
	v_fma_f32 v40, -v44, v41, v40
	v_add_f32_e32 v44, 1.0, v45
	v_div_scale_f32 v45, s[6:7], v44, v44, 1.0
	v_rcp_f32_e32 v50, v45
	v_div_fmas_f32 v40, v40, v46, v41
	v_div_fixup_f32 v40, v40, v42, 1.0
	v_mul_f32_e32 v42, 0xbfb8aa3b, v43
	v_exp_f32_e32 v42, v42
	v_mul_f32_e32 v38, v38, v40
	v_fma_f32 v40, -v45, v50, 1.0
	v_fmac_f32_e32 v50, v40, v50
	v_div_scale_f32 v40, vcc, 1.0, v44, 1.0
	v_mul_f32_e32 v41, v40, v50
	v_fma_f32 v43, -v45, v41, v40
	v_add_f32_e32 v42, 1.0, v42
	v_fmac_f32_e32 v41, v43, v50
	v_div_scale_f32 v43, s[6:7], v42, v42, 1.0
	v_fma_f32 v40, -v45, v41, v40
	v_rcp_f32_e32 v45, v43
	v_div_fmas_f32 v40, v40, v50, v41
	v_div_fixup_f32 v40, v40, v44, 1.0
	v_mul_f32_e32 v40, v34, v40
	v_fma_f32 v34, -v43, v45, 1.0
	v_mul_f32_e32 v44, 0xbfb8aa3b, v47
	v_fmac_f32_e32 v45, v34, v45
	v_div_scale_f32 v34, vcc, 1.0, v42, 1.0
	v_exp_f32_e32 v44, v44
	v_mul_f32_e32 v41, v34, v45
	v_fma_f32 v46, -v43, v41, v34
	v_fmac_f32_e32 v41, v46, v45
	v_fma_f32 v34, -v43, v41, v34
	v_add_f32_e32 v43, 1.0, v44
	v_div_scale_f32 v44, s[6:7], v43, v43, 1.0
	v_rcp_f32_e32 v46, v44
	v_div_fmas_f32 v34, v34, v45, v41
	v_div_fixup_f32 v34, v34, v42, 1.0
	v_mul_f32_e32 v39, v39, v34
	v_fma_f32 v34, -v44, v46, 1.0
	v_fmac_f32_e32 v46, v34, v46
	v_div_scale_f32 v34, vcc, 1.0, v43, 1.0
	v_mul_f32_e32 v41, v34, v46
	v_fma_f32 v42, -v44, v41, v34
	v_fmac_f32_e32 v41, v42, v46
	v_fma_f32 v34, -v44, v41, v34
	v_div_fmas_f32 v34, v34, v46, v41
	v_div_fixup_f32 v34, v34, v43, 1.0
	v_mul_f32_e32 v41, v35, v34
	v_cvt_pk_bf16_f32 v34, v36, v37
	v_cvt_pk_bf16_f32 v35, v38, v39
	v_cvt_pk_bf16_f32 v36, v32, v33
	v_add_u32_e32 v32, 0xa0, v160
	v_mad_i64_i32 v[32:33], s[6:7], v32, s61, v[146:147]
	v_lshl_add_u64 v[32:33], v[32:33], 0, v[148:149]
	v_add_co_u32_e32 v42, vcc, s62, v32
	v_cvt_pk_bf16_f32 v37, v40, v41
	global_store_dwordx4 v[48:49], v[34:37], off offset:256
	s_nop 0
	v_addc_co_u32_e32 v43, vcc, 0, v33, vcc
	s_waitcnt vmcnt(14)
; __device__ __forceinline__ float sigmoidf_(float x) { return 1.0f / (1.0f + __expf(-x)); }
; __device__ __forceinline__ u32x4 pack8(const f32x4 v0, const f32x4 v1) { u32x4 w; w.x = pk2(v0[0], v0[1]); w.y = pk2(v0[2], v0[3]); w.z = pk2(v1[0], v1[1]); w.w = pk2(v1[2], v1[3]); return w; }
; __device__ __forceinline__ void unpack8(const u32x4 w, f32x4& v0, f32x4& v1) { v0 = (f32x4){bflo(w.x), bfhi(w.x), bflo(w.y), bfhi(w.y)}; v1 = (f32x4){bflo(w.z), bfhi(w.z), bflo(w.w), bfhi(w.w)}; }
;     __device__ __forceinline__ void operator()(const f32x4 (&acc)[2][2][4][2], const Unit& u, int wr, int wc, int fr, int fq) const {
;     ...
;         for (int ai = 0; ai < 2; ++ai)
; #pragma unroll
;             for (int m = 0; m < 4; ++m) {
;                 bf16_t* rowp = z + (size_t)(row0 + ai * 128 + m * 16) * DIN + col0;
; #pragma unroll
;                 for (int bj = 0; bj < 2; ++bj) {
;                     const u32x4 gw = *(const u32x4*)(rowp + (MODE == 0 ? O_GB : O_GA) + bj * 128);
;                     f32x4 g0, g1; unpack8(gw, g0, g1);
;                     f32x4 v0, v1;
; #pragma unroll
;                     for (int j = 0; j < 4; ++j) { v0[j] = sigmoidf_(g0[j]) * acc[ai][bj][m][0][j]; v1[j] = sigmoidf_(g1[j]) * acc[ai][bj][m][1][j]; }
;                     if (MODE == 1) { const u32x4 mw = *(const u32x4*)(rowp + bj * 128); f32x4 m0, m1; unpack8(mw, m0, m1); v0 += m0; v1 += m1; }
;                     *(u32x4*)(rowp + bj * 128) = pack8(v0, v1); }
	v_mov_b32_e32 v38, v204
	v_mov_b32_e32 v39, v205
	v_mov_b32_e32 v40, v206
	v_mov_b32_e32 v41, v207
	v_lshlrev_b32_e32 v34, 16, v38
	v_mul_f32_e32 v34, 0xbfb8aa3b, v34
	v_exp_f32_e32 v34, v34
	v_lshlrev_b32_e32 v36, 16, v39
	v_and_b32_e32 v37, 0xffff0000, v39
	v_and_b32_e32 v35, 0xffff0000, v38
	v_add_f32_e32 v34, 1.0, v34
	v_div_scale_f32 v39, s[6:7], v34, v34, 1.0
	v_rcp_f32_e32 v44, v39
	v_lshlrev_b32_e32 v38, 16, v40
	v_mul_f32_e32 v38, 0xbfb8aa3b, v38
	v_exp_f32_e32 v38, v38
	v_fma_f32 v46, -v39, v44, 1.0
	v_fmac_f32_e32 v44, v46, v44
	v_div_scale_f32 v46, vcc, 1.0, v34, 1.0
	v_mul_f32_e32 v47, v46, v44
	v_fma_f32 v48, -v39, v47, v46
	v_fmac_f32_e32 v47, v48, v44
	v_add_f32_e32 v38, 1.0, v38
	v_fma_f32 v39, -v39, v47, v46
	v_div_scale_f32 v46, s[6:7], v38, v38, 1.0
	v_rcp_f32_e32 v48, v46
	v_div_fmas_f32 v39, v39, v44, v47
	v_mul_f32_e32 v35, 0xbfb8aa3b, v35
	v_div_fixup_f32 v34, v39, v34, 1.0
	v_exp_f32_e32 v35, v35
	v_mul_f32_e32 v28, v28, v34
	v_fma_f32 v34, -v46, v48, 1.0
	v_fmac_f32_e32 v48, v34, v48
	v_div_scale_f32 v34, vcc, 1.0, v38, 1.0
	v_mul_f32_e32 v39, v34, v48
	v_fma_f32 v44, -v46, v39, v34
	v_add_f32_e32 v35, 1.0, v35
	v_fmac_f32_e32 v39, v44, v48
	v_div_scale_f32 v44, s[6:7], v35, v35, 1.0
	v_fma_f32 v34, -v46, v39, v34
	v_rcp_f32_e32 v46, v44
	v_and_b32_e32 v40, 0xffff0000, v40
	v_div_fmas_f32 v34, v34, v48, v39
	v_mul_f32_e32 v39, 0xbfb8aa3b, v40
	v_div_fixup_f32 v34, v34, v38, 1.0
	v_exp_f32_e32 v39, v39
	v_mul_f32_e32 v34, v24, v34
	v_fma_f32 v24, -v44, v46, 1.0
	v_fmac_f32_e32 v46, v24, v46
	v_div_scale_f32 v24, vcc, 1.0, v35, 1.0
	v_mul_f32_e32 v38, v24, v46
	v_fma_f32 v40, -v44, v38, v24
	v_add_f32_e32 v39, 1.0, v39
	v_fmac_f32_e32 v38, v40, v46
	v_div_scale_f32 v40, s[6:7], v39, v39, 1.0
	v_fma_f32 v24, -v44, v38, v24
	v_rcp_f32_e32 v44, v40
	v_div_fmas_f32 v24, v24, v46, v38
	v_mul_f32_e32 v36, 0xbfb8aa3b, v36
	v_div_fixup_f32 v24, v24, v35, 1.0
	v_exp_f32_e32 v36, v36
	v_mul_f32_e32 v24, v29, v24
	v_fma_f32 v29, -v40, v44, 1.0
	v_fmac_f32_e32 v44, v29, v44
	v_div_scale_f32 v29, vcc, 1.0, v39, 1.0
	v_mul_f32_e32 v35, v29, v44
	v_fma_f32 v38, -v40, v35, v29
	v_add_f32_e32 v36, 1.0, v36
	v_fmac_f32_e32 v35, v38, v44
	v_div_scale_f32 v38, s[6:7], v36, v36, 1.0
	v_fma_f32 v29, -v40, v35, v29
	v_rcp_f32_e32 v40, v38
	v_div_fmas_f32 v29, v29, v44, v35
	v_lshlrev_b32_e32 v45, 16, v41
	v_div_fixup_f32 v29, v29, v39, 1.0
	v_mul_f32_e32 v29, v25, v29
	v_fma_f32 v25, -v38, v40, 1.0
	v_mul_f32_e32 v39, 0xbfb8aa3b, v45
	v_fmac_f32_e32 v40, v25, v40
	v_div_scale_f32 v25, vcc, 1.0, v36, 1.0
	v_exp_f32_e32 v39, v39
	v_mul_f32_e32 v35, v25, v40
	v_fma_f32 v44, -v38, v35, v25
	v_fmac_f32_e32 v35, v44, v40
	v_fma_f32 v25, -v38, v35, v25
	v_add_f32_e32 v38, 1.0, v39
	v_div_scale_f32 v39, s[6:7], v38, v38, 1.0
	v_rcp_f32_e32 v44, v39
	v_div_fmas_f32 v25, v25, v40, v35
	v_div_fixup_f32 v25, v25, v36, 1.0
	v_mul_f32_e32 v36, 0xbfb8aa3b, v37
	v_exp_f32_e32 v36, v36
	v_mul_f32_e32 v25, v30, v25
	v_fma_f32 v30, -v39, v44, 1.0
	v_fmac_f32_e32 v44, v30, v44
	v_div_scale_f32 v30, vcc, 1.0, v38, 1.0
	v_mul_f32_e32 v35, v30, v44
	v_fma_f32 v37, -v39, v35, v30
	v_add_f32_e32 v36, 1.0, v36
	v_fmac_f32_e32 v35, v37, v44
	v_div_scale_f32 v37, s[6:7], v36, v36, 1.0
	v_fma_f32 v30, -v39, v35, v30
	v_rcp_f32_e32 v39, v37
	v_div_fmas_f32 v30, v30, v44, v35
	v_and_b32_e32 v41, 0xffff0000, v41
	v_div_fixup_f32 v30, v30, v38, 1.0
	v_mul_f32_e32 v30, v26, v30
	v_fma_f32 v26, -v37, v39, 1.0
	v_mul_f32_e32 v38, 0xbfb8aa3b, v41
	v_fmac_f32_e32 v39, v26, v39
	v_div_scale_f32 v26, vcc, 1.0, v36, 1.0
	v_exp_f32_e32 v38, v38
	v_mul_f32_e32 v35, v26, v39
	v_fma_f32 v40, -v37, v35, v26
	v_fmac_f32_e32 v35, v40, v39
	v_fma_f32 v26, -v37, v35, v26
	v_add_f32_e32 v37, 1.0, v38
	v_div_scale_f32 v38, s[6:7], v37, v37, 1.0
	v_rcp_f32_e32 v40, v38
	v_div_fmas_f32 v26, v26, v39, v35
	v_div_fixup_f32 v26, v26, v36, 1.0
	v_mul_f32_e32 v26, v31, v26
	v_fma_f32 v31, -v38, v40, 1.0
	v_fmac_f32_e32 v40, v31, v40
	v_div_scale_f32 v31, vcc, 1.0, v37, 1.0
	v_mul_f32_e32 v35, v31, v40
	v_fma_f32 v36, -v38, v35, v31
	v_fmac_f32_e32 v35, v36, v40
	v_fma_f32 v31, -v38, v35, v31
	v_div_fmas_f32 v31, v31, v40, v35
	v_div_fixup_f32 v31, v31, v37, 1.0
	v_mul_f32_e32 v27, v27, v31
	v_cvt_pk_bf16_f32 v24, v28, v24
	v_cvt_pk_bf16_f32 v25, v25, v26
	v_cvt_pk_bf16_f32 v26, v34, v29
	v_cvt_pk_bf16_f32 v27, v30, v27
	s_waitcnt vmcnt(12)
; __device__ __forceinline__ float sigmoidf_(float x) { return 1.0f / (1.0f + __expf(-x)); }
; __device__ __forceinline__ u32x4 pack8(const f32x4 v0, const f32x4 v1) { u32x4 w; w.x = pk2(v0[0], v0[1]); w.y = pk2(v0[2], v0[3]); w.z = pk2(v1[0], v1[1]); w.w = pk2(v1[2], v1[3]); return w; }
; __device__ __forceinline__ void unpack8(const u32x4 w, f32x4& v0, f32x4& v1) { v0 = (f32x4){bflo(w.x), bfhi(w.x), bflo(w.y), bfhi(w.y)}; v1 = (f32x4){bflo(w.z), bfhi(w.z), bflo(w.w), bfhi(w.w)}; }
;     __device__ __forceinline__ void operator()(const f32x4 (&acc)[2][2][4][2], const Unit& u, int wr, int wc, int fr, int fq) const {
;     ...
;         for (int ai = 0; ai < 2; ++ai)
; #pragma unroll
;             for (int m = 0; m < 4; ++m) {
;                 bf16_t* rowp = z + (size_t)(row0 + ai * 128 + m * 16) * DIN + col0;
; #pragma unroll
;                 for (int bj = 0; bj < 2; ++bj) {
;                     const u32x4 gw = *(const u32x4*)(rowp + (MODE == 0 ? O_GB : O_GA) + bj * 128);
;                     f32x4 g0, g1; unpack8(gw, g0, g1);
;                     f32x4 v0, v1;
; #pragma unroll
;                     for (int j = 0; j < 4; ++j) { v0[j] = sigmoidf_(g0[j]) * acc[ai][bj][m][0][j]; v1[j] = sigmoidf_(g1[j]) * acc[ai][bj][m][1][j]; }
;                     if (MODE == 1) { const u32x4 mw = *(const u32x4*)(rowp + bj * 128); f32x4 m0, m1; unpack8(mw, m0, m1); v0 += m0; v1 += m1; }
;                     *(u32x4*)(rowp + bj * 128) = pack8(v0, v1); }
	v_mov_b32_e32 v28, v208
	v_mov_b32_e32 v29, v209
	v_mov_b32_e32 v30, v210
	v_mov_b32_e32 v31, v211
	v_lshlrev_b32_e32 v35, 16, v31
	global_store_dwordx4 v[32:33], v[24:27], off
	v_and_b32_e32 v31, 0xffff0000, v31
	s_nop 0
	v_lshlrev_b32_e32 v24, 16, v28
	v_mul_f32_e32 v24, 0xbfb8aa3b, v24
	v_exp_f32_e32 v24, v24
	v_lshlrev_b32_e32 v26, 16, v29
	v_and_b32_e32 v27, 0xffff0000, v29
	v_and_b32_e32 v25, 0xffff0000, v28
	v_add_f32_e32 v24, 1.0, v24
	v_div_scale_f32 v29, s[6:7], v24, v24, 1.0
	v_rcp_f32_e32 v34, v29
	v_lshlrev_b32_e32 v28, 16, v30
	v_mul_f32_e32 v28, 0xbfb8aa3b, v28
	v_exp_f32_e32 v28, v28
	v_fma_f32 v36, -v29, v34, 1.0
	v_fmac_f32_e32 v34, v36, v34
	v_div_scale_f32 v36, vcc, 1.0, v24, 1.0
	v_mul_f32_e32 v37, v36, v34
	v_fma_f32 v38, -v29, v37, v36
	v_fmac_f32_e32 v37, v38, v34
	v_add_f32_e32 v28, 1.0, v28
	v_fma_f32 v29, -v29, v37, v36
	v_div_scale_f32 v36, s[6:7], v28, v28, 1.0
	v_rcp_f32_e32 v38, v36
	v_div_fmas_f32 v29, v29, v34, v37
	v_mul_f32_e32 v25, 0xbfb8aa3b, v25
	v_div_fixup_f32 v24, v29, v24, 1.0
	v_exp_f32_e32 v25, v25
	v_mul_f32_e32 v20, v20, v24
	v_fma_f32 v24, -v36, v38, 1.0
	v_fmac_f32_e32 v38, v24, v38
	v_div_scale_f32 v24, vcc, 1.0, v28, 1.0
	v_mul_f32_e32 v29, v24, v38
	v_fma_f32 v34, -v36, v29, v24
	v_add_f32_e32 v25, 1.0, v25
	v_fmac_f32_e32 v29, v34, v38
	v_div_scale_f32 v34, s[6:7], v25, v25, 1.0
	v_fma_f32 v24, -v36, v29, v24
	v_rcp_f32_e32 v36, v34
	v_and_b32_e32 v30, 0xffff0000, v30
	v_div_fmas_f32 v24, v24, v38, v29
	v_mul_f32_e32 v29, 0xbfb8aa3b, v30
	v_div_fixup_f32 v24, v24, v28, 1.0
	v_exp_f32_e32 v29, v29
	v_mul_f32_e32 v16, v16, v24
	v_fma_f32 v24, -v34, v36, 1.0
	v_fmac_f32_e32 v36, v24, v36
	v_div_scale_f32 v24, vcc, 1.0, v25, 1.0
	v_mul_f32_e32 v28, v24, v36
	v_fma_f32 v30, -v34, v28, v24
	v_add_f32_e32 v29, 1.0, v29
	v_fmac_f32_e32 v28, v30, v36
	v_div_scale_f32 v30, s[6:7], v29, v29, 1.0
	v_fma_f32 v24, -v34, v28, v24
	v_rcp_f32_e32 v34, v30
	v_div_fmas_f32 v24, v24, v36, v28
	v_mul_f32_e32 v26, 0xbfb8aa3b, v26
	v_div_fixup_f32 v24, v24, v25, 1.0
	v_exp_f32_e32 v26, v26
	v_mul_f32_e32 v21, v21, v24
	v_fma_f32 v24, -v30, v34, 1.0
	v_fmac_f32_e32 v34, v24, v34
	v_div_scale_f32 v24, vcc, 1.0, v29, 1.0
	v_mul_f32_e32 v25, v24, v34
	v_fma_f32 v28, -v30, v25, v24
	v_add_f32_e32 v26, 1.0, v26
	v_fmac_f32_e32 v25, v28, v34
	v_div_scale_f32 v28, s[6:7], v26, v26, 1.0
	v_fma_f32 v24, -v30, v25, v24
	v_rcp_f32_e32 v30, v28
	v_div_fmas_f32 v24, v24, v34, v25
	v_div_fixup_f32 v24, v24, v29, 1.0
	v_mul_f32_e32 v17, v17, v24
	v_fma_f32 v24, -v28, v30, 1.0
	v_mul_f32_e32 v29, 0xbfb8aa3b, v35
	v_fmac_f32_e32 v30, v24, v30
	v_div_scale_f32 v24, vcc, 1.0, v26, 1.0
	v_exp_f32_e32 v29, v29
	v_mul_f32_e32 v25, v24, v30
	v_fma_f32 v34, -v28, v25, v24
	v_fmac_f32_e32 v25, v34, v30
	v_fma_f32 v24, -v28, v25, v24
	v_add_f32_e32 v28, 1.0, v29
	v_div_scale_f32 v29, s[6:7], v28, v28, 1.0
	v_rcp_f32_e32 v34, v29
	v_div_fmas_f32 v24, v24, v30, v25
	v_div_fixup_f32 v24, v24, v26, 1.0
	v_mul_f32_e32 v26, 0xbfb8aa3b, v27
	v_exp_f32_e32 v26, v26
	v_mul_f32_e32 v22, v22, v24
	v_fma_f32 v24, -v29, v34, 1.0
	v_fmac_f32_e32 v34, v24, v34
	v_div_scale_f32 v24, vcc, 1.0, v28, 1.0
	v_mul_f32_e32 v25, v24, v34
	v_fma_f32 v27, -v29, v25, v24
	v_add_f32_e32 v26, 1.0, v26
	v_fmac_f32_e32 v25, v27, v34
	v_div_scale_f32 v27, s[6:7], v26, v26, 1.0
	v_fma_f32 v24, -v29, v25, v24
	v_rcp_f32_e32 v29, v27
	v_div_fmas_f32 v24, v24, v34, v25
	v_div_fixup_f32 v24, v24, v28, 1.0
	v_mul_f32_e32 v24, v18, v24
	v_fma_f32 v18, -v27, v29, 1.0
	v_mul_f32_e32 v28, 0xbfb8aa3b, v31
	v_fmac_f32_e32 v29, v18, v29
	v_div_scale_f32 v18, vcc, 1.0, v26, 1.0
	v_exp_f32_e32 v28, v28
	v_mul_f32_e32 v25, v18, v29
	v_fma_f32 v30, -v27, v25, v18
	v_fmac_f32_e32 v25, v30, v29
	v_fma_f32 v18, -v27, v25, v18
	v_add_f32_e32 v27, 1.0, v28
	v_div_scale_f32 v28, s[6:7], v27, v27, 1.0
	v_rcp_f32_e32 v30, v28
	v_div_fmas_f32 v18, v18, v29, v25
	v_div_fixup_f32 v18, v18, v26, 1.0
	v_mul_f32_e32 v23, v23, v18
	v_fma_f32 v18, -v28, v30, 1.0
	v_fmac_f32_e32 v30, v18, v30
	v_div_scale_f32 v18, vcc, 1.0, v27, 1.0
	v_mul_f32_e32 v25, v18, v30
	v_fma_f32 v26, -v28, v25, v18
	v_fmac_f32_e32 v25, v26, v30
	v_fma_f32 v18, -v28, v25, v18
	v_div_fmas_f32 v18, v18, v30, v25
	v_div_fixup_f32 v18, v18, v27, 1.0
	v_mul_f32_e32 v25, v19, v18
	v_cvt_pk_bf16_f32 v18, v20, v21
	v_cvt_pk_bf16_f32 v19, v22, v23
	v_cvt_pk_bf16_f32 v20, v16, v17
	v_add_u32_e32 v16, 0xb0, v160
	v_mad_i64_i32 v[16:17], s[6:7], v16, s61, v[146:147]
	v_lshl_add_u64 v[16:17], v[16:17], 0, v[148:149]
	v_add_co_u32_e32 v26, vcc, s62, v16
	v_cvt_pk_bf16_f32 v21, v24, v25
	global_store_dwordx4 v[32:33], v[18:21], off offset:256
	s_nop 0
	v_addc_co_u32_e32 v27, vcc, 0, v17, vcc
	s_waitcnt vmcnt(13)
; __device__ __forceinline__ float sigmoidf_(float x) { return 1.0f / (1.0f + __expf(-x)); }
; __device__ __forceinline__ u32x4 pack8(const f32x4 v0, const f32x4 v1) { u32x4 w; w.x = pk2(v0[0], v0[1]); w.y = pk2(v0[2], v0[3]); w.z = pk2(v1[0], v1[1]); w.w = pk2(v1[2], v1[3]); return w; }
; __device__ __forceinline__ void unpack8(const u32x4 w, f32x4& v0, f32x4& v1) { v0 = (f32x4){bflo(w.x), bfhi(w.x), bflo(w.y), bfhi(w.y)}; v1 = (f32x4){bflo(w.z), bfhi(w.z), bflo(w.w), bfhi(w.w)}; }
;     __device__ __forceinline__ void operator()(const f32x4 (&acc)[2][2][4][2], const Unit& u, int wr, int wc, int fr, int fq) const {
;     ...
;         for (int ai = 0; ai < 2; ++ai)
; #pragma unroll
;             for (int m = 0; m < 4; ++m) {
;                 bf16_t* rowp = z + (size_t)(row0 + ai * 128 + m * 16) * DIN + col0;
; #pragma unroll
;                 for (int bj = 0; bj < 2; ++bj) {
;                     const u32x4 gw = *(const u32x4*)(rowp + (MODE == 0 ? O_GB : O_GA) + bj * 128);
;                     f32x4 g0, g1; unpack8(gw, g0, g1);
;                     f32x4 v0, v1;
; #pragma unroll
;                     for (int j = 0; j < 4; ++j) { v0[j] = sigmoidf_(g0[j]) * acc[ai][bj][m][0][j]; v1[j] = sigmoidf_(g1[j]) * acc[ai][bj][m][1][j]; }
;                     if (MODE == 1) { const u32x4 mw = *(const u32x4*)(rowp + bj * 128); f32x4 m0, m1; unpack8(mw, m0, m1); v0 += m0; v1 += m1; }
;                     *(u32x4*)(rowp + bj * 128) = pack8(v0, v1); }
	v_mov_b32_e32 v22, v212
	v_mov_b32_e32 v23, v213
	v_mov_b32_e32 v24, v214
	v_mov_b32_e32 v25, v215
	v_lshlrev_b32_e32 v18, 16, v22
	v_mul_f32_e32 v18, 0xbfb8aa3b, v18
	v_exp_f32_e32 v18, v18
	v_lshlrev_b32_e32 v20, 16, v23
	v_and_b32_e32 v21, 0xffff0000, v23
	v_and_b32_e32 v19, 0xffff0000, v22
	v_add_f32_e32 v18, 1.0, v18
	v_div_scale_f32 v23, s[6:7], v18, v18, 1.0
	v_rcp_f32_e32 v28, v23
	v_lshlrev_b32_e32 v22, 16, v24
	v_mul_f32_e32 v22, 0xbfb8aa3b, v22
	v_exp_f32_e32 v22, v22
	v_fma_f32 v30, -v23, v28, 1.0
	v_fmac_f32_e32 v28, v30, v28
	v_div_scale_f32 v30, vcc, 1.0, v18, 1.0
	v_mul_f32_e32 v31, v30, v28
	v_fma_f32 v32, -v23, v31, v30
	v_fmac_f32_e32 v31, v32, v28
	v_add_f32_e32 v22, 1.0, v22
	v_fma_f32 v23, -v23, v31, v30
	v_div_scale_f32 v30, s[6:7], v22, v22, 1.0
	v_rcp_f32_e32 v32, v30
	v_div_fmas_f32 v23, v23, v28, v31
	v_mul_f32_e32 v19, 0xbfb8aa3b, v19
	v_div_fixup_f32 v18, v23, v18, 1.0
	v_exp_f32_e32 v19, v19
	v_mul_f32_e32 v12, v12, v18
	v_fma_f32 v18, -v30, v32, 1.0
	v_fmac_f32_e32 v32, v18, v32
	v_div_scale_f32 v18, vcc, 1.0, v22, 1.0
	v_mul_f32_e32 v23, v18, v32
	v_fma_f32 v28, -v30, v23, v18
	v_add_f32_e32 v19, 1.0, v19
	v_fmac_f32_e32 v23, v28, v32
	v_div_scale_f32 v28, s[6:7], v19, v19, 1.0
	v_fma_f32 v18, -v30, v23, v18
	v_rcp_f32_e32 v30, v28
	v_and_b32_e32 v24, 0xffff0000, v24
	v_div_fmas_f32 v18, v18, v32, v23
	v_mul_f32_e32 v23, 0xbfb8aa3b, v24
	v_div_fixup_f32 v18, v18, v22, 1.0
	v_exp_f32_e32 v23, v23
	v_mul_f32_e32 v18, v8, v18
	v_fma_f32 v8, -v28, v30, 1.0
	v_fmac_f32_e32 v30, v8, v30
	v_div_scale_f32 v8, vcc, 1.0, v19, 1.0
	v_mul_f32_e32 v22, v8, v30
	v_fma_f32 v24, -v28, v22, v8
	v_add_f32_e32 v23, 1.0, v23
	v_fmac_f32_e32 v22, v24, v30
	v_div_scale_f32 v24, s[6:7], v23, v23, 1.0
	v_fma_f32 v8, -v28, v22, v8
	v_rcp_f32_e32 v28, v24
	v_div_fmas_f32 v8, v8, v30, v22
	v_mul_f32_e32 v20, 0xbfb8aa3b, v20
	v_div_fixup_f32 v8, v8, v19, 1.0
	v_exp_f32_e32 v20, v20
	v_mul_f32_e32 v8, v13, v8
	v_fma_f32 v13, -v24, v28, 1.0
	v_fmac_f32_e32 v28, v13, v28
	v_div_scale_f32 v13, vcc, 1.0, v23, 1.0
	v_mul_f32_e32 v19, v13, v28
	v_fma_f32 v22, -v24, v19, v13
	v_add_f32_e32 v20, 1.0, v20
	v_fmac_f32_e32 v19, v22, v28
	v_div_scale_f32 v22, s[6:7], v20, v20, 1.0
	v_fma_f32 v13, -v24, v19, v13
	v_rcp_f32_e32 v24, v22
	v_div_fmas_f32 v13, v13, v28, v19
	v_lshlrev_b32_e32 v29, 16, v25
	v_div_fixup_f32 v13, v13, v23, 1.0
	v_mul_f32_e32 v13, v9, v13
	v_fma_f32 v9, -v22, v24, 1.0
	v_mul_f32_e32 v23, 0xbfb8aa3b, v29
	v_fmac_f32_e32 v24, v9, v24
	v_div_scale_f32 v9, vcc, 1.0, v20, 1.0
	v_exp_f32_e32 v23, v23
	v_mul_f32_e32 v19, v9, v24
	v_fma_f32 v28, -v22, v19, v9
	v_fmac_f32_e32 v19, v28, v24
	v_fma_f32 v9, -v22, v19, v9
	v_add_f32_e32 v22, 1.0, v23
	v_div_scale_f32 v23, s[6:7], v22, v22, 1.0
	v_rcp_f32_e32 v28, v23
	v_div_fmas_f32 v9, v9, v24, v19
	v_div_fixup_f32 v9, v9, v20, 1.0
	v_mul_f32_e32 v20, 0xbfb8aa3b, v21
	v_exp_f32_e32 v20, v20
	v_mul_f32_e32 v9, v14, v9
	v_fma_f32 v14, -v23, v28, 1.0
	v_fmac_f32_e32 v28, v14, v28
	v_div_scale_f32 v14, vcc, 1.0, v22, 1.0
	v_mul_f32_e32 v19, v14, v28
	v_fma_f32 v21, -v23, v19, v14
	v_add_f32_e32 v20, 1.0, v20
	v_fmac_f32_e32 v19, v21, v28
	v_div_scale_f32 v21, s[6:7], v20, v20, 1.0
	v_fma_f32 v14, -v23, v19, v14
	v_rcp_f32_e32 v23, v21
	v_div_fmas_f32 v14, v14, v28, v19
	v_and_b32_e32 v25, 0xffff0000, v25
	v_div_fixup_f32 v14, v14, v22, 1.0
	v_mul_f32_e32 v14, v10, v14
	v_fma_f32 v10, -v21, v23, 1.0
	v_mul_f32_e32 v22, 0xbfb8aa3b, v25
	v_fmac_f32_e32 v23, v10, v23
	v_div_scale_f32 v10, vcc, 1.0, v20, 1.0
	v_exp_f32_e32 v22, v22
	v_mul_f32_e32 v19, v10, v23
	v_fma_f32 v24, -v21, v19, v10
	v_fmac_f32_e32 v19, v24, v23
	v_fma_f32 v10, -v21, v19, v10
	v_add_f32_e32 v21, 1.0, v22
	v_div_scale_f32 v22, s[6:7], v21, v21, 1.0
	v_rcp_f32_e32 v24, v22
	v_div_fmas_f32 v10, v10, v23, v19
	v_div_fixup_f32 v10, v10, v20, 1.0
	v_mul_f32_e32 v10, v15, v10
	v_fma_f32 v15, -v22, v24, 1.0
	v_fmac_f32_e32 v24, v15, v24
	v_div_scale_f32 v15, vcc, 1.0, v21, 1.0
	v_mul_f32_e32 v19, v15, v24
	v_fma_f32 v20, -v22, v19, v15
	v_fmac_f32_e32 v19, v20, v24
	v_fma_f32 v15, -v22, v19, v15
	v_div_fmas_f32 v15, v15, v24, v19
	v_div_fixup_f32 v15, v15, v21, 1.0
	v_mul_f32_e32 v11, v11, v15
	v_cvt_pk_bf16_f32 v8, v12, v8
	v_cvt_pk_bf16_f32 v9, v9, v10
	v_cvt_pk_bf16_f32 v10, v18, v13
	v_cvt_pk_bf16_f32 v11, v14, v11
	s_waitcnt vmcnt(10)
; __device__ __forceinline__ float sigmoidf_(float x) { return 1.0f / (1.0f + __expf(-x)); }
; #define PG8_WAIT_V(n) asm volatile("s_waitcnt vmcnt(" #n ")" ::: "memory")
; #define PG8_BAR __builtin_amdgcn_s_barrier()
; __device__ __forceinline__ u32x4 pack8(const f32x4 v0, const f32x4 v1) { u32x4 w; w.x = pk2(v0[0], v0[1]); w.y = pk2(v0[2], v0[3]); w.z = pk2(v1[0], v1[1]); w.w = pk2(v1[2], v1[3]); return w; }
; __device__ __forceinline__ void unpack8(const u32x4 w, f32x4& v0, f32x4& v1) { v0 = (f32x4){bflo(w.x), bfhi(w.x), bflo(w.y), bfhi(w.y)}; v1 = (f32x4){bflo(w.z), bfhi(w.z), bflo(w.w), bfhi(w.w)}; }
;     ...
;         E(acc, cur, wr, wc, fr, fq);
;         if (!has_next) break;
; #pragma unroll
;         for (int a = 0; a < 2; ++a)
; #pragma unroll
;             for (int b = 0; b < 2; ++b)
; #pragma unroll
;                 for (int m = 0; m < 4; ++m)
; #pragma unroll
;                     for (int n = 0; n < 2; ++n) acc[a][b][m][n] = (f32x4){0.f, 0.f, 0.f, 0.f};
;         cur = nxt; cA = nA; cB = nB; ++ui;
;     }
;     PG8_WAIT_V(0);
;     if (wr == 0) PG8_BAR;
;     __device__ __forceinline__ void operator()(const f32x4 (&acc)[2][2][4][2], const Unit& u, int wr, int wc, int fr, int fq) const {
;     ...
;                 bf16_t* rowp = z + (size_t)(row0 + ai * 128 + m * 16) * DIN + col0;
; #pragma unroll
;                 for (int bj = 0; bj < 2; ++bj) {
;                     const u32x4 gw = *(const u32x4*)(rowp + (MODE == 0 ? O_GB : O_GA) + bj * 128);
;                     f32x4 g0, g1; unpack8(gw, g0, g1);
;                     f32x4 v0, v1;
; #pragma unroll
;                     for (int j = 0; j < 4; ++j) { v0[j] = sigmoidf_(g0[j]) * acc[ai][bj][m][0][j]; v1[j] = sigmoidf_(g1[j]) * acc[ai][bj][m][1][j]; }
;                     if (MODE == 1) { const u32x4 mw = *(const u32x4*)(rowp + bj * 128); f32x4 m0, m1; unpack8(mw, m0, m1); v0 += m0; v1 += m1; }
;                     *(u32x4*)(rowp + bj * 128) = pack8(v0, v1); }
	v_mov_b32_e32 v12, v216
	v_mov_b32_e32 v13, v217
	v_mov_b32_e32 v14, v218
	v_mov_b32_e32 v15, v219
	v_lshlrev_b32_e32 v19, 16, v15
	global_store_dwordx4 v[16:17], v[8:11], off
	v_and_b32_e32 v15, 0xffff0000, v15
	s_nop 0
	v_lshlrev_b32_e32 v8, 16, v12
	v_mul_f32_e32 v8, 0xbfb8aa3b, v8
	v_exp_f32_e32 v8, v8
	v_lshlrev_b32_e32 v10, 16, v13
	v_and_b32_e32 v11, 0xffff0000, v13
	v_and_b32_e32 v9, 0xffff0000, v12
	v_add_f32_e32 v8, 1.0, v8
	v_div_scale_f32 v13, s[6:7], v8, v8, 1.0
	v_rcp_f32_e32 v18, v13
	v_lshlrev_b32_e32 v12, 16, v14
	v_mul_f32_e32 v12, 0xbfb8aa3b, v12
	v_exp_f32_e32 v12, v12
	v_fma_f32 v20, -v13, v18, 1.0
	v_fmac_f32_e32 v18, v20, v18
	v_div_scale_f32 v20, vcc, 1.0, v8, 1.0
	v_mul_f32_e32 v21, v20, v18
	v_fma_f32 v22, -v13, v21, v20
	v_fmac_f32_e32 v21, v22, v18
	v_add_f32_e32 v12, 1.0, v12
	v_fma_f32 v13, -v13, v21, v20
	v_div_scale_f32 v20, s[6:7], v12, v12, 1.0
	v_rcp_f32_e32 v22, v20
	v_div_fmas_f32 v13, v13, v18, v21
	v_mul_f32_e32 v9, 0xbfb8aa3b, v9
	v_div_fixup_f32 v8, v13, v8, 1.0
	v_exp_f32_e32 v9, v9
	v_mul_f32_e32 v4, v4, v8
	v_fma_f32 v8, -v20, v22, 1.0
	v_fmac_f32_e32 v22, v8, v22
	v_div_scale_f32 v8, vcc, 1.0, v12, 1.0
	v_mul_f32_e32 v13, v8, v22
	v_fma_f32 v18, -v20, v13, v8
	v_add_f32_e32 v9, 1.0, v9
	v_fmac_f32_e32 v13, v18, v22
	v_div_scale_f32 v18, s[6:7], v9, v9, 1.0
	v_fma_f32 v8, -v20, v13, v8
	v_rcp_f32_e32 v20, v18
	v_and_b32_e32 v14, 0xffff0000, v14
	v_div_fmas_f32 v8, v8, v22, v13
	v_mul_f32_e32 v13, 0xbfb8aa3b, v14
	v_div_fixup_f32 v8, v8, v12, 1.0
	v_exp_f32_e32 v13, v13
	v_mul_f32_e32 v8, v0, v8
	v_fma_f32 v0, -v18, v20, 1.0
	v_fmac_f32_e32 v20, v0, v20
	v_div_scale_f32 v0, vcc, 1.0, v9, 1.0
	v_mul_f32_e32 v12, v0, v20
	v_fma_f32 v14, -v18, v12, v0
	v_add_f32_e32 v13, 1.0, v13
	v_fmac_f32_e32 v12, v14, v20
	v_div_scale_f32 v14, s[6:7], v13, v13, 1.0
	v_fma_f32 v0, -v18, v12, v0
	v_rcp_f32_e32 v18, v14
	v_div_fmas_f32 v0, v0, v20, v12
	v_mul_f32_e32 v10, 0xbfb8aa3b, v10
	v_div_fixup_f32 v0, v0, v9, 1.0
	v_exp_f32_e32 v10, v10
	v_mul_f32_e32 v0, v5, v0
	v_fma_f32 v5, -v14, v18, 1.0
	v_fmac_f32_e32 v18, v5, v18
	v_div_scale_f32 v5, vcc, 1.0, v13, 1.0
	v_mul_f32_e32 v9, v5, v18
	v_fma_f32 v12, -v14, v9, v5
	v_add_f32_e32 v10, 1.0, v10
	v_fmac_f32_e32 v9, v12, v18
	v_div_scale_f32 v12, s[6:7], v10, v10, 1.0
	v_fma_f32 v5, -v14, v9, v5
	v_rcp_f32_e32 v14, v12
	v_div_fmas_f32 v5, v5, v18, v9
	v_div_fixup_f32 v5, v5, v13, 1.0
	v_mul_f32_e32 v5, v1, v5
	v_fma_f32 v1, -v12, v14, 1.0
	v_mul_f32_e32 v13, 0xbfb8aa3b, v19
	v_fmac_f32_e32 v14, v1, v14
	v_div_scale_f32 v1, vcc, 1.0, v10, 1.0
	v_exp_f32_e32 v13, v13
	v_mul_f32_e32 v9, v1, v14
	v_fma_f32 v18, -v12, v9, v1
	v_fmac_f32_e32 v9, v18, v14
	v_fma_f32 v1, -v12, v9, v1
	v_add_f32_e32 v12, 1.0, v13
	v_div_scale_f32 v13, s[6:7], v12, v12, 1.0
	v_rcp_f32_e32 v18, v13
	v_div_fmas_f32 v1, v1, v14, v9
	v_div_fixup_f32 v1, v1, v10, 1.0
	v_mul_f32_e32 v10, 0xbfb8aa3b, v11
	v_exp_f32_e32 v10, v10
	v_mul_f32_e32 v1, v6, v1
	v_fma_f32 v6, -v13, v18, 1.0
	v_fmac_f32_e32 v18, v6, v18
	v_div_scale_f32 v6, vcc, 1.0, v12, 1.0
	v_mul_f32_e32 v9, v6, v18
	v_fma_f32 v11, -v13, v9, v6
	v_add_f32_e32 v10, 1.0, v10
	v_fmac_f32_e32 v9, v11, v18
	v_div_scale_f32 v11, s[6:7], v10, v10, 1.0
	v_fma_f32 v6, -v13, v9, v6
	v_rcp_f32_e32 v13, v11
	v_div_fmas_f32 v6, v6, v18, v9
	v_div_fixup_f32 v6, v6, v12, 1.0
	v_mul_f32_e32 v6, v2, v6
	v_fma_f32 v2, -v11, v13, 1.0
	v_mul_f32_e32 v12, 0xbfb8aa3b, v15
	v_fmac_f32_e32 v13, v2, v13
	v_div_scale_f32 v2, vcc, 1.0, v10, 1.0
	v_exp_f32_e32 v12, v12
	v_mul_f32_e32 v9, v2, v13
	v_fma_f32 v14, -v11, v9, v2
	v_fmac_f32_e32 v9, v14, v13
	v_fma_f32 v2, -v11, v9, v2
	v_add_f32_e32 v11, 1.0, v12
	v_div_scale_f32 v12, s[6:7], v11, v11, 1.0
	v_rcp_f32_e32 v14, v12
	v_div_fmas_f32 v2, v2, v13, v9
	v_div_fixup_f32 v2, v2, v10, 1.0
	v_mul_f32_e32 v2, v7, v2
	v_fma_f32 v7, -v12, v14, 1.0
	v_fmac_f32_e32 v14, v7, v14
	v_div_scale_f32 v7, vcc, 1.0, v11, 1.0
	v_mul_f32_e32 v9, v7, v14
	v_fma_f32 v10, -v12, v9, v7
	v_fmac_f32_e32 v9, v10, v14
	v_fma_f32 v7, -v12, v9, v7
	v_div_fmas_f32 v7, v7, v14, v9
	v_div_fixup_f32 v7, v7, v11, 1.0
	v_mul_f32_e32 v3, v3, v7
	s_and_b64 vcc, exec, s[10:11]
	s_mov_b32 s7, s28
	s_mov_b32 s6, s63
	v_cvt_pk_bf16_f32 v0, v4, v0
	v_cvt_pk_bf16_f32 v1, v1, v2
	v_cvt_pk_bf16_f32 v2, v8, v5
	v_cvt_pk_bf16_f32 v3, v6, v3
	global_store_dwordx4 v[16:17], v[0:3], off offset:256
	s_cbranch_vccz .LBB0_622
	s_waitcnt vmcnt(0)
	s_cmpk_gt_u32 s36, 0xff
	s_cbranch_scc1 .LBB0_631
	s_barrier

; #define PG8_STAGE(bufoff, gbase, voff) do { _Pragma("unroll") for (int _i = 0; _i < 2; ++_i) \
;         __builtin_amdgcn_global_load_lds((const unsigned*)((const char*)(gbase) + (voff)[_i]), (LAS unsigned*)(lds + (bufoff) + ldsw + _i * 8192), 16, 0, 0); } while (0)
; #define PG8_LDA(dst, b, h) do { _Pragma("unroll") for (int m = 0; m < 4; ++m) _Pragma("unroll") for (int k = 0; k < 2; ++k) dst[m][k] = *(const LAS bf16x8*)(lds + PG8_SA(b, h) + aoff + m * 2048 + k * 1024); } while (0)
; #define PG8_LDB(dst, b, h) do { _Pragma("unroll") for (int n = 0; n < 2; ++n) _Pragma("unroll") for (int k = 0; k < 2; ++k) dst[n][k] = *(const LAS bf16x8*)(lds + PG8_SB(b, h) + boff + n * 2048 + k * 1024); } while (0)
; #define PG8_MMA(ai, bj, At, Bt) do { __builtin_amdgcn_s_setprio(1); _Pragma("unroll") for (int m = 0; m < 4; ++m) _Pragma("unroll") for (int n = 0; n < 2; ++n) _Pragma("unroll") for (int k = 0; k < 2; ++k) \
;         acc[ai][bj][m][n] = __builtin_amdgcn_mfma_f32_16x16x32_bf16(Bt[n][k], At[m][k], acc[ai][bj][m][n], 0, 0, 0); __builtin_amdgcn_s_setprio(0); } while (0)
; #define PG8_WAIT_L(n) asm volatile("s_waitcnt lgkmcnt(" #n ")" ::: "memory")
; #define PG8_BAR __builtin_amdgcn_s_barrier()
; #define PG8_SCHED __builtin_amdgcn_sched_barrier(0)
;     ...
;             PG8_LDB(B0, 0, 0); PG8_SCHED; PG8_LDA(At, 0, 0); PG8_STAGE(PG8_SA(1, 1), a1 + hA, voffA);
;             PG8_WAIT_L(8); PG8_BAR; PG8_WAIT_L(0); PG8_MMA(0, 0, At, B0); PG8_BAR; PG8_SCHED;
;             PG8_LDB(B1, 0, 1); PG8_STAGE(PG8_SB(0, 0), b2, voffB);
;             PG8_BAR; PG8_WAIT_L(0); PG8_MMA(0, 1, At, B1); PG8_BAR;
;             PG8_LDA(At, 0, 1); PG8_STAGE(PG8_SA(0, 0), a2, voffA);
;             PG8_BAR; PG8_WAIT_L(0); PG8_MMA(1, 0, At, B0); PG8_BAR; PG8_SCHED;
.LBB0_1768:
	ds_read_b128 v[146:149], v157
	ds_read_b128 v[150:153], v157 offset:1024
	ds_read_b128 v[160:163], v157 offset:2048
	ds_read_b128 v[170:173], v157 offset:3072
	s_add_u32 s10, s12, 0x100
	s_addc_u32 s11, s13, 0
	s_cmp_eq_u32 s60, 4
	s_cselect_b32 s17, s29, s11
	s_cselect_b32 s16, s28, s10
	s_cselect_b32 s15, s27, s45
	s_cselect_b32 s14, s33, s44
	v_lshl_add_u64 v[164:165], s[12:13], 0, v[138:139]
	s_add_i32 m0, s37, 0xc000
	ds_read_b128 v[174:177], v158
	ds_read_b128 v[178:181], v158 offset:1024
	ds_read_b128 v[182:185], v158 offset:2048
	ds_read_b128 v[186:189], v158 offset:3072
	ds_read_b128 v[190:193], v158 offset:4096
	ds_read_b128 v[194:197], v158 offset:5120
	ds_read_b128 v[198:201], v158 offset:6144
	ds_read_b128 v[202:205], v158 offset:7168
	global_load_lds_dwordx4 v[164:165], off
	v_lshl_add_u64 v[164:165], s[12:13], 0, v[136:137]
	s_add_i32 m0, s37, 0xe000
	s_nop 0
	global_load_lds_dwordx4 v[164:165], off
	s_waitcnt lgkmcnt(8)
	s_barrier
	s_waitcnt lgkmcnt(0)
	s_setprio 1
	s_waitcnt lgkmcnt(0)
	v_mfma_f32_16x16x32_bf16 v[124:127], v[146:149], v[174:177], v[124:127]
	v_mfma_f32_16x16x32_bf16 v[120:123], v[160:163], v[174:177], v[120:123]
	v_mfma_f32_16x16x32_bf16 v[108:111], v[146:149], v[182:185], v[108:111]
	v_mfma_f32_16x16x32_bf16 v[104:107], v[160:163], v[182:185], v[104:107]
	v_mfma_f32_16x16x32_bf16 v[92:95], v[146:149], v[190:193], v[92:95]
	v_mfma_f32_16x16x32_bf16 v[88:91], v[160:163], v[190:193], v[88:91]
	v_mfma_f32_16x16x32_bf16 v[76:79], v[146:149], v[198:201], v[76:79]
	v_mfma_f32_16x16x32_bf16 v[72:75], v[160:163], v[198:201], v[72:75]
	v_mfma_f32_16x16x32_bf16 v[124:127], v[150:153], v[178:181], v[124:127]
	v_mfma_f32_16x16x32_bf16 v[120:123], v[170:173], v[178:181], v[120:123]
	v_mfma_f32_16x16x32_bf16 v[108:111], v[150:153], v[186:189], v[108:111]
	v_mfma_f32_16x16x32_bf16 v[104:107], v[170:173], v[186:189], v[104:107]
	v_mfma_f32_16x16x32_bf16 v[92:95], v[150:153], v[194:197], v[92:95]
	v_mfma_f32_16x16x32_bf16 v[88:91], v[170:173], v[194:197], v[88:91]
	v_mfma_f32_16x16x32_bf16 v[76:79], v[150:153], v[202:205], v[76:79]
	v_mfma_f32_16x16x32_bf16 v[72:75], v[170:173], v[202:205], v[72:75]
	s_setprio 0
	s_barrier
	s_add_i32 s12, s55, s35
	v_lshl_add_u64 v[164:165], s[14:15], 0, v[132:133]
	s_mov_b32 m0, s12
	ds_read_b128 v[206:209], v159
	ds_read_b128 v[210:213], v159 offset:1024
	ds_read_b128 v[214:217], v159 offset:2048
	ds_read_b128 v[218:221], v159 offset:3072
	global_load_lds_dwordx4 v[164:165], off
	v_lshl_add_u64 v[222:223], s[14:15], 0, v[128:129]
	s_add_i32 m0, s12, 0x2000
	s_nop 0
	global_load_lds_dwordx4 v[222:223], off
	s_barrier
	s_waitcnt lgkmcnt(0)
	s_setprio 1
	s_waitcnt lgkmcnt(0)
	v_mfma_f32_16x16x32_bf16 v[116:119], v[206:209], v[174:177], v[116:119]
	v_mfma_f32_16x16x32_bf16 v[112:115], v[214:217], v[174:177], v[112:115]
	v_mfma_f32_16x16x32_bf16 v[100:103], v[206:209], v[182:185], v[100:103]
	v_mfma_f32_16x16x32_bf16 v[96:99], v[214:217], v[182:185], v[96:99]
	v_mfma_f32_16x16x32_bf16 v[84:87], v[206:209], v[190:193], v[84:87]
	v_mfma_f32_16x16x32_bf16 v[80:83], v[214:217], v[190:193], v[80:83]
	v_mfma_f32_16x16x32_bf16 v[68:71], v[206:209], v[198:201], v[68:71]
	v_mfma_f32_16x16x32_bf16 v[64:67], v[214:217], v[198:201], v[64:67]
	v_mfma_f32_16x16x32_bf16 v[116:119], v[210:213], v[178:181], v[116:119]
	v_mfma_f32_16x16x32_bf16 v[112:115], v[218:221], v[178:181], v[112:115]
	v_mfma_f32_16x16x32_bf16 v[100:103], v[210:213], v[186:189], v[100:103]
	v_mfma_f32_16x16x32_bf16 v[96:99], v[218:221], v[186:189], v[96:99]
	v_mfma_f32_16x16x32_bf16 v[84:87], v[210:213], v[194:197], v[84:87]
	v_mfma_f32_16x16x32_bf16 v[80:83], v[218:221], v[194:197], v[80:83]
	v_mfma_f32_16x16x32_bf16 v[68:71], v[210:213], v[202:205], v[68:71]
	v_mfma_f32_16x16x32_bf16 v[64:67], v[218:221], v[202:205], v[64:67]
	s_setprio 0
	s_mov_b32 m0, s37
	v_lshl_add_u64 v[224:225], s[16:17], 0, v[134:135]
	s_barrier
	ds_read_b128 v[174:177], v158 offset:16384
	ds_read_b128 v[178:181], v158 offset:17408
	ds_read_b128 v[182:185], v158 offset:18432
	ds_read_b128 v[186:189], v158 offset:19456
	ds_read_b128 v[190:193], v158 offset:20480
	ds_read_b128 v[194:197], v158 offset:21504
	ds_read_b128 v[198:201], v158 offset:22528
	ds_read_b128 v[202:205], v158 offset:23552
	global_load_lds_dwordx4 v[224:225], off
	v_lshl_add_u64 v[226:227], s[16:17], 0, v[130:131]
	s_mov_b32 m0, s40
	s_nop 0
	global_load_lds_dwordx4 v[226:227], off
	s_barrier
	s_waitcnt lgkmcnt(0)
	s_setprio 1
	s_waitcnt lgkmcnt(0)
	v_mfma_f32_16x16x32_bf16 v[60:63], v[146:149], v[174:177], v[60:63]
	v_mfma_f32_16x16x32_bf16 v[56:59], v[160:163], v[174:177], v[56:59]
	v_mfma_f32_16x16x32_bf16 v[44:47], v[146:149], v[182:185], v[44:47]
	v_mfma_f32_16x16x32_bf16 v[40:43], v[160:163], v[182:185], v[40:43]
	v_mfma_f32_16x16x32_bf16 v[28:31], v[146:149], v[190:193], v[28:31]
	v_mfma_f32_16x16x32_bf16 v[24:27], v[160:163], v[190:193], v[24:27]
	v_mfma_f32_16x16x32_bf16 v[12:15], v[146:149], v[198:201], v[12:15]
	v_mfma_f32_16x16x32_bf16 v[8:11], v[160:163], v[198:201], v[8:11]
	v_mfma_f32_16x16x32_bf16 v[60:63], v[150:153], v[178:181], v[60:63]
	v_mfma_f32_16x16x32_bf16 v[56:59], v[170:173], v[178:181], v[56:59]
	v_mfma_f32_16x16x32_bf16 v[44:47], v[150:153], v[186:189], v[44:47]
	v_mfma_f32_16x16x32_bf16 v[40:43], v[170:173], v[186:189], v[40:43]
	v_mfma_f32_16x16x32_bf16 v[28:31], v[150:153], v[194:197], v[28:31]
	v_mfma_f32_16x16x32_bf16 v[24:27], v[170:173], v[194:197], v[24:27]
	v_mfma_f32_16x16x32_bf16 v[12:15], v[150:153], v[202:205], v[12:15]
	v_mfma_f32_16x16x32_bf16 v[8:11], v[170:173], v[202:205], v[8:11]
	s_setprio 0
	s_barrier
; #define PG8_STAGE(bufoff, gbase, voff) do { _Pragma("unroll") for (int _i = 0; _i < 2; ++_i) \
;         __builtin_amdgcn_global_load_lds((const unsigned*)((const char*)(gbase) + (voff)[_i]), (LAS unsigned*)(lds + (bufoff) + ldsw + _i * 8192), 16, 0, 0); } while (0)
; #define PG8_LDA(dst, b, h) do { _Pragma("unroll") for (int m = 0; m < 4; ++m) _Pragma("unroll") for (int k = 0; k < 2; ++k) dst[m][k] = *(const LAS bf16x8*)(lds + PG8_SA(b, h) + aoff + m * 2048 + k * 1024); } while (0)
; #define PG8_LDB(dst, b, h) do { _Pragma("unroll") for (int n = 0; n < 2; ++n) _Pragma("unroll") for (int k = 0; k < 2; ++k) dst[n][k] = *(const LAS bf16x8*)(lds + PG8_SB(b, h) + boff + n * 2048 + k * 1024); } while (0)
; #define PG8_MMA(ai, bj, At, Bt) do { __builtin_amdgcn_s_setprio(1); _Pragma("unroll") for (int m = 0; m < 4; ++m) _Pragma("unroll") for (int n = 0; n < 2; ++n) _Pragma("unroll") for (int k = 0; k < 2; ++k) \
;         acc[ai][bj][m][n] = __builtin_amdgcn_mfma_f32_16x16x32_bf16(Bt[n][k], At[m][k], acc[ai][bj][m][n], 0, 0, 0); __builtin_amdgcn_s_setprio(0); } while (0)
; #define PG8_WAIT_V(n) asm volatile("s_waitcnt vmcnt(" #n ")" ::: "memory")
; #define PG8_WAIT_L(n) asm volatile("s_waitcnt lgkmcnt(" #n ")" ::: "memory")
; #define PG8_BAR __builtin_amdgcn_s_barrier()
; #define PG8_SCHED __builtin_amdgcn_sched_barrier(0)
;     ...
;             PG8_STAGE(PG8_SB(0, 1), b2 + hB, voffB);
;             PG8_WAIT_V(6); PG8_BAR; PG8_MMA(1, 1, At, B1); PG8_BAR;
;             PG8_LDB(B0, 1, 0); PG8_SCHED; PG8_LDA(At, 1, 0); PG8_STAGE(PG8_SA(0, 1), a2 + hA, voffA);
;             PG8_WAIT_L(8); PG8_BAR; PG8_WAIT_L(0); PG8_MMA(0, 0, At, B0); PG8_BAR; PG8_SCHED;
;             PG8_LDB(B1, 1, 1); PG8_STAGE(PG8_SB(1, 0), b3, voffB);
;             PG8_BAR; PG8_WAIT_L(0); PG8_MMA(0, 1, At, B1); PG8_BAR;
;             PG8_LDA(At, 1, 1); PG8_STAGE(PG8_SA(1, 0), a3, voffA);
	s_add_u32 s12, s14, 0x20000
	s_addc_u32 s13, s15, 0
	s_add_i32 s61, s56, s35
	v_lshl_add_u64 v[146:147], s[12:13], 0, v[132:133]
	s_mov_b32 m0, s61
	s_nop 0
	global_load_lds_dwordx4 v[146:147], off
	v_lshl_add_u64 v[146:147], s[12:13], 0, v[128:129]
	s_add_i32 m0, s61, 0x2000
	s_nop 0
	global_load_lds_dwordx4 v[146:147], off
	s_waitcnt vmcnt(6)
	s_barrier
	s_setprio 1
	v_mfma_f32_16x16x32_bf16 v[52:55], v[206:209], v[174:177], v[52:55]
	v_mfma_f32_16x16x32_bf16 v[48:51], v[214:217], v[174:177], v[48:51]
	v_mfma_f32_16x16x32_bf16 v[36:39], v[206:209], v[182:185], v[36:39]
	v_mfma_f32_16x16x32_bf16 v[32:35], v[214:217], v[182:185], v[32:35]
	v_mfma_f32_16x16x32_bf16 v[20:23], v[206:209], v[190:193], v[20:23]
	v_mfma_f32_16x16x32_bf16 v[16:19], v[214:217], v[190:193], v[16:19]
	v_mfma_f32_16x16x32_bf16 v[4:7], v[206:209], v[198:201], v[4:7]
	v_mfma_f32_16x16x32_bf16 v[0:3], v[214:217], v[198:201], v[0:3]
	v_mfma_f32_16x16x32_bf16 v[52:55], v[210:213], v[178:181], v[52:55]
	v_mfma_f32_16x16x32_bf16 v[48:51], v[218:221], v[178:181], v[48:51]
	v_mfma_f32_16x16x32_bf16 v[36:39], v[210:213], v[186:189], v[36:39]
	v_mfma_f32_16x16x32_bf16 v[32:35], v[218:221], v[186:189], v[32:35]
	v_mfma_f32_16x16x32_bf16 v[20:23], v[210:213], v[194:197], v[20:23]
	v_mfma_f32_16x16x32_bf16 v[16:19], v[218:221], v[194:197], v[16:19]
	v_mfma_f32_16x16x32_bf16 v[4:7], v[210:213], v[202:205], v[4:7]
	v_mfma_f32_16x16x32_bf16 v[0:3], v[218:221], v[202:205], v[0:3]
	s_setprio 0
	s_add_i32 s61, 0, 0x18000
	v_add_u32_e32 v169, s61, v155
	s_barrier
	ds_read_b128 v[146:149], v169
	ds_read_b128 v[150:153], v169 offset:1024
	ds_read_b128 v[160:163], v169 offset:2048
	ds_read_b128 v[170:173], v169 offset:3072
	s_add_u32 s12, s16, 0x110000
	s_addc_u32 s13, s17, 0
	s_mov_b32 m0, s41
	v_lshl_add_u64 v[206:207], s[12:13], 0, v[134:135]
	ds_read_b128 v[174:177], v158 offset:32768
	ds_read_b128 v[178:181], v158 offset:33792
	ds_read_b128 v[182:185], v158 offset:34816
	ds_read_b128 v[186:189], v158 offset:35840
	ds_read_b128 v[190:193], v158 offset:36864
	ds_read_b128 v[194:197], v158 offset:37888
	ds_read_b128 v[198:201], v158 offset:38912
	ds_read_b128 v[202:205], v158 offset:39936
	global_load_lds_dwordx4 v[206:207], off
	v_lshl_add_u64 v[206:207], s[12:13], 0, v[130:131]
	s_mov_b32 m0, s42
	s_nop 0
	global_load_lds_dwordx4 v[206:207], off
	s_waitcnt lgkmcnt(8)
	s_barrier
	s_waitcnt lgkmcnt(0)
	s_setprio 1
	s_waitcnt lgkmcnt(0)
	v_mfma_f32_16x16x32_bf16 v[124:127], v[146:149], v[174:177], v[124:127]
	v_mfma_f32_16x16x32_bf16 v[120:123], v[160:163], v[174:177], v[120:123]
	v_mfma_f32_16x16x32_bf16 v[108:111], v[146:149], v[182:185], v[108:111]
	v_mfma_f32_16x16x32_bf16 v[104:107], v[160:163], v[182:185], v[104:107]
	v_mfma_f32_16x16x32_bf16 v[92:95], v[146:149], v[190:193], v[92:95]
	v_mfma_f32_16x16x32_bf16 v[88:91], v[160:163], v[190:193], v[88:91]
	v_mfma_f32_16x16x32_bf16 v[76:79], v[146:149], v[198:201], v[76:79]
	v_mfma_f32_16x16x32_bf16 v[72:75], v[160:163], v[198:201], v[72:75]
	v_mfma_f32_16x16x32_bf16 v[124:127], v[150:153], v[178:181], v[124:127]
	v_mfma_f32_16x16x32_bf16 v[120:123], v[170:173], v[178:181], v[120:123]
	v_mfma_f32_16x16x32_bf16 v[108:111], v[150:153], v[186:189], v[108:111]
	v_mfma_f32_16x16x32_bf16 v[104:107], v[170:173], v[186:189], v[104:107]
	v_mfma_f32_16x16x32_bf16 v[92:95], v[150:153], v[194:197], v[92:95]
	v_mfma_f32_16x16x32_bf16 v[88:91], v[170:173], v[194:197], v[88:91]
	v_mfma_f32_16x16x32_bf16 v[76:79], v[150:153], v[202:205], v[76:79]
	v_mfma_f32_16x16x32_bf16 v[72:75], v[170:173], v[202:205], v[72:75]
	s_setprio 0
	s_barrier
	s_add_i32 s16, 0, 0x1c000
	s_add_i32 s12, s61, s35
	v_add_u32_e32 v169, s16, v155
	v_lshl_add_u64 v[164:165], v[164:165], 0, s[24:25]
	s_mov_b32 m0, s12
	ds_read_b128 v[206:209], v169
	ds_read_b128 v[210:213], v169 offset:1024
	ds_read_b128 v[214:217], v169 offset:2048
	ds_read_b128 v[218:221], v169 offset:3072
	global_load_lds_dwordx4 v[164:165], off
	v_lshl_add_u64 v[164:165], v[222:223], 0, s[24:25]
	s_add_i32 m0, s12, 0x2000
	s_nop 0
	global_load_lds_dwordx4 v[164:165], off
	s_barrier
	s_waitcnt lgkmcnt(0)
	s_setprio 1
	s_waitcnt lgkmcnt(0)
	v_mfma_f32_16x16x32_bf16 v[116:119], v[206:209], v[174:177], v[116:119]
	v_mfma_f32_16x16x32_bf16 v[112:115], v[214:217], v[174:177], v[112:115]
	v_mfma_f32_16x16x32_bf16 v[100:103], v[206:209], v[182:185], v[100:103]
	v_mfma_f32_16x16x32_bf16 v[96:99], v[214:217], v[182:185], v[96:99]
	v_mfma_f32_16x16x32_bf16 v[84:87], v[206:209], v[190:193], v[84:87]
	v_mfma_f32_16x16x32_bf16 v[80:83], v[214:217], v[190:193], v[80:83]
	v_mfma_f32_16x16x32_bf16 v[68:71], v[206:209], v[198:201], v[68:71]
	v_mfma_f32_16x16x32_bf16 v[64:67], v[214:217], v[198:201], v[64:67]
	v_mfma_f32_16x16x32_bf16 v[116:119], v[210:213], v[178:181], v[116:119]
	v_mfma_f32_16x16x32_bf16 v[112:115], v[218:221], v[178:181], v[112:115]
	v_mfma_f32_16x16x32_bf16 v[100:103], v[210:213], v[186:189], v[100:103]
	v_mfma_f32_16x16x32_bf16 v[96:99], v[218:221], v[186:189], v[96:99]
	v_mfma_f32_16x16x32_bf16 v[84:87], v[210:213], v[194:197], v[84:87]
	v_mfma_f32_16x16x32_bf16 v[80:83], v[218:221], v[194:197], v[80:83]
	v_mfma_f32_16x16x32_bf16 v[68:71], v[210:213], v[202:205], v[68:71]
	v_mfma_f32_16x16x32_bf16 v[64:67], v[218:221], v[202:205], v[64:67]
	s_setprio 0
	s_mov_b32 m0, s52
	v_lshl_add_u64 v[164:165], v[224:225], 0, s[24:25]
	s_barrier
	ds_read_b128 v[174:177], v158 offset:49152
	ds_read_b128 v[178:181], v158 offset:50176
	ds_read_b128 v[182:185], v158 offset:51200
	ds_read_b128 v[186:189], v158 offset:52224
	ds_read_b128 v[190:193], v158 offset:53248
	ds_read_b128 v[194:197], v158 offset:54272
	ds_read_b128 v[198:201], v158 offset:55296
	ds_read_b128 v[202:205], v158 offset:56320
	global_load_lds_dwordx4 v[164:165], off
	v_lshl_add_u64 v[164:165], v[226:227], 0, s[24:25]
	s_mov_b32 m0, s53
	s_nop 0
	global_load_lds_dwordx4 v[164:165], off
	s_barrier
; __device__ __forceinline__ float sigmoidf_(float x) { return 1.0f / (1.0f + __expf(-x)); }
; #define PG8_STAGE(bufoff, gbase, voff) do { _Pragma("unroll") for (int _i = 0; _i < 2; ++_i) \
;         __builtin_amdgcn_global_load_lds((const unsigned*)((const char*)(gbase) + (voff)[_i]), (LAS unsigned*)(lds + (bufoff) + ldsw + _i * 8192), 16, 0, 0); } while (0)
; #define PG8_MMA(ai, bj, At, Bt) do { __builtin_amdgcn_s_setprio(1); _Pragma("unroll") for (int m = 0; m < 4; ++m) _Pragma("unroll") for (int n = 0; n < 2; ++n) _Pragma("unroll") for (int k = 0; k < 2; ++k) \
;         acc[ai][bj][m][n] = __builtin_amdgcn_mfma_f32_16x16x32_bf16(Bt[n][k], At[m][k], acc[ai][bj][m][n], 0, 0, 0); __builtin_amdgcn_s_setprio(0); } while (0)
; #define PG8_WAIT_V(n) asm volatile("s_waitcnt vmcnt(" #n ")" ::: "memory")
; #define PG8_WAIT_L(n) asm volatile("s_waitcnt lgkmcnt(" #n ")" ::: "memory")
; #define PG8_BAR __builtin_amdgcn_s_barrier()
; #define PG8_SCHED __builtin_amdgcn_sched_barrier(0)
; __device__ __forceinline__ void unpack8(const u32x4 w, f32x4& v0, f32x4& v1) { v0 = (f32x4){bflo(w.x), bfhi(w.x), bflo(w.y), bfhi(w.y)}; v1 = (f32x4){bflo(w.z), bfhi(w.z), bflo(w.w), bfhi(w.w)}; }
;     ...
;             PG8_BAR; PG8_WAIT_L(0); PG8_MMA(1, 0, At, B0); PG8_BAR; PG8_SCHED;
;             PG8_STAGE(PG8_SB(1, 1), b3 + hB, voffB);
;             PG8_WAIT_V(6); PG8_BAR; PG8_MMA(1, 1, At, B1); PG8_BAR;
;         }
;         E(acc, cur, wr, wc, fr, fq);
;     __device__ __forceinline__ void operator()(const f32x4 (&acc)[2][2][4][2], const Unit& u, int wr, int wc, int fr, int fq) const {
;         const int row0 = u.pm * 256 + wr * 64 + fr, col0 = u.pn * 256 + wc * 32 + 8 * fq;
; #pragma unroll
;         for (int ai = 0; ai < 2; ++ai)
; #pragma unroll
;             for (int m = 0; m < 4; ++m) {
;                 bf16_t* rowp = z + (size_t)(row0 + ai * 128 + m * 16) * DIN + col0;
; #pragma unroll
;                 for (int bj = 0; bj < 2; ++bj) {
;                     const u32x4 gw = *(const u32x4*)(rowp + (MODE == 0 ? O_GB : O_GA) + bj * 128);
;                     f32x4 g0, g1; unpack8(gw, g0, g1);
;                     f32x4 v0, v1;
; #pragma unroll
;                     for (int j = 0; j < 4; ++j) { v0[j] = sigmoidf_(g0[j]) * acc[ai][bj][m][0][j]; v1[j] = sigmoidf_(g1[j]) * acc[ai][bj][m][1][j]; }
	s_waitcnt lgkmcnt(0)
	s_setprio 1
	s_waitcnt lgkmcnt(0)
	v_mfma_f32_16x16x32_bf16 v[60:63], v[146:149], v[174:177], v[60:63]
	v_mfma_f32_16x16x32_bf16 v[56:59], v[160:163], v[174:177], v[56:59]
	v_mfma_f32_16x16x32_bf16 v[44:47], v[146:149], v[182:185], v[44:47]
	v_mfma_f32_16x16x32_bf16 v[40:43], v[160:163], v[182:185], v[40:43]
	v_mfma_f32_16x16x32_bf16 v[28:31], v[146:149], v[190:193], v[28:31]
	v_mfma_f32_16x16x32_bf16 v[24:27], v[160:163], v[190:193], v[24:27]
	v_mfma_f32_16x16x32_bf16 v[12:15], v[146:149], v[198:201], v[12:15]
	v_mfma_f32_16x16x32_bf16 v[8:11], v[160:163], v[198:201], v[8:11]
	v_mfma_f32_16x16x32_bf16 v[60:63], v[150:153], v[178:181], v[60:63]
	v_mfma_f32_16x16x32_bf16 v[56:59], v[170:173], v[178:181], v[56:59]
	v_mfma_f32_16x16x32_bf16 v[44:47], v[150:153], v[186:189], v[44:47]
	v_mfma_f32_16x16x32_bf16 v[40:43], v[170:173], v[186:189], v[40:43]
	v_mfma_f32_16x16x32_bf16 v[28:31], v[150:153], v[194:197], v[28:31]
	v_mfma_f32_16x16x32_bf16 v[24:27], v[170:173], v[194:197], v[24:27]
	v_mfma_f32_16x16x32_bf16 v[12:15], v[150:153], v[202:205], v[12:15]
	v_mfma_f32_16x16x32_bf16 v[8:11], v[170:173], v[202:205], v[8:11]
	s_setprio 0
	s_barrier
	s_add_u32 s12, s14, 0x20080
	s_addc_u32 s13, s15, 0
	s_add_i32 s14, s16, s35
	v_lshl_add_u64 v[146:147], s[12:13], 0, v[132:133]
	s_mov_b32 m0, s14
	s_nop 0
	global_load_lds_dwordx4 v[146:147], off
	v_lshl_add_u64 v[146:147], s[12:13], 0, v[128:129]
	s_add_i32 m0, s14, 0x2000
	s_nop 0
	global_load_lds_dwordx4 v[146:147], off
	s_waitcnt vmcnt(6)
	s_barrier
	s_setprio 1
	v_mfma_f32_16x16x32_bf16 v[52:55], v[206:209], v[174:177], v[52:55]
	v_mfma_f32_16x16x32_bf16 v[48:51], v[214:217], v[174:177], v[48:51]
	v_mfma_f32_16x16x32_bf16 v[36:39], v[206:209], v[182:185], v[36:39]
	v_mfma_f32_16x16x32_bf16 v[32:35], v[214:217], v[182:185], v[32:35]
	v_mfma_f32_16x16x32_bf16 v[20:23], v[206:209], v[190:193], v[20:23]
	v_mfma_f32_16x16x32_bf16 v[16:19], v[214:217], v[190:193], v[16:19]
	v_mfma_f32_16x16x32_bf16 v[4:7], v[206:209], v[198:201], v[4:7]
	v_mfma_f32_16x16x32_bf16 v[0:3], v[214:217], v[198:201], v[0:3]
	v_mfma_f32_16x16x32_bf16 v[52:55], v[210:213], v[178:181], v[52:55]
	v_mfma_f32_16x16x32_bf16 v[48:51], v[218:221], v[178:181], v[48:51]
	v_mfma_f32_16x16x32_bf16 v[36:39], v[210:213], v[186:189], v[36:39]
	v_mfma_f32_16x16x32_bf16 v[32:35], v[218:221], v[186:189], v[32:35]
	v_mfma_f32_16x16x32_bf16 v[20:23], v[210:213], v[194:197], v[20:23]
	v_mfma_f32_16x16x32_bf16 v[16:19], v[218:221], v[194:197], v[16:19]
	v_mfma_f32_16x16x32_bf16 v[4:7], v[210:213], v[202:205], v[4:7]
	v_mfma_f32_16x16x32_bf16 v[0:3], v[218:221], v[202:205], v[0:3]
	s_setprio 0
	s_add_i32 s60, s60, 2
	s_add_u32 s44, s44, 0x100
	s_addc_u32 s45, s45, 0
	s_cmp_gt_u32 s60, 5
	s_mov_b64 s[12:13], s[10:11]
	s_barrier
	s_cbranch_scc0 .LBB0_1768
	v_lshl_or_b32 v148, s7, 8, v156
	v_lshl_add_u32 v160, s6, 8, v154
	v_ashrrev_i32_e32 v149, 31, v148
	v_mov_b64_e32 v[146:147], s[22:23]
	v_mad_i64_i32 v[150:151], s[6:7], v160, s57, v[146:147]
	v_lshlrev_b64 v[148:149], 1, v[148:149]
	v_lshl_add_u64 v[150:151], v[150:151], 0, v[148:149]
	v_add_co_u32_e32 v152, vcc, 0x1000, v150
	s_nop 1
	v_addc_co_u32_e32 v153, vcc, 0, v151, vcc
	v_subrev_u32_e32 v197, s22, v150
	v_add_u32_e32 v198, 0x1a00, v197
	global_load_dwordx4 v[200:203], v198, s[22:23]
	v_add_u32_e32 v198, 0x1b00, v197
	global_load_dwordx4 v[204:207], v198, s[22:23]
	v_add_u32_e32 v198, 0x23a00, v197
	global_load_dwordx4 v[208:211], v198, s[22:23]
	v_add_u32_e32 v198, 0x23b00, v197
	global_load_dwordx4 v[212:215], v198, s[22:23]
	v_add_u32_e32 v198, 0x45a00, v197
	global_load_dwordx4 v[216:219], v198, s[22:23]
	v_add_u32_e32 v198, 0x45b00, v197
	global_load_dwordx4 v[232:235], v198, s[22:23]
	v_add_u32_e32 v198, 0x67a00, v197
	global_load_dwordx4 v[236:239], v198, s[22:23]
	v_add_u32_e32 v198, 0x67b00, v197
	global_load_dwordx4 v[240:243], v198, s[22:23]
	v_add_u32_e32 v198, 0x111a00, v197
	global_load_dwordx4 v[244:247], v198, s[22:23]
	v_add_u32_e32 v198, 0x111b00, v197
	global_load_dwordx4 v[248:251], v198, s[22:23]
	v_add_u32_e32 v198, 0x133a00, v197
	global_load_dwordx4 v[252:255], v198, s[22:23]
	s_waitcnt vmcnt(10)
	v_mov_b32_e32 v162, v200
	v_mov_b32_e32 v163, v201
	v_mov_b32_e32 v164, v202
	v_mov_b32_e32 v165, v203
	v_add_u32_e32 v198, 0x133b00, v197
	global_load_dwordx4 v[200:203], v198, s[22:23]
	v_lshlrev_b32_e32 v161, 16, v162
	v_lshlrev_b32_e32 v170, 16, v164
	v_mul_f32_e32 v161, 0xbfb8aa3b, v161
	v_and_b32_e32 v162, 0xffff0000, v162
	v_mul_f32_e32 v170, 0xbfb8aa3b, v170
	v_exp_f32_e32 v161, v161
	v_and_b32_e32 v164, 0xffff0000, v164
	v_mul_f32_e32 v162, 0xbfb8aa3b, v162
	v_exp_f32_e32 v170, v170
	v_mul_f32_e32 v164, 0xbfb8aa3b, v164
	v_exp_f32_e32 v162, v162
	v_exp_f32_e32 v164, v164
	v_add_f32_e32 v161, 1.0, v161
	v_add_f32_e32 v170, 1.0, v170
	v_div_scale_f32 v172, s[6:7], v161, v161, 1.0
	v_add_f32_e32 v162, 1.0, v162
	v_div_scale_f32 v174, s[6:7], v170, v170, 1.0
	v_rcp_f32_e32 v182, v172
	v_lshlrev_b32_e32 v169, 16, v163
	v_add_f32_e32 v164, 1.0, v164
	v_div_scale_f32 v176, s[6:7], v162, v162, 1.0
	v_rcp_f32_e32 v183, v174
	v_mul_f32_e32 v169, 0xbfb8aa3b, v169
	v_div_scale_f32 v178, s[6:7], v164, v164, 1.0
	v_rcp_f32_e32 v184, v176
	v_exp_f32_e32 v169, v169
	v_rcp_f32_e32 v185, v178
	v_fma_f32 v187, -v172, v182, 1.0
	v_div_scale_f32 v173, vcc, 1.0, v161, 1.0
	v_fma_f32 v188, -v174, v183, 1.0
	v_fmac_f32_e32 v182, v187, v182
	v_div_scale_f32 v175, s[10:11], 1.0, v170, 1.0
	v_fma_f32 v189, -v176, v184, 1.0
	v_fmac_f32_e32 v183, v188, v183
	v_mul_f32_e32 v187, v173, v182
	v_add_f32_e32 v169, 1.0, v169
	v_div_scale_f32 v177, s[12:13], 1.0, v162, 1.0
; __device__ __forceinline__ float sigmoidf_(float x) { return 1.0f / (1.0f + __expf(-x)); }
; __device__ __forceinline__ u32x4 pack8(const f32x4 v0, const f32x4 v1) { u32x4 w; w.x = pk2(v0[0], v0[1]); w.y = pk2(v0[2], v0[3]); w.z = pk2(v1[0], v1[1]); w.w = pk2(v1[2], v1[3]); return w; }
; __device__ __forceinline__ void unpack8(const u32x4 w, f32x4& v0, f32x4& v1) { v0 = (f32x4){bflo(w.x), bfhi(w.x), bflo(w.y), bfhi(w.y)}; v1 = (f32x4){bflo(w.z), bfhi(w.z), bflo(w.w), bfhi(w.w)}; }
;     __device__ __forceinline__ void operator()(const f32x4 (&acc)[2][2][4][2], const Unit& u, int wr, int wc, int fr, int fq) const {
;     ...
;         for (int ai = 0; ai < 2; ++ai)
; #pragma unroll
;             for (int m = 0; m < 4; ++m) {
;                 bf16_t* rowp = z + (size_t)(row0 + ai * 128 + m * 16) * DIN + col0;
; #pragma unroll
;                 for (int bj = 0; bj < 2; ++bj) {
;                     const u32x4 gw = *(const u32x4*)(rowp + (MODE == 0 ? O_GB : O_GA) + bj * 128);
;                     f32x4 g0, g1; unpack8(gw, g0, g1);
;                     f32x4 v0, v1;
; #pragma unroll
;                     for (int j = 0; j < 4; ++j) { v0[j] = sigmoidf_(g0[j]) * acc[ai][bj][m][0][j]; v1[j] = sigmoidf_(g1[j]) * acc[ai][bj][m][1][j]; }
;                     if (MODE == 1) { const u32x4 mw = *(const u32x4*)(rowp + bj * 128); f32x4 m0, m1; unpack8(mw, m0, m1); v0 += m0; v1 += m1; }
;                     *(u32x4*)(rowp + bj * 128) = pack8(v0, v1); }
	v_fma_f32 v190, -v178, v185, 1.0
	v_fmac_f32_e32 v184, v189, v184
	v_mul_f32_e32 v188, v175, v183
	v_fma_f32 v192, -v172, v187, v173
	v_div_scale_f32 v179, s[14:15], 1.0, v164, 1.0
	v_div_scale_f32 v180, s[6:7], v169, v169, 1.0
	v_fmac_f32_e32 v185, v190, v185
	v_mul_f32_e32 v189, v177, v184
	v_fma_f32 v193, -v174, v188, v175
	v_fmac_f32_e32 v187, v192, v182
	v_lshlrev_b32_e32 v171, 16, v165
	v_rcp_f32_e32 v186, v180
	v_mul_f32_e32 v190, v179, v185
	v_fma_f32 v194, -v176, v189, v177
	v_fmac_f32_e32 v188, v193, v183
	v_fma_f32 v172, -v172, v187, v173
	v_mul_f32_e32 v171, 0xbfb8aa3b, v171
	v_fma_f32 v195, -v178, v190, v179
	v_fmac_f32_e32 v189, v194, v184
	v_fma_f32 v173, -v174, v188, v175
	v_div_fmas_f32 v172, v172, v182, v187
	s_mov_b64 vcc, s[10:11]
	v_exp_f32_e32 v171, v171
	v_fmac_f32_e32 v190, v195, v185
	v_fma_f32 v174, -v176, v189, v177
	v_div_fixup_f32 v161, v172, v161, 1.0
	v_div_fmas_f32 v172, v173, v183, v188
	s_mov_b64 vcc, s[12:13]
	v_fma_f32 v175, -v178, v190, v179
	v_mul_f32_e32 v124, v124, v161
	v_div_fixup_f32 v161, v172, v170, 1.0
	v_div_fmas_f32 v170, v174, v184, v189
	s_mov_b64 vcc, s[14:15]
	v_fma_f32 v191, -v180, v186, 1.0
	v_mul_f32_e32 v161, v120, v161
	v_div_fixup_f32 v120, v170, v162, 1.0
	v_div_fmas_f32 v162, v175, v185, v190
	v_div_scale_f32 v181, s[16:17], 1.0, v169, 1.0
	v_fmac_f32_e32 v186, v191, v186
	v_mul_f32_e32 v120, v125, v120
	v_div_fixup_f32 v125, v162, v164, 1.0
	v_mul_f32_e32 v191, v181, v186
	v_mul_f32_e32 v125, v121, v125
	v_add_f32_e32 v121, 1.0, v171
	v_fma_f32 v196, -v180, v191, v181
	v_div_scale_f32 v162, s[6:7], v121, v121, 1.0
	v_fmac_f32_e32 v191, v196, v186
	v_rcp_f32_e32 v164, v162
	v_fma_f32 v176, -v180, v191, v181
	s_mov_b64 vcc, s[16:17]
	v_and_b32_e32 v163, 0xffff0000, v163
	v_div_fmas_f32 v170, v176, v186, v191
	v_div_fixup_f32 v169, v170, v169, 1.0
	v_mul_f32_e32 v163, 0xbfb8aa3b, v163
	v_mul_f32_e32 v126, v126, v169
	v_fma_f32 v169, -v162, v164, 1.0
	v_exp_f32_e32 v163, v163
	v_fmac_f32_e32 v164, v169, v164
	v_div_scale_f32 v169, vcc, 1.0, v121, 1.0
	v_mul_f32_e32 v170, v169, v164
	v_fma_f32 v171, -v162, v170, v169
	v_fmac_f32_e32 v170, v171, v164
	v_add_f32_e32 v163, 1.0, v163
	v_fma_f32 v162, -v162, v170, v169
	v_div_scale_f32 v169, s[6:7], v163, v163, 1.0
	v_rcp_f32_e32 v171, v169
	v_and_b32_e32 v165, 0xffff0000, v165
	v_div_fmas_f32 v162, v162, v164, v170
	v_mul_f32_e32 v164, 0xbfb8aa3b, v165
	v_div_fixup_f32 v121, v162, v121, 1.0
	v_exp_f32_e32 v164, v164
	v_mul_f32_e32 v162, v122, v121
	v_fma_f32 v121, -v169, v171, 1.0
	v_fmac_f32_e32 v171, v121, v171
	v_div_scale_f32 v121, vcc, 1.0, v163, 1.0
	v_mul_f32_e32 v122, v121, v171
	v_fma_f32 v165, -v169, v122, v121
	v_add_f32_e32 v164, 1.0, v164
	v_fmac_f32_e32 v122, v165, v171
	v_div_scale_f32 v165, s[6:7], v164, v164, 1.0
	v_fma_f32 v121, -v169, v122, v121
	v_rcp_f32_e32 v169, v165
	v_div_fmas_f32 v121, v121, v171, v122
	v_div_fixup_f32 v121, v121, v163, 1.0
	v_mul_f32_e32 v121, v127, v121
	v_fma_f32 v122, -v165, v169, 1.0
	v_fmac_f32_e32 v169, v122, v169
	v_div_scale_f32 v122, vcc, 1.0, v164, 1.0
	v_mul_f32_e32 v127, v122, v169
	v_fma_f32 v163, -v165, v127, v122
	v_fmac_f32_e32 v127, v163, v169
	v_fma_f32 v122, -v165, v127, v122
	v_div_fmas_f32 v122, v122, v169, v127
	v_div_fixup_f32 v122, v122, v164, 1.0
	v_mul_f32_e32 v123, v123, v122
	v_cvt_pk_bf16_f32 v120, v124, v120
	v_cvt_pk_bf16_f32 v121, v126, v121
	v_cvt_pk_bf16_f32 v122, v161, v125
	v_cvt_pk_bf16_f32 v123, v162, v123
	s_mov_b64 s[14:15], s[30:31]
	global_store_dwordx4 v[150:151], v[120:123], off
	s_mov_b64 s[12:13], s[28:29]
	s_waitcnt vmcnt(11)
	v_mov_b32_e32 v124, v204
	v_mov_b32_e32 v125, v205
	v_mov_b32_e32 v126, v206
	v_mov_b32_e32 v127, v207
	v_add_u32_e32 v198, 0x155a00, v197
	global_load_dwordx4 v[204:207], v198, s[22:23]
	v_lshlrev_b32_e32 v120, 16, v124
	v_mul_f32_e32 v120, 0xbfb8aa3b, v120
	v_exp_f32_e32 v120, v120
	v_and_b32_e32 v121, 0xffff0000, v124
	v_lshlrev_b32_e32 v124, 16, v126
	v_mul_f32_e32 v124, 0xbfb8aa3b, v124
	v_add_f32_e32 v120, 1.0, v120
	v_exp_f32_e32 v124, v124
	v_div_scale_f32 v152, s[6:7], v120, v120, 1.0
	v_rcp_f32_e32 v162, v152
	v_add_f32_e32 v124, 1.0, v124
	v_div_scale_f32 v161, s[6:7], v124, v124, 1.0
	v_fma_f32 v165, -v152, v162, 1.0
	v_div_scale_f32 v153, vcc, 1.0, v120, 1.0
	v_rcp_f32_e32 v163, v161
	v_fmac_f32_e32 v162, v165, v162
	v_mul_f32_e32 v121, 0xbfb8aa3b, v121
	v_mul_f32_e32 v165, v153, v162
	v_exp_f32_e32 v121, v121
	v_fma_f32 v170, -v152, v165, v153
	v_fmac_f32_e32 v165, v170, v162
	v_fma_f32 v169, -v161, v163, 1.0
	v_fma_f32 v152, -v152, v165, v153
	v_div_scale_f32 v164, s[10:11], 1.0, v124, 1.0
	v_fmac_f32_e32 v163, v169, v163
	v_div_fmas_f32 v152, v152, v162, v165
	v_add_f32_e32 v121, 1.0, v121
	v_mul_f32_e32 v169, v164, v163
	v_div_fixup_f32 v120, v152, v120, 1.0
	v_fma_f32 v171, -v161, v169, v164
	v_mul_f32_e32 v116, v116, v120
	v_div_scale_f32 v120, s[6:7], v121, v121, 1.0
	v_fmac_f32_e32 v169, v171, v163
	v_rcp_f32_e32 v152, v120
	v_fma_f32 v153, -v161, v169, v164
	s_mov_b64 vcc, s[10:11]
	v_div_fmas_f32 v153, v153, v163, v169
	v_lshlrev_b32_e32 v122, 16, v125
	v_and_b32_e32 v123, 0xffff0000, v125
	v_and_b32_e32 v125, 0xffff0000, v126
	v_div_fixup_f32 v124, v153, v124, 1.0
	v_mul_f32_e32 v112, v112, v124
	v_fma_f32 v124, -v120, v152, 1.0
	v_mul_f32_e32 v125, 0xbfb8aa3b, v125
	v_fmac_f32_e32 v152, v124, v152
	v_div_scale_f32 v124, vcc, 1.0, v121, 1.0
	v_exp_f32_e32 v125, v125
	v_mul_f32_e32 v153, v124, v152
	v_fma_f32 v161, -v120, v153, v124
	v_fmac_f32_e32 v153, v161, v152
	v_fma_f32 v120, -v120, v153, v124
	v_add_f32_e32 v124, 1.0, v125
	v_div_scale_f32 v125, s[6:7], v124, v124, 1.0
	v_rcp_f32_e32 v161, v125
; __device__ __forceinline__ float sigmoidf_(float x) { return 1.0f / (1.0f + __expf(-x)); }
; __device__ __forceinline__ u32x4 pack8(const f32x4 v0, const f32x4 v1) { u32x4 w; w.x = pk2(v0[0], v0[1]); w.y = pk2(v0[2], v0[3]); w.z = pk2(v1[0], v1[1]); w.w = pk2(v1[2], v1[3]); return w; }
; __device__ __forceinline__ void unpack8(const u32x4 w, f32x4& v0, f32x4& v1) { v0 = (f32x4){bflo(w.x), bfhi(w.x), bflo(w.y), bfhi(w.y)}; v1 = (f32x4){bflo(w.z), bfhi(w.z), bflo(w.w), bfhi(w.w)}; }
;     __device__ __forceinline__ void operator()(const f32x4 (&acc)[2][2][4][2], const Unit& u, int wr, int wc, int fr, int fq) const {
;     ...
;         for (int ai = 0; ai < 2; ++ai)
; #pragma unroll
;             for (int m = 0; m < 4; ++m) {
;                 bf16_t* rowp = z + (size_t)(row0 + ai * 128 + m * 16) * DIN + col0;
; #pragma unroll
;                 for (int bj = 0; bj < 2; ++bj) {
;                     const u32x4 gw = *(const u32x4*)(rowp + (MODE == 0 ? O_GB : O_GA) + bj * 128);
;                     f32x4 g0, g1; unpack8(gw, g0, g1);
;                     f32x4 v0, v1;
; #pragma unroll
;                     for (int j = 0; j < 4; ++j) { v0[j] = sigmoidf_(g0[j]) * acc[ai][bj][m][0][j]; v1[j] = sigmoidf_(g1[j]) * acc[ai][bj][m][1][j]; }
;                     if (MODE == 1) { const u32x4 mw = *(const u32x4*)(rowp + bj * 128); f32x4 m0, m1; unpack8(mw, m0, m1); v0 += m0; v1 += m1; }
;                     *(u32x4*)(rowp + bj * 128) = pack8(v0, v1); }
	v_div_fmas_f32 v120, v120, v152, v153
	v_div_fixup_f32 v120, v120, v121, 1.0
	v_mul_f32_e32 v122, 0xbfb8aa3b, v122
	v_mul_f32_e32 v117, v117, v120
	v_fma_f32 v120, -v125, v161, 1.0
	v_exp_f32_e32 v122, v122
	v_fmac_f32_e32 v161, v120, v161
	v_div_scale_f32 v120, vcc, 1.0, v124, 1.0
	v_mul_f32_e32 v121, v120, v161
	v_fma_f32 v152, -v125, v121, v120
	v_fmac_f32_e32 v121, v152, v161
	v_add_f32_e32 v122, 1.0, v122
	v_fma_f32 v120, -v125, v121, v120
	v_div_scale_f32 v125, s[6:7], v122, v122, 1.0
	v_rcp_f32_e32 v152, v125
	v_lshlrev_b32_e32 v126, 16, v127
	v_div_fmas_f32 v120, v120, v161, v121
	v_div_fixup_f32 v120, v120, v124, 1.0
	v_mul_f32_e32 v124, 0xbfb8aa3b, v126
	v_mul_f32_e32 v113, v113, v120
	v_fma_f32 v120, -v125, v152, 1.0
	v_exp_f32_e32 v124, v124
	v_fmac_f32_e32 v152, v120, v152
	v_div_scale_f32 v120, vcc, 1.0, v122, 1.0
	v_mul_f32_e32 v121, v120, v152
	v_fma_f32 v126, -v125, v121, v120
	v_fmac_f32_e32 v121, v126, v152
	v_add_f32_e32 v124, 1.0, v124
	v_fma_f32 v120, -v125, v121, v120
	v_div_scale_f32 v125, s[6:7], v124, v124, 1.0
	v_rcp_f32_e32 v126, v125
	v_div_fmas_f32 v120, v120, v152, v121
	v_div_fixup_f32 v120, v120, v122, 1.0
	v_mul_f32_e32 v122, 0xbfb8aa3b, v123
	v_exp_f32_e32 v122, v122
	v_mul_f32_e32 v118, v118, v120
	v_fma_f32 v120, -v125, v126, 1.0
	v_fmac_f32_e32 v126, v120, v126
	v_div_scale_f32 v120, vcc, 1.0, v124, 1.0
	v_mul_f32_e32 v121, v120, v126
	v_fma_f32 v123, -v125, v121, v120
	v_add_f32_e32 v122, 1.0, v122
	v_fmac_f32_e32 v121, v123, v126
	v_div_scale_f32 v123, s[6:7], v122, v122, 1.0
	v_fma_f32 v120, -v125, v121, v120
	v_rcp_f32_e32 v125, v123
	v_div_fmas_f32 v120, v120, v126, v121
	v_and_b32_e32 v127, 0xffff0000, v127
	v_div_fixup_f32 v120, v120, v124, 1.0
	v_mul_f32_e32 v120, v114, v120
	v_fma_f32 v114, -v123, v125, 1.0
	v_mul_f32_e32 v124, 0xbfb8aa3b, v127
	v_fmac_f32_e32 v125, v114, v125
	v_div_scale_f32 v114, vcc, 1.0, v122, 1.0
	v_exp_f32_e32 v124, v124
	v_mul_f32_e32 v121, v114, v125
	v_fma_f32 v126, -v123, v121, v114
	v_fmac_f32_e32 v121, v126, v125
	v_fma_f32 v114, -v123, v121, v114
	v_add_f32_e32 v123, 1.0, v124
	v_div_scale_f32 v124, s[6:7], v123, v123, 1.0
	v_rcp_f32_e32 v126, v124
	v_div_fmas_f32 v114, v114, v125, v121
	v_div_fixup_f32 v114, v114, v122, 1.0
	v_mul_f32_e32 v119, v119, v114
	v_fma_f32 v114, -v124, v126, 1.0
	v_fmac_f32_e32 v126, v114, v126
	v_div_scale_f32 v114, vcc, 1.0, v123, 1.0
	v_mul_f32_e32 v121, v114, v126
	v_fma_f32 v122, -v124, v121, v114
	v_fmac_f32_e32 v121, v122, v126
	v_fma_f32 v114, -v124, v121, v114
	v_div_fmas_f32 v114, v114, v126, v121
	v_div_fixup_f32 v114, v114, v123, 1.0
	v_mul_f32_e32 v121, v115, v114
	v_cvt_pk_bf16_f32 v114, v116, v117
	v_cvt_pk_bf16_f32 v115, v118, v119
	v_cvt_pk_bf16_f32 v116, v112, v113
	v_or_b32_e32 v112, 16, v160
	v_mad_i64_i32 v[112:113], s[6:7], v112, s57, v[146:147]
	v_lshl_add_u64 v[112:113], v[112:113], 0, v[148:149]
	v_add_co_u32_e32 v122, vcc, s58, v112
	v_cvt_pk_bf16_f32 v117, v120, v121
	global_store_dwordx4 v[150:151], v[114:117], off offset:256
	s_nop 0
	v_addc_co_u32_e32 v123, vcc, 0, v113, vcc
	s_waitcnt vmcnt(12)
	v_mov_b32_e32 v118, v208
	v_mov_b32_e32 v119, v209
	v_mov_b32_e32 v120, v210
	v_mov_b32_e32 v121, v211
	v_add_u32_e32 v198, 0x155b00, v197
	global_load_dwordx4 v[208:211], v198, s[22:23]
	v_lshlrev_b32_e32 v114, 16, v118
	v_mul_f32_e32 v114, 0xbfb8aa3b, v114
	v_exp_f32_e32 v114, v114
	v_lshlrev_b32_e32 v116, 16, v119
	v_and_b32_e32 v117, 0xffff0000, v119
	v_and_b32_e32 v115, 0xffff0000, v118
	v_add_f32_e32 v114, 1.0, v114
	v_div_scale_f32 v119, s[6:7], v114, v114, 1.0
	v_rcp_f32_e32 v124, v119
	v_lshlrev_b32_e32 v118, 16, v120
	v_mul_f32_e32 v118, 0xbfb8aa3b, v118
	v_exp_f32_e32 v118, v118
	v_fma_f32 v126, -v119, v124, 1.0
	v_fmac_f32_e32 v124, v126, v124
	v_div_scale_f32 v126, vcc, 1.0, v114, 1.0
	v_mul_f32_e32 v127, v126, v124
	v_fma_f32 v150, -v119, v127, v126
	v_fmac_f32_e32 v127, v150, v124
	v_add_f32_e32 v118, 1.0, v118
	v_fma_f32 v119, -v119, v127, v126
	v_div_scale_f32 v126, s[6:7], v118, v118, 1.0
	v_rcp_f32_e32 v150, v126
	v_div_fmas_f32 v119, v119, v124, v127
	v_mul_f32_e32 v115, 0xbfb8aa3b, v115
	v_div_fixup_f32 v114, v119, v114, 1.0
	v_exp_f32_e32 v115, v115
	v_mul_f32_e32 v108, v108, v114
	v_fma_f32 v114, -v126, v150, 1.0
	v_fmac_f32_e32 v150, v114, v150
	v_div_scale_f32 v114, vcc, 1.0, v118, 1.0
	v_mul_f32_e32 v119, v114, v150
	v_fma_f32 v124, -v126, v119, v114
	v_add_f32_e32 v115, 1.0, v115
	v_fmac_f32_e32 v119, v124, v150
	v_div_scale_f32 v124, s[6:7], v115, v115, 1.0
	v_fma_f32 v114, -v126, v119, v114
	v_rcp_f32_e32 v126, v124
	v_and_b32_e32 v120, 0xffff0000, v120
	v_div_fmas_f32 v114, v114, v150, v119
	v_mul_f32_e32 v119, 0xbfb8aa3b, v120
	v_div_fixup_f32 v114, v114, v118, 1.0
	v_exp_f32_e32 v119, v119
	v_mul_f32_e32 v114, v104, v114
	v_fma_f32 v104, -v124, v126, 1.0
	v_fmac_f32_e32 v126, v104, v126
	v_div_scale_f32 v104, vcc, 1.0, v115, 1.0
	v_mul_f32_e32 v118, v104, v126
	v_fma_f32 v120, -v124, v118, v104
	v_add_f32_e32 v119, 1.0, v119
	v_fmac_f32_e32 v118, v120, v126
	v_div_scale_f32 v120, s[6:7], v119, v119, 1.0
	v_fma_f32 v104, -v124, v118, v104
	v_rcp_f32_e32 v124, v120
	v_div_fmas_f32 v104, v104, v126, v118
	v_mul_f32_e32 v116, 0xbfb8aa3b, v116
	v_div_fixup_f32 v104, v104, v115, 1.0
	v_exp_f32_e32 v116, v116
	v_mul_f32_e32 v104, v109, v104
	v_fma_f32 v109, -v120, v124, 1.0
	v_fmac_f32_e32 v124, v109, v124
	v_div_scale_f32 v109, vcc, 1.0, v119, 1.0
	v_mul_f32_e32 v115, v109, v124
	v_fma_f32 v118, -v120, v115, v109
	v_add_f32_e32 v116, 1.0, v116
	v_fmac_f32_e32 v115, v118, v124
	v_div_scale_f32 v118, s[6:7], v116, v116, 1.0
	v_fma_f32 v109, -v120, v115, v109
	v_rcp_f32_e32 v120, v118
; __device__ __forceinline__ u32x4 pack8(const f32x4 v0, const f32x4 v1) { u32x4 w; w.x = pk2(v0[0], v0[1]); w.y = pk2(v0[2], v0[3]); w.z = pk2(v1[0], v1[1]); w.w = pk2(v1[2], v1[3]); return w; }
; __device__ __forceinline__ void unpack8(const u32x4 w, f32x4& v0, f32x4& v1) { v0 = (f32x4){bflo(w.x), bfhi(w.x), bflo(w.y), bfhi(w.y)}; v1 = (f32x4){bflo(w.z), bfhi(w.z), bflo(w.w), bfhi(w.w)}; }
; __device__ __forceinline__ float sigmoidf_(float x) { return 1.0f / (1.0f + __expf(-x)); }
;     __device__ __forceinline__ void operator()(const f32x4 (&acc)[2][2][4][2], const Unit& u, int wr, int wc, int fr, int fq) const {
;     ...
;                 bf16_t* rowp = z + (size_t)(row0 + ai * 128 + m * 16) * DIN + col0;
; #pragma unroll
;                 for (int bj = 0; bj < 2; ++bj) {
;                     const u32x4 gw = *(const u32x4*)(rowp + (MODE == 0 ? O_GB : O_GA) + bj * 128);
;                     f32x4 g0, g1; unpack8(gw, g0, g1);
;                     f32x4 v0, v1;
; #pragma unroll
;                     for (int j = 0; j < 4; ++j) { v0[j] = sigmoidf_(g0[j]) * acc[ai][bj][m][0][j]; v1[j] = sigmoidf_(g1[j]) * acc[ai][bj][m][1][j]; }
;                     if (MODE == 1) { const u32x4 mw = *(const u32x4*)(rowp + bj * 128); f32x4 m0, m1; unpack8(mw, m0, m1); v0 += m0; v1 += m1; }
;                     *(u32x4*)(rowp + bj * 128) = pack8(v0, v1); }
	v_div_fmas_f32 v109, v109, v124, v115
	v_lshlrev_b32_e32 v125, 16, v121
	v_div_fixup_f32 v109, v109, v119, 1.0
	v_mul_f32_e32 v109, v105, v109
	v_fma_f32 v105, -v118, v120, 1.0
	v_mul_f32_e32 v119, 0xbfb8aa3b, v125
	v_fmac_f32_e32 v120, v105, v120
	v_div_scale_f32 v105, vcc, 1.0, v116, 1.0
	v_exp_f32_e32 v119, v119
	v_mul_f32_e32 v115, v105, v120
	v_fma_f32 v124, -v118, v115, v105
	v_fmac_f32_e32 v115, v124, v120
	v_fma_f32 v105, -v118, v115, v105
	v_add_f32_e32 v118, 1.0, v119
	v_div_scale_f32 v119, s[6:7], v118, v118, 1.0
	v_rcp_f32_e32 v124, v119
	v_div_fmas_f32 v105, v105, v120, v115
	v_div_fixup_f32 v105, v105, v116, 1.0
	v_mul_f32_e32 v116, 0xbfb8aa3b, v117
	v_exp_f32_e32 v116, v116
	v_mul_f32_e32 v105, v110, v105
	v_fma_f32 v110, -v119, v124, 1.0
	v_fmac_f32_e32 v124, v110, v124
	v_div_scale_f32 v110, vcc, 1.0, v118, 1.0
	v_mul_f32_e32 v115, v110, v124
	v_fma_f32 v117, -v119, v115, v110
	v_add_f32_e32 v116, 1.0, v116
	v_fmac_f32_e32 v115, v117, v124
	v_div_scale_f32 v117, s[6:7], v116, v116, 1.0
	v_fma_f32 v110, -v119, v115, v110
	v_rcp_f32_e32 v119, v117
	v_div_fmas_f32 v110, v110, v124, v115
	v_and_b32_e32 v121, 0xffff0000, v121
	v_div_fixup_f32 v110, v110, v118, 1.0
	v_mul_f32_e32 v110, v106, v110
	v_fma_f32 v106, -v117, v119, 1.0
	v_mul_f32_e32 v118, 0xbfb8aa3b, v121
	v_fmac_f32_e32 v119, v106, v119
	v_div_scale_f32 v106, vcc, 1.0, v116, 1.0
	v_exp_f32_e32 v118, v118
	v_mul_f32_e32 v115, v106, v119
	v_fma_f32 v120, -v117, v115, v106
	v_fmac_f32_e32 v115, v120, v119
	v_fma_f32 v106, -v117, v115, v106
	v_add_f32_e32 v117, 1.0, v118
	v_div_scale_f32 v118, s[6:7], v117, v117, 1.0
	v_rcp_f32_e32 v120, v118
	v_div_fmas_f32 v106, v106, v119, v115
	v_div_fixup_f32 v106, v106, v116, 1.0
	v_mul_f32_e32 v106, v111, v106
	v_fma_f32 v111, -v118, v120, 1.0
	v_fmac_f32_e32 v120, v111, v120
	v_div_scale_f32 v111, vcc, 1.0, v117, 1.0
	v_mul_f32_e32 v115, v111, v120
	v_fma_f32 v116, -v118, v115, v111
	v_fmac_f32_e32 v115, v116, v120
	v_fma_f32 v111, -v118, v115, v111
	v_div_fmas_f32 v111, v111, v120, v115
	v_div_fixup_f32 v111, v111, v117, 1.0
	v_mul_f32_e32 v107, v107, v111
	v_cvt_pk_bf16_f32 v104, v108, v104
	v_cvt_pk_bf16_f32 v105, v105, v106
	v_cvt_pk_bf16_f32 v106, v114, v109
	v_cvt_pk_bf16_f32 v107, v110, v107
	s_waitcnt vmcnt(12)
	v_mov_b32_e32 v108, v212
	v_mov_b32_e32 v109, v213
	v_mov_b32_e32 v110, v214
	v_mov_b32_e32 v111, v215
	v_add_u32_e32 v198, 0x177a00, v197
	global_load_dwordx4 v[212:215], v198, s[22:23]
	v_lshlrev_b32_e32 v115, 16, v111
	global_store_dwordx4 v[112:113], v[104:107], off
	v_and_b32_e32 v111, 0xffff0000, v111
	s_nop 0
	v_lshlrev_b32_e32 v104, 16, v108
	v_mul_f32_e32 v104, 0xbfb8aa3b, v104
	v_exp_f32_e32 v104, v104
	v_lshlrev_b32_e32 v106, 16, v109
	v_and_b32_e32 v107, 0xffff0000, v109
	v_and_b32_e32 v105, 0xffff0000, v108
	v_add_f32_e32 v104, 1.0, v104
	v_div_scale_f32 v109, s[6:7], v104, v104, 1.0
	v_rcp_f32_e32 v114, v109
	v_lshlrev_b32_e32 v108, 16, v110
	v_mul_f32_e32 v108, 0xbfb8aa3b, v108
	v_exp_f32_e32 v108, v108
	v_fma_f32 v116, -v109, v114, 1.0
	v_fmac_f32_e32 v114, v116, v114
	v_div_scale_f32 v116, vcc, 1.0, v104, 1.0
	v_mul_f32_e32 v117, v116, v114
	v_fma_f32 v118, -v109, v117, v116
	v_fmac_f32_e32 v117, v118, v114
	v_add_f32_e32 v108, 1.0, v108
	v_fma_f32 v109, -v109, v117, v116
	v_div_scale_f32 v116, s[6:7], v108, v108, 1.0
	v_rcp_f32_e32 v118, v116
	v_div_fmas_f32 v109, v109, v114, v117
	v_mul_f32_e32 v105, 0xbfb8aa3b, v105
	v_div_fixup_f32 v104, v109, v104, 1.0
	v_exp_f32_e32 v105, v105
	v_mul_f32_e32 v100, v100, v104
	v_fma_f32 v104, -v116, v118, 1.0
	v_fmac_f32_e32 v118, v104, v118
	v_div_scale_f32 v104, vcc, 1.0, v108, 1.0
	v_mul_f32_e32 v109, v104, v118
	v_fma_f32 v114, -v116, v109, v104
	v_add_f32_e32 v105, 1.0, v105
	v_fmac_f32_e32 v109, v114, v118
	v_div_scale_f32 v114, s[6:7], v105, v105, 1.0
	v_fma_f32 v104, -v116, v109, v104
	v_rcp_f32_e32 v116, v114
	v_and_b32_e32 v110, 0xffff0000, v110
	v_div_fmas_f32 v104, v104, v118, v109
	v_mul_f32_e32 v109, 0xbfb8aa3b, v110
	v_div_fixup_f32 v104, v104, v108, 1.0
	v_exp_f32_e32 v109, v109
	v_mul_f32_e32 v96, v96, v104
	v_fma_f32 v104, -v114, v116, 1.0
	v_fmac_f32_e32 v116, v104, v116
	v_div_scale_f32 v104, vcc, 1.0, v105, 1.0
	v_mul_f32_e32 v108, v104, v116
	v_fma_f32 v110, -v114, v108, v104
	v_add_f32_e32 v109, 1.0, v109
	v_fmac_f32_e32 v108, v110, v116
	v_div_scale_f32 v110, s[6:7], v109, v109, 1.0
	v_fma_f32 v104, -v114, v108, v104
	v_rcp_f32_e32 v114, v110
	v_div_fmas_f32 v104, v104, v116, v108
	v_mul_f32_e32 v106, 0xbfb8aa3b, v106
	v_div_fixup_f32 v104, v104, v105, 1.0
	v_exp_f32_e32 v106, v106
	v_mul_f32_e32 v101, v101, v104
	v_fma_f32 v104, -v110, v114, 1.0
	v_fmac_f32_e32 v114, v104, v114
	v_div_scale_f32 v104, vcc, 1.0, v109, 1.0
	v_mul_f32_e32 v105, v104, v114
	v_fma_f32 v108, -v110, v105, v104
	v_add_f32_e32 v106, 1.0, v106
	v_fmac_f32_e32 v105, v108, v114
	v_div_scale_f32 v108, s[6:7], v106, v106, 1.0
	v_fma_f32 v104, -v110, v105, v104
	v_rcp_f32_e32 v110, v108
	v_div_fmas_f32 v104, v104, v114, v105
	v_div_fixup_f32 v104, v104, v109, 1.0
	v_mul_f32_e32 v97, v97, v104
	v_fma_f32 v104, -v108, v110, 1.0
	v_mul_f32_e32 v109, 0xbfb8aa3b, v115
	v_fmac_f32_e32 v110, v104, v110
	v_div_scale_f32 v104, vcc, 1.0, v106, 1.0
	v_exp_f32_e32 v109, v109
	v_mul_f32_e32 v105, v104, v110
	v_fma_f32 v114, -v108, v105, v104
	v_fmac_f32_e32 v105, v114, v110
	v_fma_f32 v104, -v108, v105, v104
	v_add_f32_e32 v108, 1.0, v109
	v_div_scale_f32 v109, s[6:7], v108, v108, 1.0
	v_rcp_f32_e32 v114, v109
	v_div_fmas_f32 v104, v104, v110, v105
	v_div_fixup_f32 v104, v104, v106, 1.0
	v_mul_f32_e32 v106, 0xbfb8aa3b, v107
	v_exp_f32_e32 v106, v106
	v_mul_f32_e32 v102, v102, v104
; __device__ __forceinline__ u32x4 pack8(const f32x4 v0, const f32x4 v1) { u32x4 w; w.x = pk2(v0[0], v0[1]); w.y = pk2(v0[2], v0[3]); w.z = pk2(v1[0], v1[1]); w.w = pk2(v1[2], v1[3]); return w; }
; __device__ __forceinline__ void unpack8(const u32x4 w, f32x4& v0, f32x4& v1) { v0 = (f32x4){bflo(w.x), bfhi(w.x), bflo(w.y), bfhi(w.y)}; v1 = (f32x4){bflo(w.z), bfhi(w.z), bflo(w.w), bfhi(w.w)}; }
; __device__ __forceinline__ float sigmoidf_(float x) { return 1.0f / (1.0f + __expf(-x)); }
;     __device__ __forceinline__ void operator()(const f32x4 (&acc)[2][2][4][2], const Unit& u, int wr, int wc, int fr, int fq) const {
;     ...
;                 bf16_t* rowp = z + (size_t)(row0 + ai * 128 + m * 16) * DIN + col0;
; #pragma unroll
;                 for (int bj = 0; bj < 2; ++bj) {
;                     const u32x4 gw = *(const u32x4*)(rowp + (MODE == 0 ? O_GB : O_GA) + bj * 128);
;                     f32x4 g0, g1; unpack8(gw, g0, g1);
;                     f32x4 v0, v1;
; #pragma unroll
;                     for (int j = 0; j < 4; ++j) { v0[j] = sigmoidf_(g0[j]) * acc[ai][bj][m][0][j]; v1[j] = sigmoidf_(g1[j]) * acc[ai][bj][m][1][j]; }
;                     if (MODE == 1) { const u32x4 mw = *(const u32x4*)(rowp + bj * 128); f32x4 m0, m1; unpack8(mw, m0, m1); v0 += m0; v1 += m1; }
;                     *(u32x4*)(rowp + bj * 128) = pack8(v0, v1); }
	v_fma_f32 v104, -v109, v114, 1.0
	v_fmac_f32_e32 v114, v104, v114
	v_div_scale_f32 v104, vcc, 1.0, v108, 1.0
	v_mul_f32_e32 v105, v104, v114
	v_fma_f32 v107, -v109, v105, v104
	v_add_f32_e32 v106, 1.0, v106
	v_fmac_f32_e32 v105, v107, v114
	v_div_scale_f32 v107, s[6:7], v106, v106, 1.0
	v_fma_f32 v104, -v109, v105, v104
	v_rcp_f32_e32 v109, v107
	v_div_fmas_f32 v104, v104, v114, v105
	v_div_fixup_f32 v104, v104, v108, 1.0
	v_mul_f32_e32 v104, v98, v104
	v_fma_f32 v98, -v107, v109, 1.0
	v_mul_f32_e32 v108, 0xbfb8aa3b, v111
	v_fmac_f32_e32 v109, v98, v109
	v_div_scale_f32 v98, vcc, 1.0, v106, 1.0
	v_exp_f32_e32 v108, v108
	v_mul_f32_e32 v105, v98, v109
	v_fma_f32 v110, -v107, v105, v98
	v_fmac_f32_e32 v105, v110, v109
	v_fma_f32 v98, -v107, v105, v98
	v_add_f32_e32 v107, 1.0, v108
	v_div_scale_f32 v108, s[6:7], v107, v107, 1.0
	v_rcp_f32_e32 v110, v108
	v_div_fmas_f32 v98, v98, v109, v105
	v_div_fixup_f32 v98, v98, v106, 1.0
	v_mul_f32_e32 v103, v103, v98
	v_fma_f32 v98, -v108, v110, 1.0
	v_fmac_f32_e32 v110, v98, v110
	v_div_scale_f32 v98, vcc, 1.0, v107, 1.0
	v_mul_f32_e32 v105, v98, v110
	v_fma_f32 v106, -v108, v105, v98
	v_fmac_f32_e32 v105, v106, v110
	v_fma_f32 v98, -v108, v105, v98
	v_div_fmas_f32 v98, v98, v110, v105
	v_div_fixup_f32 v98, v98, v107, 1.0
	v_mul_f32_e32 v105, v99, v98
	v_cvt_pk_bf16_f32 v98, v100, v101
	v_cvt_pk_bf16_f32 v99, v102, v103
	v_cvt_pk_bf16_f32 v100, v96, v97
	v_or_b32_e32 v96, 32, v160
	v_mad_i64_i32 v[96:97], s[6:7], v96, s57, v[146:147]
	v_lshl_add_u64 v[96:97], v[96:97], 0, v[148:149]
	v_add_co_u32_e32 v106, vcc, s58, v96
	v_cvt_pk_bf16_f32 v101, v104, v105
	global_store_dwordx4 v[112:113], v[98:101], off offset:256
	s_nop 0
	v_addc_co_u32_e32 v107, vcc, 0, v97, vcc
	s_waitcnt vmcnt(14)
	v_mov_b32_e32 v102, v216
	v_mov_b32_e32 v103, v217
	v_mov_b32_e32 v104, v218
	v_mov_b32_e32 v105, v219
	v_add_u32_e32 v198, 0x177b00, v197
	global_load_dwordx4 v[216:219], v198, s[22:23]
	v_lshlrev_b32_e32 v98, 16, v102
	v_mul_f32_e32 v98, 0xbfb8aa3b, v98
	v_exp_f32_e32 v98, v98
	v_lshlrev_b32_e32 v100, 16, v103
	v_and_b32_e32 v101, 0xffff0000, v103
	v_and_b32_e32 v99, 0xffff0000, v102
	v_add_f32_e32 v98, 1.0, v98
	v_div_scale_f32 v103, s[6:7], v98, v98, 1.0
	v_rcp_f32_e32 v108, v103
	v_lshlrev_b32_e32 v102, 16, v104
	v_mul_f32_e32 v102, 0xbfb8aa3b, v102
	v_exp_f32_e32 v102, v102
	v_fma_f32 v110, -v103, v108, 1.0
	v_fmac_f32_e32 v108, v110, v108
	v_div_scale_f32 v110, vcc, 1.0, v98, 1.0
	v_mul_f32_e32 v111, v110, v108
	v_fma_f32 v112, -v103, v111, v110
	v_fmac_f32_e32 v111, v112, v108
	v_add_f32_e32 v102, 1.0, v102
	v_fma_f32 v103, -v103, v111, v110
	v_div_scale_f32 v110, s[6:7], v102, v102, 1.0
	v_rcp_f32_e32 v112, v110
	v_div_fmas_f32 v103, v103, v108, v111
	v_mul_f32_e32 v99, 0xbfb8aa3b, v99
	v_div_fixup_f32 v98, v103, v98, 1.0
	v_exp_f32_e32 v99, v99
	v_mul_f32_e32 v92, v92, v98
	v_fma_f32 v98, -v110, v112, 1.0
	v_fmac_f32_e32 v112, v98, v112
	v_div_scale_f32 v98, vcc, 1.0, v102, 1.0
	v_mul_f32_e32 v103, v98, v112
	v_fma_f32 v108, -v110, v103, v98
	v_add_f32_e32 v99, 1.0, v99
	v_fmac_f32_e32 v103, v108, v112
	v_div_scale_f32 v108, s[6:7], v99, v99, 1.0
	v_fma_f32 v98, -v110, v103, v98
	v_rcp_f32_e32 v110, v108
	v_and_b32_e32 v104, 0xffff0000, v104
	v_div_fmas_f32 v98, v98, v112, v103
	v_mul_f32_e32 v103, 0xbfb8aa3b, v104
	v_div_fixup_f32 v98, v98, v102, 1.0
	v_exp_f32_e32 v103, v103
	v_mul_f32_e32 v98, v88, v98
	v_fma_f32 v88, -v108, v110, 1.0
	v_fmac_f32_e32 v110, v88, v110
	v_div_scale_f32 v88, vcc, 1.0, v99, 1.0
	v_mul_f32_e32 v102, v88, v110
	v_fma_f32 v104, -v108, v102, v88
	v_add_f32_e32 v103, 1.0, v103
	v_fmac_f32_e32 v102, v104, v110
	v_div_scale_f32 v104, s[6:7], v103, v103, 1.0
	v_fma_f32 v88, -v108, v102, v88
	v_rcp_f32_e32 v108, v104
	v_div_fmas_f32 v88, v88, v110, v102
	v_mul_f32_e32 v100, 0xbfb8aa3b, v100
	v_div_fixup_f32 v88, v88, v99, 1.0
	v_exp_f32_e32 v100, v100
	v_mul_f32_e32 v88, v93, v88
	v_fma_f32 v93, -v104, v108, 1.0
	v_fmac_f32_e32 v108, v93, v108
	v_div_scale_f32 v93, vcc, 1.0, v103, 1.0
	v_mul_f32_e32 v99, v93, v108
	v_fma_f32 v102, -v104, v99, v93
	v_add_f32_e32 v100, 1.0, v100
	v_fmac_f32_e32 v99, v102, v108
	v_div_scale_f32 v102, s[6:7], v100, v100, 1.0
	v_fma_f32 v93, -v104, v99, v93
	v_rcp_f32_e32 v104, v102
	v_div_fmas_f32 v93, v93, v108, v99
	v_lshlrev_b32_e32 v109, 16, v105
	v_div_fixup_f32 v93, v93, v103, 1.0
	v_mul_f32_e32 v93, v89, v93
	v_fma_f32 v89, -v102, v104, 1.0
	v_mul_f32_e32 v103, 0xbfb8aa3b, v109
	v_fmac_f32_e32 v104, v89, v104
	v_div_scale_f32 v89, vcc, 1.0, v100, 1.0
	v_exp_f32_e32 v103, v103
	v_mul_f32_e32 v99, v89, v104
	v_fma_f32 v108, -v102, v99, v89
	v_fmac_f32_e32 v99, v108, v104
	v_fma_f32 v89, -v102, v99, v89
	v_add_f32_e32 v102, 1.0, v103
	v_div_scale_f32 v103, s[6:7], v102, v102, 1.0
	v_rcp_f32_e32 v108, v103
	v_div_fmas_f32 v89, v89, v104, v99
	v_div_fixup_f32 v89, v89, v100, 1.0
	v_mul_f32_e32 v100, 0xbfb8aa3b, v101
	v_exp_f32_e32 v100, v100
	v_mul_f32_e32 v89, v94, v89
	v_fma_f32 v94, -v103, v108, 1.0
	v_fmac_f32_e32 v108, v94, v108
	v_div_scale_f32 v94, vcc, 1.0, v102, 1.0
	v_mul_f32_e32 v99, v94, v108
	v_fma_f32 v101, -v103, v99, v94
	v_add_f32_e32 v100, 1.0, v100
	v_fmac_f32_e32 v99, v101, v108
	v_div_scale_f32 v101, s[6:7], v100, v100, 1.0
	v_fma_f32 v94, -v103, v99, v94
	v_rcp_f32_e32 v103, v101
	v_div_fmas_f32 v94, v94, v108, v99
	v_and_b32_e32 v105, 0xffff0000, v105
	v_div_fixup_f32 v94, v94, v102, 1.0
	v_mul_f32_e32 v94, v90, v94
	v_fma_f32 v90, -v101, v103, 1.0
	v_mul_f32_e32 v102, 0xbfb8aa3b, v105
	v_fmac_f32_e32 v103, v90, v103
	v_div_scale_f32 v90, vcc, 1.0, v100, 1.0
	v_exp_f32_e32 v102, v102
	v_mul_f32_e32 v99, v90, v103
	v_fma_f32 v104, -v101, v99, v90
	v_fmac_f32_e32 v99, v104, v103
	v_fma_f32 v90, -v101, v99, v90
	v_add_f32_e32 v101, 1.0, v102
	v_div_scale_f32 v102, s[6:7], v101, v101, 1.0
	v_rcp_f32_e32 v104, v102
	v_div_fmas_f32 v90, v90, v103, v99
	v_div_fixup_f32 v90, v90, v100, 1.0
	v_mul_f32_e32 v90, v95, v90
	v_fma_f32 v95, -v102, v104, 1.0
	v_fmac_f32_e32 v104, v95, v104
	v_div_scale_f32 v95, vcc, 1.0, v101, 1.0
	v_mul_f32_e32 v99, v95, v104
	v_fma_f32 v100, -v102, v99, v95
	v_fmac_f32_e32 v99, v100, v104
	v_fma_f32 v95, -v102, v99, v95
	v_div_fmas_f32 v95, v95, v104, v99
	v_div_fixup_f32 v95, v95, v101, 1.0
	v_mul_f32_e32 v91, v91, v95
	v_cvt_pk_bf16_f32 v88, v92, v88
	v_cvt_pk_bf16_f32 v89, v89, v90
	v_cvt_pk_bf16_f32 v90, v98, v93
	v_cvt_pk_bf16_f32 v91, v94, v91
	s_waitcnt vmcnt(14)
; __device__ __forceinline__ u32x4 pack8(const f32x4 v0, const f32x4 v1) { u32x4 w; w.x = pk2(v0[0], v0[1]); w.y = pk2(v0[2], v0[3]); w.z = pk2(v1[0], v1[1]); w.w = pk2(v1[2], v1[3]); return w; }
; __device__ __forceinline__ void unpack8(const u32x4 w, f32x4& v0, f32x4& v1) { v0 = (f32x4){bflo(w.x), bfhi(w.x), bflo(w.y), bfhi(w.y)}; v1 = (f32x4){bflo(w.z), bfhi(w.z), bflo(w.w), bfhi(w.w)}; }
; __device__ __forceinline__ float sigmoidf_(float x) { return 1.0f / (1.0f + __expf(-x)); }
;     __device__ __forceinline__ void operator()(const f32x4 (&acc)[2][2][4][2], const Unit& u, int wr, int wc, int fr, int fq) const {
;     ...
;                 bf16_t* rowp = z + (size_t)(row0 + ai * 128 + m * 16) * DIN + col0;
; #pragma unroll
;                 for (int bj = 0; bj < 2; ++bj) {
;                     const u32x4 gw = *(const u32x4*)(rowp + (MODE == 0 ? O_GB : O_GA) + bj * 128);
;                     f32x4 g0, g1; unpack8(gw, g0, g1);
;                     f32x4 v0, v1;
; #pragma unroll
;                     for (int j = 0; j < 4; ++j) { v0[j] = sigmoidf_(g0[j]) * acc[ai][bj][m][0][j]; v1[j] = sigmoidf_(g1[j]) * acc[ai][bj][m][1][j]; }
;                     if (MODE == 1) { const u32x4 mw = *(const u32x4*)(rowp + bj * 128); f32x4 m0, m1; unpack8(mw, m0, m1); v0 += m0; v1 += m1; }
;                     *(u32x4*)(rowp + bj * 128) = pack8(v0, v1); }
	v_mov_b32_e32 v92, v232
	v_mov_b32_e32 v93, v233
	v_mov_b32_e32 v94, v234
	v_mov_b32_e32 v95, v235
	v_lshlrev_b32_e32 v99, 16, v95
	global_store_dwordx4 v[96:97], v[88:91], off
	v_and_b32_e32 v95, 0xffff0000, v95
	s_nop 0
	v_lshlrev_b32_e32 v88, 16, v92
	v_mul_f32_e32 v88, 0xbfb8aa3b, v88
	v_exp_f32_e32 v88, v88
	v_lshlrev_b32_e32 v90, 16, v93
	v_and_b32_e32 v91, 0xffff0000, v93
	v_and_b32_e32 v89, 0xffff0000, v92
	v_add_f32_e32 v88, 1.0, v88
	v_div_scale_f32 v93, s[6:7], v88, v88, 1.0
	v_rcp_f32_e32 v98, v93
	v_lshlrev_b32_e32 v92, 16, v94
	v_mul_f32_e32 v92, 0xbfb8aa3b, v92
	v_exp_f32_e32 v92, v92
	v_fma_f32 v100, -v93, v98, 1.0
	v_fmac_f32_e32 v98, v100, v98
	v_div_scale_f32 v100, vcc, 1.0, v88, 1.0
	v_mul_f32_e32 v101, v100, v98
	v_fma_f32 v102, -v93, v101, v100
	v_fmac_f32_e32 v101, v102, v98
	v_add_f32_e32 v92, 1.0, v92
	v_fma_f32 v93, -v93, v101, v100
	v_div_scale_f32 v100, s[6:7], v92, v92, 1.0
	v_rcp_f32_e32 v102, v100
	v_div_fmas_f32 v93, v93, v98, v101
	v_mul_f32_e32 v89, 0xbfb8aa3b, v89
	v_div_fixup_f32 v88, v93, v88, 1.0
	v_exp_f32_e32 v89, v89
	v_mul_f32_e32 v84, v84, v88
	v_fma_f32 v88, -v100, v102, 1.0
	v_fmac_f32_e32 v102, v88, v102
	v_div_scale_f32 v88, vcc, 1.0, v92, 1.0
	v_mul_f32_e32 v93, v88, v102
	v_fma_f32 v98, -v100, v93, v88
	v_add_f32_e32 v89, 1.0, v89
	v_fmac_f32_e32 v93, v98, v102
	v_div_scale_f32 v98, s[6:7], v89, v89, 1.0
	v_fma_f32 v88, -v100, v93, v88
	v_rcp_f32_e32 v100, v98
	v_and_b32_e32 v94, 0xffff0000, v94
	v_div_fmas_f32 v88, v88, v102, v93
	v_mul_f32_e32 v93, 0xbfb8aa3b, v94
	v_div_fixup_f32 v88, v88, v92, 1.0
	v_exp_f32_e32 v93, v93
	v_mul_f32_e32 v80, v80, v88
	v_fma_f32 v88, -v98, v100, 1.0
	v_fmac_f32_e32 v100, v88, v100
	v_div_scale_f32 v88, vcc, 1.0, v89, 1.0
	v_mul_f32_e32 v92, v88, v100
	v_fma_f32 v94, -v98, v92, v88
	v_add_f32_e32 v93, 1.0, v93
	v_fmac_f32_e32 v92, v94, v100
	v_div_scale_f32 v94, s[6:7], v93, v93, 1.0
	v_fma_f32 v88, -v98, v92, v88
	v_rcp_f32_e32 v98, v94
	v_div_fmas_f32 v88, v88, v100, v92
	v_mul_f32_e32 v90, 0xbfb8aa3b, v90
	v_div_fixup_f32 v88, v88, v89, 1.0
	v_exp_f32_e32 v90, v90
	v_mul_f32_e32 v85, v85, v88
	v_fma_f32 v88, -v94, v98, 1.0
	v_fmac_f32_e32 v98, v88, v98
	v_div_scale_f32 v88, vcc, 1.0, v93, 1.0
	v_mul_f32_e32 v89, v88, v98
	v_fma_f32 v92, -v94, v89, v88
	v_add_f32_e32 v90, 1.0, v90
	v_fmac_f32_e32 v89, v92, v98
	v_div_scale_f32 v92, s[6:7], v90, v90, 1.0
	v_fma_f32 v88, -v94, v89, v88
	v_rcp_f32_e32 v94, v92
	v_div_fmas_f32 v88, v88, v98, v89
	v_div_fixup_f32 v88, v88, v93, 1.0
	v_mul_f32_e32 v81, v81, v88
	v_fma_f32 v88, -v92, v94, 1.0
	v_mul_f32_e32 v93, 0xbfb8aa3b, v99
	v_fmac_f32_e32 v94, v88, v94
	v_div_scale_f32 v88, vcc, 1.0, v90, 1.0
	v_exp_f32_e32 v93, v93
	v_mul_f32_e32 v89, v88, v94
	v_fma_f32 v98, -v92, v89, v88
	v_fmac_f32_e32 v89, v98, v94
	v_fma_f32 v88, -v92, v89, v88
	v_add_f32_e32 v92, 1.0, v93
	v_div_scale_f32 v93, s[6:7], v92, v92, 1.0
	v_rcp_f32_e32 v98, v93
	v_div_fmas_f32 v88, v88, v94, v89
	v_div_fixup_f32 v88, v88, v90, 1.0
	v_mul_f32_e32 v90, 0xbfb8aa3b, v91
	v_exp_f32_e32 v90, v90
	v_mul_f32_e32 v86, v86, v88
	v_fma_f32 v88, -v93, v98, 1.0
	v_fmac_f32_e32 v98, v88, v98
	v_div_scale_f32 v88, vcc, 1.0, v92, 1.0
	v_mul_f32_e32 v89, v88, v98
	v_fma_f32 v91, -v93, v89, v88
	v_add_f32_e32 v90, 1.0, v90
	v_fmac_f32_e32 v89, v91, v98
	v_div_scale_f32 v91, s[6:7], v90, v90, 1.0
	v_fma_f32 v88, -v93, v89, v88
	v_rcp_f32_e32 v93, v91
	v_div_fmas_f32 v88, v88, v98, v89
	v_div_fixup_f32 v88, v88, v92, 1.0
	v_mul_f32_e32 v88, v82, v88
	v_fma_f32 v82, -v91, v93, 1.0
	v_mul_f32_e32 v92, 0xbfb8aa3b, v95
	v_fmac_f32_e32 v93, v82, v93
	v_div_scale_f32 v82, vcc, 1.0, v90, 1.0
	v_exp_f32_e32 v92, v92
	v_mul_f32_e32 v89, v82, v93
	v_fma_f32 v94, -v91, v89, v82
	v_fmac_f32_e32 v89, v94, v93
	v_fma_f32 v82, -v91, v89, v82
	v_add_f32_e32 v91, 1.0, v92
	v_div_scale_f32 v92, s[6:7], v91, v91, 1.0
	v_rcp_f32_e32 v94, v92
	v_div_fmas_f32 v82, v82, v93, v89
	v_div_fixup_f32 v82, v82, v90, 1.0
	v_mul_f32_e32 v87, v87, v82
	v_fma_f32 v82, -v92, v94, 1.0
	v_fmac_f32_e32 v94, v82, v94
	v_div_scale_f32 v82, vcc, 1.0, v91, 1.0
	v_mul_f32_e32 v89, v82, v94
	v_fma_f32 v90, -v92, v89, v82
	v_fmac_f32_e32 v89, v90, v94
	v_fma_f32 v82, -v92, v89, v82
	v_div_fmas_f32 v82, v82, v94, v89
	v_div_fixup_f32 v82, v82, v91, 1.0
	v_mul_f32_e32 v89, v83, v82
	v_cvt_pk_bf16_f32 v82, v84, v85
	v_cvt_pk_bf16_f32 v83, v86, v87
	v_cvt_pk_bf16_f32 v84, v80, v81
	v_or_b32_e32 v80, 48, v160
	v_mad_i64_i32 v[80:81], s[6:7], v80, s57, v[146:147]
	v_lshl_add_u64 v[80:81], v[80:81], 0, v[148:149]
	v_add_co_u32_e32 v90, vcc, s58, v80
	v_cvt_pk_bf16_f32 v85, v88, v89
	global_store_dwordx4 v[96:97], v[82:85], off offset:256
	s_nop 0
	v_addc_co_u32_e32 v91, vcc, 0, v81, vcc
	s_waitcnt vmcnt(15)
; __device__ __forceinline__ u32x4 pack8(const f32x4 v0, const f32x4 v1) { u32x4 w; w.x = pk2(v0[0], v0[1]); w.y = pk2(v0[2], v0[3]); w.z = pk2(v1[0], v1[1]); w.w = pk2(v1[2], v1[3]); return w; }
; __device__ __forceinline__ void unpack8(const u32x4 w, f32x4& v0, f32x4& v1) { v0 = (f32x4){bflo(w.x), bfhi(w.x), bflo(w.y), bfhi(w.y)}; v1 = (f32x4){bflo(w.z), bfhi(w.z), bflo(w.w), bfhi(w.w)}; }
; __device__ __forceinline__ float sigmoidf_(float x) { return 1.0f / (1.0f + __expf(-x)); }
;     __device__ __forceinline__ void operator()(const f32x4 (&acc)[2][2][4][2], const Unit& u, int wr, int wc, int fr, int fq) const {
;     ...
;                 bf16_t* rowp = z + (size_t)(row0 + ai * 128 + m * 16) * DIN + col0;
; #pragma unroll
;                 for (int bj = 0; bj < 2; ++bj) {
;                     const u32x4 gw = *(const u32x4*)(rowp + (MODE == 0 ? O_GB : O_GA) + bj * 128);
;                     f32x4 g0, g1; unpack8(gw, g0, g1);
;                     f32x4 v0, v1;
; #pragma unroll
;                     for (int j = 0; j < 4; ++j) { v0[j] = sigmoidf_(g0[j]) * acc[ai][bj][m][0][j]; v1[j] = sigmoidf_(g1[j]) * acc[ai][bj][m][1][j]; }
;                     if (MODE == 1) { const u32x4 mw = *(const u32x4*)(rowp + bj * 128); f32x4 m0, m1; unpack8(mw, m0, m1); v0 += m0; v1 += m1; }
;                     *(u32x4*)(rowp + bj * 128) = pack8(v0, v1); }
	v_mov_b32_e32 v86, v236
	v_mov_b32_e32 v87, v237
	v_mov_b32_e32 v88, v238
	v_mov_b32_e32 v89, v239
	v_lshlrev_b32_e32 v82, 16, v86
	v_mul_f32_e32 v82, 0xbfb8aa3b, v82
	v_exp_f32_e32 v82, v82
	v_lshlrev_b32_e32 v84, 16, v87
	v_and_b32_e32 v85, 0xffff0000, v87
	v_and_b32_e32 v83, 0xffff0000, v86
	v_add_f32_e32 v82, 1.0, v82
	v_div_scale_f32 v87, s[6:7], v82, v82, 1.0
	v_rcp_f32_e32 v92, v87
	v_lshlrev_b32_e32 v86, 16, v88
	v_mul_f32_e32 v86, 0xbfb8aa3b, v86
	v_exp_f32_e32 v86, v86
	v_fma_f32 v94, -v87, v92, 1.0
	v_fmac_f32_e32 v92, v94, v92
	v_div_scale_f32 v94, vcc, 1.0, v82, 1.0
	v_mul_f32_e32 v95, v94, v92
	v_fma_f32 v96, -v87, v95, v94
	v_fmac_f32_e32 v95, v96, v92
	v_add_f32_e32 v86, 1.0, v86
	v_fma_f32 v87, -v87, v95, v94
	v_div_scale_f32 v94, s[6:7], v86, v86, 1.0
	v_rcp_f32_e32 v96, v94
	v_div_fmas_f32 v87, v87, v92, v95
	v_mul_f32_e32 v83, 0xbfb8aa3b, v83
	v_div_fixup_f32 v82, v87, v82, 1.0
	v_exp_f32_e32 v83, v83
	v_mul_f32_e32 v76, v76, v82
	v_fma_f32 v82, -v94, v96, 1.0
	v_fmac_f32_e32 v96, v82, v96
	v_div_scale_f32 v82, vcc, 1.0, v86, 1.0
	v_mul_f32_e32 v87, v82, v96
	v_fma_f32 v92, -v94, v87, v82
	v_add_f32_e32 v83, 1.0, v83
	v_fmac_f32_e32 v87, v92, v96
	v_div_scale_f32 v92, s[6:7], v83, v83, 1.0
	v_fma_f32 v82, -v94, v87, v82
	v_rcp_f32_e32 v94, v92
	v_and_b32_e32 v88, 0xffff0000, v88
	v_div_fmas_f32 v82, v82, v96, v87
	v_mul_f32_e32 v87, 0xbfb8aa3b, v88
	v_div_fixup_f32 v82, v82, v86, 1.0
	v_exp_f32_e32 v87, v87
	v_mul_f32_e32 v82, v72, v82
	v_fma_f32 v72, -v92, v94, 1.0
	v_fmac_f32_e32 v94, v72, v94
	v_div_scale_f32 v72, vcc, 1.0, v83, 1.0
	v_mul_f32_e32 v86, v72, v94
	v_fma_f32 v88, -v92, v86, v72
	v_add_f32_e32 v87, 1.0, v87
	v_fmac_f32_e32 v86, v88, v94
	v_div_scale_f32 v88, s[6:7], v87, v87, 1.0
	v_fma_f32 v72, -v92, v86, v72
	v_rcp_f32_e32 v92, v88
	v_div_fmas_f32 v72, v72, v94, v86
	v_mul_f32_e32 v84, 0xbfb8aa3b, v84
	v_div_fixup_f32 v72, v72, v83, 1.0
	v_exp_f32_e32 v84, v84
	v_mul_f32_e32 v72, v77, v72
	v_fma_f32 v77, -v88, v92, 1.0
	v_fmac_f32_e32 v92, v77, v92
	v_div_scale_f32 v77, vcc, 1.0, v87, 1.0
	v_mul_f32_e32 v83, v77, v92
	v_fma_f32 v86, -v88, v83, v77
	v_add_f32_e32 v84, 1.0, v84
	v_fmac_f32_e32 v83, v86, v92
	v_div_scale_f32 v86, s[6:7], v84, v84, 1.0
	v_fma_f32 v77, -v88, v83, v77
	v_rcp_f32_e32 v88, v86
	v_div_fmas_f32 v77, v77, v92, v83
	v_lshlrev_b32_e32 v93, 16, v89
	v_div_fixup_f32 v77, v77, v87, 1.0
	v_mul_f32_e32 v77, v73, v77
	v_fma_f32 v73, -v86, v88, 1.0
	v_mul_f32_e32 v87, 0xbfb8aa3b, v93
	v_fmac_f32_e32 v88, v73, v88
	v_div_scale_f32 v73, vcc, 1.0, v84, 1.0
	v_exp_f32_e32 v87, v87
	v_mul_f32_e32 v83, v73, v88
	v_fma_f32 v92, -v86, v83, v73
	v_fmac_f32_e32 v83, v92, v88
	v_fma_f32 v73, -v86, v83, v73
	v_add_f32_e32 v86, 1.0, v87
	v_div_scale_f32 v87, s[6:7], v86, v86, 1.0
	v_rcp_f32_e32 v92, v87
	v_div_fmas_f32 v73, v73, v88, v83
	v_div_fixup_f32 v73, v73, v84, 1.0
	v_mul_f32_e32 v84, 0xbfb8aa3b, v85
	v_exp_f32_e32 v84, v84
	v_mul_f32_e32 v73, v78, v73
	v_fma_f32 v78, -v87, v92, 1.0
	v_fmac_f32_e32 v92, v78, v92
	v_div_scale_f32 v78, vcc, 1.0, v86, 1.0
	v_mul_f32_e32 v83, v78, v92
	v_fma_f32 v85, -v87, v83, v78
	v_add_f32_e32 v84, 1.0, v84
	v_fmac_f32_e32 v83, v85, v92
	v_div_scale_f32 v85, s[6:7], v84, v84, 1.0
	v_fma_f32 v78, -v87, v83, v78
	v_rcp_f32_e32 v87, v85
	v_div_fmas_f32 v78, v78, v92, v83
	v_and_b32_e32 v89, 0xffff0000, v89
	v_div_fixup_f32 v78, v78, v86, 1.0
	v_mul_f32_e32 v78, v74, v78
	v_fma_f32 v74, -v85, v87, 1.0
	v_mul_f32_e32 v86, 0xbfb8aa3b, v89
	v_fmac_f32_e32 v87, v74, v87
	v_div_scale_f32 v74, vcc, 1.0, v84, 1.0
	v_exp_f32_e32 v86, v86
	v_mul_f32_e32 v83, v74, v87
	v_fma_f32 v88, -v85, v83, v74
	v_fmac_f32_e32 v83, v88, v87
	v_fma_f32 v74, -v85, v83, v74
	v_add_f32_e32 v85, 1.0, v86
	v_div_scale_f32 v86, s[6:7], v85, v85, 1.0
	v_rcp_f32_e32 v88, v86
	v_div_fmas_f32 v74, v74, v87, v83
	v_div_fixup_f32 v74, v74, v84, 1.0
	v_mul_f32_e32 v74, v79, v74
	v_fma_f32 v79, -v86, v88, 1.0
	v_fmac_f32_e32 v88, v79, v88
	v_div_scale_f32 v79, vcc, 1.0, v85, 1.0
	v_mul_f32_e32 v83, v79, v88
	v_fma_f32 v84, -v86, v83, v79
	v_fmac_f32_e32 v83, v84, v88
	v_fma_f32 v79, -v86, v83, v79
	v_div_fmas_f32 v79, v79, v88, v83
	v_div_fixup_f32 v79, v79, v85, 1.0
	v_mul_f32_e32 v75, v75, v79
	v_cvt_pk_bf16_f32 v72, v76, v72
	v_cvt_pk_bf16_f32 v73, v73, v74
	v_cvt_pk_bf16_f32 v74, v82, v77
	v_cvt_pk_bf16_f32 v75, v78, v75
	s_waitcnt vmcnt(14)
; __device__ __forceinline__ u32x4 pack8(const f32x4 v0, const f32x4 v1) { u32x4 w; w.x = pk2(v0[0], v0[1]); w.y = pk2(v0[2], v0[3]); w.z = pk2(v1[0], v1[1]); w.w = pk2(v1[2], v1[3]); return w; }
; __device__ __forceinline__ void unpack8(const u32x4 w, f32x4& v0, f32x4& v1) { v0 = (f32x4){bflo(w.x), bfhi(w.x), bflo(w.y), bfhi(w.y)}; v1 = (f32x4){bflo(w.z), bfhi(w.z), bflo(w.w), bfhi(w.w)}; }
; __device__ __forceinline__ float sigmoidf_(float x) { return 1.0f / (1.0f + __expf(-x)); }
;     __device__ __forceinline__ void operator()(const f32x4 (&acc)[2][2][4][2], const Unit& u, int wr, int wc, int fr, int fq) const {
;     ...
;                 bf16_t* rowp = z + (size_t)(row0 + ai * 128 + m * 16) * DIN + col0;
; #pragma unroll
;                 for (int bj = 0; bj < 2; ++bj) {
;                     const u32x4 gw = *(const u32x4*)(rowp + (MODE == 0 ? O_GB : O_GA) + bj * 128);
;                     f32x4 g0, g1; unpack8(gw, g0, g1);
;                     f32x4 v0, v1;
; #pragma unroll
;                     for (int j = 0; j < 4; ++j) { v0[j] = sigmoidf_(g0[j]) * acc[ai][bj][m][0][j]; v1[j] = sigmoidf_(g1[j]) * acc[ai][bj][m][1][j]; }
;                     if (MODE == 1) { const u32x4 mw = *(const u32x4*)(rowp + bj * 128); f32x4 m0, m1; unpack8(mw, m0, m1); v0 += m0; v1 += m1; }
;                     *(u32x4*)(rowp + bj * 128) = pack8(v0, v1); }
	v_mov_b32_e32 v76, v240
	v_mov_b32_e32 v77, v241
	v_mov_b32_e32 v78, v242
	v_mov_b32_e32 v79, v243
	v_lshlrev_b32_e32 v83, 16, v79
	global_store_dwordx4 v[80:81], v[72:75], off
	v_and_b32_e32 v79, 0xffff0000, v79
	s_nop 0
	v_lshlrev_b32_e32 v72, 16, v76
	v_mul_f32_e32 v72, 0xbfb8aa3b, v72
	v_exp_f32_e32 v72, v72
	v_lshlrev_b32_e32 v74, 16, v77
	v_and_b32_e32 v75, 0xffff0000, v77
	v_and_b32_e32 v73, 0xffff0000, v76
	v_add_f32_e32 v72, 1.0, v72
	v_div_scale_f32 v77, s[6:7], v72, v72, 1.0
	v_rcp_f32_e32 v82, v77
	v_lshlrev_b32_e32 v76, 16, v78
	v_mul_f32_e32 v76, 0xbfb8aa3b, v76
	v_exp_f32_e32 v76, v76
	v_fma_f32 v84, -v77, v82, 1.0
	v_fmac_f32_e32 v82, v84, v82
	v_div_scale_f32 v84, vcc, 1.0, v72, 1.0
	v_mul_f32_e32 v85, v84, v82
	v_fma_f32 v86, -v77, v85, v84
	v_fmac_f32_e32 v85, v86, v82
	v_add_f32_e32 v76, 1.0, v76
	v_fma_f32 v77, -v77, v85, v84
	v_div_scale_f32 v84, s[6:7], v76, v76, 1.0
	v_rcp_f32_e32 v86, v84
	v_div_fmas_f32 v77, v77, v82, v85
	v_mul_f32_e32 v73, 0xbfb8aa3b, v73
	v_div_fixup_f32 v72, v77, v72, 1.0
	v_exp_f32_e32 v73, v73
	v_mul_f32_e32 v68, v68, v72
	v_fma_f32 v72, -v84, v86, 1.0
	v_fmac_f32_e32 v86, v72, v86
	v_div_scale_f32 v72, vcc, 1.0, v76, 1.0
	v_mul_f32_e32 v77, v72, v86
	v_fma_f32 v82, -v84, v77, v72
	v_add_f32_e32 v73, 1.0, v73
	v_fmac_f32_e32 v77, v82, v86
	v_div_scale_f32 v82, s[6:7], v73, v73, 1.0
	v_fma_f32 v72, -v84, v77, v72
	v_rcp_f32_e32 v84, v82
	v_and_b32_e32 v78, 0xffff0000, v78
	v_div_fmas_f32 v72, v72, v86, v77
	v_mul_f32_e32 v77, 0xbfb8aa3b, v78
	v_div_fixup_f32 v72, v72, v76, 1.0
	v_exp_f32_e32 v77, v77
	v_mul_f32_e32 v64, v64, v72
	v_fma_f32 v72, -v82, v84, 1.0
	v_fmac_f32_e32 v84, v72, v84
	v_div_scale_f32 v72, vcc, 1.0, v73, 1.0
	v_mul_f32_e32 v76, v72, v84
	v_fma_f32 v78, -v82, v76, v72
	v_add_f32_e32 v77, 1.0, v77
	v_fmac_f32_e32 v76, v78, v84
	v_div_scale_f32 v78, s[6:7], v77, v77, 1.0
	v_fma_f32 v72, -v82, v76, v72
	v_rcp_f32_e32 v82, v78
	v_div_fmas_f32 v72, v72, v84, v76
	v_mul_f32_e32 v74, 0xbfb8aa3b, v74
	v_div_fixup_f32 v72, v72, v73, 1.0
	v_exp_f32_e32 v74, v74
	v_mul_f32_e32 v69, v69, v72
	v_fma_f32 v72, -v78, v82, 1.0
	v_fmac_f32_e32 v82, v72, v82
	v_div_scale_f32 v72, vcc, 1.0, v77, 1.0
	v_mul_f32_e32 v73, v72, v82
	v_fma_f32 v76, -v78, v73, v72
	v_add_f32_e32 v74, 1.0, v74
	v_fmac_f32_e32 v73, v76, v82
	v_div_scale_f32 v76, s[6:7], v74, v74, 1.0
	v_fma_f32 v72, -v78, v73, v72
	v_rcp_f32_e32 v78, v76
	v_div_fmas_f32 v72, v72, v82, v73
	v_div_fixup_f32 v72, v72, v77, 1.0
	v_mul_f32_e32 v65, v65, v72
	v_fma_f32 v72, -v76, v78, 1.0
	v_mul_f32_e32 v77, 0xbfb8aa3b, v83
	v_fmac_f32_e32 v78, v72, v78
	v_div_scale_f32 v72, vcc, 1.0, v74, 1.0
	v_exp_f32_e32 v77, v77
	v_mul_f32_e32 v73, v72, v78
	v_fma_f32 v82, -v76, v73, v72
	v_fmac_f32_e32 v73, v82, v78
	v_fma_f32 v72, -v76, v73, v72
	v_add_f32_e32 v76, 1.0, v77
	v_div_scale_f32 v77, s[6:7], v76, v76, 1.0
	v_rcp_f32_e32 v82, v77
	v_div_fmas_f32 v72, v72, v78, v73
	v_div_fixup_f32 v72, v72, v74, 1.0
	v_mul_f32_e32 v74, 0xbfb8aa3b, v75
	v_exp_f32_e32 v74, v74
	v_mul_f32_e32 v70, v70, v72
	v_fma_f32 v72, -v77, v82, 1.0
	v_fmac_f32_e32 v82, v72, v82
	v_div_scale_f32 v72, vcc, 1.0, v76, 1.0
	v_mul_f32_e32 v73, v72, v82
	v_fma_f32 v75, -v77, v73, v72
	v_add_f32_e32 v74, 1.0, v74
	v_fmac_f32_e32 v73, v75, v82
	v_div_scale_f32 v75, s[6:7], v74, v74, 1.0
	v_fma_f32 v72, -v77, v73, v72
	v_rcp_f32_e32 v77, v75
	v_div_fmas_f32 v72, v72, v82, v73
	v_div_fixup_f32 v72, v72, v76, 1.0
	v_mul_f32_e32 v72, v66, v72
	v_fma_f32 v66, -v75, v77, 1.0
	v_mul_f32_e32 v76, 0xbfb8aa3b, v79
	v_fmac_f32_e32 v77, v66, v77
	v_div_scale_f32 v66, vcc, 1.0, v74, 1.0
	v_exp_f32_e32 v76, v76
	v_mul_f32_e32 v73, v66, v77
	v_fma_f32 v78, -v75, v73, v66
	v_fmac_f32_e32 v73, v78, v77
	v_fma_f32 v66, -v75, v73, v66
	v_add_f32_e32 v75, 1.0, v76
	v_div_scale_f32 v76, s[6:7], v75, v75, 1.0
	v_rcp_f32_e32 v78, v76
	v_div_fmas_f32 v66, v66, v77, v73
	v_div_fixup_f32 v66, v66, v74, 1.0
	v_mul_f32_e32 v71, v71, v66
	v_fma_f32 v66, -v76, v78, 1.0
	v_fmac_f32_e32 v78, v66, v78
	v_div_scale_f32 v66, vcc, 1.0, v75, 1.0
	v_mul_f32_e32 v73, v66, v78
	v_fma_f32 v74, -v76, v73, v66
	v_fmac_f32_e32 v73, v74, v78
	v_fma_f32 v66, -v76, v73, v66
	v_div_fmas_f32 v66, v66, v78, v73
	v_div_fixup_f32 v66, v66, v75, 1.0
	v_mul_f32_e32 v73, v67, v66
	v_cvt_pk_bf16_f32 v66, v68, v69
	v_cvt_pk_bf16_f32 v67, v70, v71
	v_cvt_pk_bf16_f32 v68, v64, v65
	v_add_u32_e32 v64, 0x80, v160
	v_mad_i64_i32 v[64:65], s[6:7], v64, s57, v[146:147]
	v_lshl_add_u64 v[64:65], v[64:65], 0, v[148:149]
	v_add_co_u32_e32 v74, vcc, s58, v64
	v_cvt_pk_bf16_f32 v69, v72, v73
	global_store_dwordx4 v[80:81], v[66:69], off offset:256
	s_nop 0
	v_addc_co_u32_e32 v75, vcc, 0, v65, vcc
	s_waitcnt vmcnt(15)
; __device__ __forceinline__ u32x4 pack8(const f32x4 v0, const f32x4 v1) { u32x4 w; w.x = pk2(v0[0], v0[1]); w.y = pk2(v0[2], v0[3]); w.z = pk2(v1[0], v1[1]); w.w = pk2(v1[2], v1[3]); return w; }
; __device__ __forceinline__ void unpack8(const u32x4 w, f32x4& v0, f32x4& v1) { v0 = (f32x4){bflo(w.x), bfhi(w.x), bflo(w.y), bfhi(w.y)}; v1 = (f32x4){bflo(w.z), bfhi(w.z), bflo(w.w), bfhi(w.w)}; }
; __device__ __forceinline__ float sigmoidf_(float x) { return 1.0f / (1.0f + __expf(-x)); }
;     __device__ __forceinline__ void operator()(const f32x4 (&acc)[2][2][4][2], const Unit& u, int wr, int wc, int fr, int fq) const {
;     ...
;                 bf16_t* rowp = z + (size_t)(row0 + ai * 128 + m * 16) * DIN + col0;
; #pragma unroll
;                 for (int bj = 0; bj < 2; ++bj) {
;                     const u32x4 gw = *(const u32x4*)(rowp + (MODE == 0 ? O_GB : O_GA) + bj * 128);
;                     f32x4 g0, g1; unpack8(gw, g0, g1);
;                     f32x4 v0, v1;
; #pragma unroll
;                     for (int j = 0; j < 4; ++j) { v0[j] = sigmoidf_(g0[j]) * acc[ai][bj][m][0][j]; v1[j] = sigmoidf_(g1[j]) * acc[ai][bj][m][1][j]; }
;                     if (MODE == 1) { const u32x4 mw = *(const u32x4*)(rowp + bj * 128); f32x4 m0, m1; unpack8(mw, m0, m1); v0 += m0; v1 += m1; }
;                     *(u32x4*)(rowp + bj * 128) = pack8(v0, v1); }
	v_mov_b32_e32 v70, v244
	v_mov_b32_e32 v71, v245
	v_mov_b32_e32 v72, v246
	v_mov_b32_e32 v73, v247
	v_lshlrev_b32_e32 v66, 16, v70
	v_mul_f32_e32 v66, 0xbfb8aa3b, v66
	v_exp_f32_e32 v66, v66
	v_lshlrev_b32_e32 v68, 16, v71
	v_and_b32_e32 v69, 0xffff0000, v71
	v_and_b32_e32 v67, 0xffff0000, v70
	v_add_f32_e32 v66, 1.0, v66
	v_div_scale_f32 v71, s[6:7], v66, v66, 1.0
	v_rcp_f32_e32 v76, v71
	v_lshlrev_b32_e32 v70, 16, v72
	v_mul_f32_e32 v70, 0xbfb8aa3b, v70
	v_exp_f32_e32 v70, v70
	v_fma_f32 v78, -v71, v76, 1.0
	v_fmac_f32_e32 v76, v78, v76
	v_div_scale_f32 v78, vcc, 1.0, v66, 1.0
	v_mul_f32_e32 v79, v78, v76
	v_fma_f32 v80, -v71, v79, v78
	v_fmac_f32_e32 v79, v80, v76
	v_add_f32_e32 v70, 1.0, v70
	v_fma_f32 v71, -v71, v79, v78
	v_div_scale_f32 v78, s[6:7], v70, v70, 1.0
	v_rcp_f32_e32 v80, v78
	v_div_fmas_f32 v71, v71, v76, v79
	v_mul_f32_e32 v67, 0xbfb8aa3b, v67
	v_div_fixup_f32 v66, v71, v66, 1.0
	v_exp_f32_e32 v67, v67
	v_mul_f32_e32 v60, v60, v66
	v_fma_f32 v66, -v78, v80, 1.0
	v_fmac_f32_e32 v80, v66, v80
	v_div_scale_f32 v66, vcc, 1.0, v70, 1.0
	v_mul_f32_e32 v71, v66, v80
	v_fma_f32 v76, -v78, v71, v66
	v_add_f32_e32 v67, 1.0, v67
	v_fmac_f32_e32 v71, v76, v80
	v_div_scale_f32 v76, s[6:7], v67, v67, 1.0
	v_fma_f32 v66, -v78, v71, v66
	v_rcp_f32_e32 v78, v76
	v_and_b32_e32 v72, 0xffff0000, v72
	v_div_fmas_f32 v66, v66, v80, v71
	v_mul_f32_e32 v71, 0xbfb8aa3b, v72
	v_div_fixup_f32 v66, v66, v70, 1.0
	v_exp_f32_e32 v71, v71
	v_mul_f32_e32 v66, v56, v66
	v_fma_f32 v56, -v76, v78, 1.0
	v_fmac_f32_e32 v78, v56, v78
	v_div_scale_f32 v56, vcc, 1.0, v67, 1.0
	v_mul_f32_e32 v70, v56, v78
	v_fma_f32 v72, -v76, v70, v56
	v_add_f32_e32 v71, 1.0, v71
	v_fmac_f32_e32 v70, v72, v78
	v_div_scale_f32 v72, s[6:7], v71, v71, 1.0
	v_fma_f32 v56, -v76, v70, v56
	v_rcp_f32_e32 v76, v72
	v_div_fmas_f32 v56, v56, v78, v70
	v_mul_f32_e32 v68, 0xbfb8aa3b, v68
	v_div_fixup_f32 v56, v56, v67, 1.0
	v_exp_f32_e32 v68, v68
	v_mul_f32_e32 v56, v61, v56
	v_fma_f32 v61, -v72, v76, 1.0
	v_fmac_f32_e32 v76, v61, v76
	v_div_scale_f32 v61, vcc, 1.0, v71, 1.0
	v_mul_f32_e32 v67, v61, v76
	v_fma_f32 v70, -v72, v67, v61
	v_add_f32_e32 v68, 1.0, v68
	v_fmac_f32_e32 v67, v70, v76
	v_div_scale_f32 v70, s[6:7], v68, v68, 1.0
	v_fma_f32 v61, -v72, v67, v61
	v_rcp_f32_e32 v72, v70
	v_div_fmas_f32 v61, v61, v76, v67
	v_lshlrev_b32_e32 v77, 16, v73
	v_div_fixup_f32 v61, v61, v71, 1.0
	v_mul_f32_e32 v61, v57, v61
	v_fma_f32 v57, -v70, v72, 1.0
	v_mul_f32_e32 v71, 0xbfb8aa3b, v77
	v_fmac_f32_e32 v72, v57, v72
	v_div_scale_f32 v57, vcc, 1.0, v68, 1.0
	v_exp_f32_e32 v71, v71
	v_mul_f32_e32 v67, v57, v72
	v_fma_f32 v76, -v70, v67, v57
	v_fmac_f32_e32 v67, v76, v72
	v_fma_f32 v57, -v70, v67, v57
	v_add_f32_e32 v70, 1.0, v71
	v_div_scale_f32 v71, s[6:7], v70, v70, 1.0
	v_rcp_f32_e32 v76, v71
	v_div_fmas_f32 v57, v57, v72, v67
	v_div_fixup_f32 v57, v57, v68, 1.0
	v_mul_f32_e32 v68, 0xbfb8aa3b, v69
	v_exp_f32_e32 v68, v68
	v_mul_f32_e32 v57, v62, v57
	v_fma_f32 v62, -v71, v76, 1.0
	v_fmac_f32_e32 v76, v62, v76
	v_div_scale_f32 v62, vcc, 1.0, v70, 1.0
	v_mul_f32_e32 v67, v62, v76
	v_fma_f32 v69, -v71, v67, v62
	v_add_f32_e32 v68, 1.0, v68
	v_fmac_f32_e32 v67, v69, v76
	v_div_scale_f32 v69, s[6:7], v68, v68, 1.0
	v_fma_f32 v62, -v71, v67, v62
	v_rcp_f32_e32 v71, v69
	v_div_fmas_f32 v62, v62, v76, v67
	v_and_b32_e32 v73, 0xffff0000, v73
	v_div_fixup_f32 v62, v62, v70, 1.0
	v_mul_f32_e32 v62, v58, v62
	v_fma_f32 v58, -v69, v71, 1.0
	v_mul_f32_e32 v70, 0xbfb8aa3b, v73
	v_fmac_f32_e32 v71, v58, v71
	v_div_scale_f32 v58, vcc, 1.0, v68, 1.0
	v_exp_f32_e32 v70, v70
	v_mul_f32_e32 v67, v58, v71
	v_fma_f32 v72, -v69, v67, v58
	v_fmac_f32_e32 v67, v72, v71
	v_fma_f32 v58, -v69, v67, v58
	v_add_f32_e32 v69, 1.0, v70
	v_div_scale_f32 v70, s[6:7], v69, v69, 1.0
	v_rcp_f32_e32 v72, v70
	v_div_fmas_f32 v58, v58, v71, v67
	v_div_fixup_f32 v58, v58, v68, 1.0
	v_mul_f32_e32 v58, v63, v58
	v_fma_f32 v63, -v70, v72, 1.0
	v_fmac_f32_e32 v72, v63, v72
	v_div_scale_f32 v63, vcc, 1.0, v69, 1.0
	v_mul_f32_e32 v67, v63, v72
	v_fma_f32 v68, -v70, v67, v63
	v_fmac_f32_e32 v67, v68, v72
	v_fma_f32 v63, -v70, v67, v63
	v_div_fmas_f32 v63, v63, v72, v67
	v_div_fixup_f32 v63, v63, v69, 1.0
	v_mul_f32_e32 v59, v59, v63
	v_cvt_pk_bf16_f32 v56, v60, v56
	v_cvt_pk_bf16_f32 v57, v57, v58
	v_cvt_pk_bf16_f32 v58, v66, v61
	v_cvt_pk_bf16_f32 v59, v62, v59
	s_waitcnt vmcnt(14)
; __device__ __forceinline__ u32x4 pack8(const f32x4 v0, const f32x4 v1) { u32x4 w; w.x = pk2(v0[0], v0[1]); w.y = pk2(v0[2], v0[3]); w.z = pk2(v1[0], v1[1]); w.w = pk2(v1[2], v1[3]); return w; }
; __device__ __forceinline__ void unpack8(const u32x4 w, f32x4& v0, f32x4& v1) { v0 = (f32x4){bflo(w.x), bfhi(w.x), bflo(w.y), bfhi(w.y)}; v1 = (f32x4){bflo(w.z), bfhi(w.z), bflo(w.w), bfhi(w.w)}; }
; __device__ __forceinline__ float sigmoidf_(float x) { return 1.0f / (1.0f + __expf(-x)); }
;     __device__ __forceinline__ void operator()(const f32x4 (&acc)[2][2][4][2], const Unit& u, int wr, int wc, int fr, int fq) const {
;     ...
;                 bf16_t* rowp = z + (size_t)(row0 + ai * 128 + m * 16) * DIN + col0;
; #pragma unroll
;                 for (int bj = 0; bj < 2; ++bj) {
;                     const u32x4 gw = *(const u32x4*)(rowp + (MODE == 0 ? O_GB : O_GA) + bj * 128);
;                     f32x4 g0, g1; unpack8(gw, g0, g1);
;                     f32x4 v0, v1;
; #pragma unroll
;                     for (int j = 0; j < 4; ++j) { v0[j] = sigmoidf_(g0[j]) * acc[ai][bj][m][0][j]; v1[j] = sigmoidf_(g1[j]) * acc[ai][bj][m][1][j]; }
;                     if (MODE == 1) { const u32x4 mw = *(const u32x4*)(rowp + bj * 128); f32x4 m0, m1; unpack8(mw, m0, m1); v0 += m0; v1 += m1; }
;                     *(u32x4*)(rowp + bj * 128) = pack8(v0, v1); }
	v_mov_b32_e32 v60, v248
	v_mov_b32_e32 v61, v249
	v_mov_b32_e32 v62, v250
	v_mov_b32_e32 v63, v251
	v_lshlrev_b32_e32 v67, 16, v63
	global_store_dwordx4 v[64:65], v[56:59], off
	v_and_b32_e32 v63, 0xffff0000, v63
	s_nop 0
	v_lshlrev_b32_e32 v56, 16, v60
	v_mul_f32_e32 v56, 0xbfb8aa3b, v56
	v_exp_f32_e32 v56, v56
	v_lshlrev_b32_e32 v58, 16, v61
	v_and_b32_e32 v59, 0xffff0000, v61
	v_and_b32_e32 v57, 0xffff0000, v60
	v_add_f32_e32 v56, 1.0, v56
	v_div_scale_f32 v61, s[6:7], v56, v56, 1.0
	v_rcp_f32_e32 v66, v61
	v_lshlrev_b32_e32 v60, 16, v62
	v_mul_f32_e32 v60, 0xbfb8aa3b, v60
	v_exp_f32_e32 v60, v60
	v_fma_f32 v68, -v61, v66, 1.0
	v_fmac_f32_e32 v66, v68, v66
	v_div_scale_f32 v68, vcc, 1.0, v56, 1.0
	v_mul_f32_e32 v69, v68, v66
	v_fma_f32 v70, -v61, v69, v68
	v_fmac_f32_e32 v69, v70, v66
	v_add_f32_e32 v60, 1.0, v60
	v_fma_f32 v61, -v61, v69, v68
	v_div_scale_f32 v68, s[6:7], v60, v60, 1.0
	v_rcp_f32_e32 v70, v68
	v_div_fmas_f32 v61, v61, v66, v69
	v_mul_f32_e32 v57, 0xbfb8aa3b, v57
	v_div_fixup_f32 v56, v61, v56, 1.0
	v_exp_f32_e32 v57, v57
	v_mul_f32_e32 v52, v52, v56
	v_fma_f32 v56, -v68, v70, 1.0
	v_fmac_f32_e32 v70, v56, v70
	v_div_scale_f32 v56, vcc, 1.0, v60, 1.0
	v_mul_f32_e32 v61, v56, v70
	v_fma_f32 v66, -v68, v61, v56
	v_add_f32_e32 v57, 1.0, v57
	v_fmac_f32_e32 v61, v66, v70
	v_div_scale_f32 v66, s[6:7], v57, v57, 1.0
	v_fma_f32 v56, -v68, v61, v56
	v_rcp_f32_e32 v68, v66
	v_and_b32_e32 v62, 0xffff0000, v62
	v_div_fmas_f32 v56, v56, v70, v61
	v_mul_f32_e32 v61, 0xbfb8aa3b, v62
	v_div_fixup_f32 v56, v56, v60, 1.0
	v_exp_f32_e32 v61, v61
	v_mul_f32_e32 v48, v48, v56
	v_fma_f32 v56, -v66, v68, 1.0
	v_fmac_f32_e32 v68, v56, v68
	v_div_scale_f32 v56, vcc, 1.0, v57, 1.0
	v_mul_f32_e32 v60, v56, v68
	v_fma_f32 v62, -v66, v60, v56
	v_add_f32_e32 v61, 1.0, v61
	v_fmac_f32_e32 v60, v62, v68
	v_div_scale_f32 v62, s[6:7], v61, v61, 1.0
	v_fma_f32 v56, -v66, v60, v56
	v_rcp_f32_e32 v66, v62
	v_div_fmas_f32 v56, v56, v68, v60
	v_mul_f32_e32 v58, 0xbfb8aa3b, v58
	v_div_fixup_f32 v56, v56, v57, 1.0
	v_exp_f32_e32 v58, v58
	v_mul_f32_e32 v53, v53, v56
	v_fma_f32 v56, -v62, v66, 1.0
	v_fmac_f32_e32 v66, v56, v66
	v_div_scale_f32 v56, vcc, 1.0, v61, 1.0
	v_mul_f32_e32 v57, v56, v66
	v_fma_f32 v60, -v62, v57, v56
	v_add_f32_e32 v58, 1.0, v58
	v_fmac_f32_e32 v57, v60, v66
	v_div_scale_f32 v60, s[6:7], v58, v58, 1.0
	v_fma_f32 v56, -v62, v57, v56
	v_rcp_f32_e32 v62, v60
	v_div_fmas_f32 v56, v56, v66, v57
	v_div_fixup_f32 v56, v56, v61, 1.0
	v_mul_f32_e32 v49, v49, v56
	v_fma_f32 v56, -v60, v62, 1.0
	v_mul_f32_e32 v61, 0xbfb8aa3b, v67
	v_fmac_f32_e32 v62, v56, v62
	v_div_scale_f32 v56, vcc, 1.0, v58, 1.0
	v_exp_f32_e32 v61, v61
	v_mul_f32_e32 v57, v56, v62
	v_fma_f32 v66, -v60, v57, v56
	v_fmac_f32_e32 v57, v66, v62
	v_fma_f32 v56, -v60, v57, v56
	v_add_f32_e32 v60, 1.0, v61
	v_div_scale_f32 v61, s[6:7], v60, v60, 1.0
	v_rcp_f32_e32 v66, v61
	v_div_fmas_f32 v56, v56, v62, v57
	v_div_fixup_f32 v56, v56, v58, 1.0
	v_mul_f32_e32 v58, 0xbfb8aa3b, v59
	v_exp_f32_e32 v58, v58
	v_mul_f32_e32 v54, v54, v56
	v_fma_f32 v56, -v61, v66, 1.0
	v_fmac_f32_e32 v66, v56, v66
	v_div_scale_f32 v56, vcc, 1.0, v60, 1.0
	v_mul_f32_e32 v57, v56, v66
	v_fma_f32 v59, -v61, v57, v56
	v_add_f32_e32 v58, 1.0, v58
	v_fmac_f32_e32 v57, v59, v66
	v_div_scale_f32 v59, s[6:7], v58, v58, 1.0
	v_fma_f32 v56, -v61, v57, v56
	v_rcp_f32_e32 v61, v59
	v_div_fmas_f32 v56, v56, v66, v57
	v_div_fixup_f32 v56, v56, v60, 1.0
	v_mul_f32_e32 v56, v50, v56
	v_fma_f32 v50, -v59, v61, 1.0
	v_mul_f32_e32 v60, 0xbfb8aa3b, v63
	v_fmac_f32_e32 v61, v50, v61
	v_div_scale_f32 v50, vcc, 1.0, v58, 1.0
	v_exp_f32_e32 v60, v60
	v_mul_f32_e32 v57, v50, v61
	v_fma_f32 v62, -v59, v57, v50
	v_fmac_f32_e32 v57, v62, v61
	v_fma_f32 v50, -v59, v57, v50
	v_add_f32_e32 v59, 1.0, v60
	v_div_scale_f32 v60, s[6:7], v59, v59, 1.0
	v_rcp_f32_e32 v62, v60
	v_div_fmas_f32 v50, v50, v61, v57
	v_div_fixup_f32 v50, v50, v58, 1.0
	v_mul_f32_e32 v55, v55, v50
	v_fma_f32 v50, -v60, v62, 1.0
	v_fmac_f32_e32 v62, v50, v62
	v_div_scale_f32 v50, vcc, 1.0, v59, 1.0
	v_mul_f32_e32 v57, v50, v62
	v_fma_f32 v58, -v60, v57, v50
	v_fmac_f32_e32 v57, v58, v62
	v_fma_f32 v50, -v60, v57, v50
	v_div_fmas_f32 v50, v50, v62, v57
	v_div_fixup_f32 v50, v50, v59, 1.0
	v_mul_f32_e32 v57, v51, v50
	v_cvt_pk_bf16_f32 v50, v52, v53
	v_cvt_pk_bf16_f32 v51, v54, v55
	v_cvt_pk_bf16_f32 v52, v48, v49
	v_add_u32_e32 v48, 0x90, v160
	v_mad_i64_i32 v[48:49], s[6:7], v48, s57, v[146:147]
	v_lshl_add_u64 v[48:49], v[48:49], 0, v[148:149]
	v_add_co_u32_e32 v58, vcc, s58, v48
	v_cvt_pk_bf16_f32 v53, v56, v57
	global_store_dwordx4 v[64:65], v[50:53], off offset:256
	s_nop 0
	v_addc_co_u32_e32 v59, vcc, 0, v49, vcc
	s_waitcnt vmcnt(15)
; __device__ __forceinline__ u32x4 pack8(const f32x4 v0, const f32x4 v1) { u32x4 w; w.x = pk2(v0[0], v0[1]); w.y = pk2(v0[2], v0[3]); w.z = pk2(v1[0], v1[1]); w.w = pk2(v1[2], v1[3]); return w; }
; __device__ __forceinline__ void unpack8(const u32x4 w, f32x4& v0, f32x4& v1) { v0 = (f32x4){bflo(w.x), bfhi(w.x), bflo(w.y), bfhi(w.y)}; v1 = (f32x4){bflo(w.z), bfhi(w.z), bflo(w.w), bfhi(w.w)}; }
; __device__ __forceinline__ float sigmoidf_(float x) { return 1.0f / (1.0f + __expf(-x)); }
;     __device__ __forceinline__ void operator()(const f32x4 (&acc)[2][2][4][2], const Unit& u, int wr, int wc, int fr, int fq) const {
;     ...
;                 bf16_t* rowp = z + (size_t)(row0 + ai * 128 + m * 16) * DIN + col0;
; #pragma unroll
;                 for (int bj = 0; bj < 2; ++bj) {
;                     const u32x4 gw = *(const u32x4*)(rowp + (MODE == 0 ? O_GB : O_GA) + bj * 128);
;                     f32x4 g0, g1; unpack8(gw, g0, g1);
;                     f32x4 v0, v1;
; #pragma unroll
;                     for (int j = 0; j < 4; ++j) { v0[j] = sigmoidf_(g0[j]) * acc[ai][bj][m][0][j]; v1[j] = sigmoidf_(g1[j]) * acc[ai][bj][m][1][j]; }
;                     if (MODE == 1) { const u32x4 mw = *(const u32x4*)(rowp + bj * 128); f32x4 m0, m1; unpack8(mw, m0, m1); v0 += m0; v1 += m1; }
;                     *(u32x4*)(rowp + bj * 128) = pack8(v0, v1); }
	v_mov_b32_e32 v54, v252
	v_mov_b32_e32 v55, v253
	v_mov_b32_e32 v56, v254
	v_mov_b32_e32 v57, v255
	v_lshlrev_b32_e32 v50, 16, v54
	v_mul_f32_e32 v50, 0xbfb8aa3b, v50
	v_exp_f32_e32 v50, v50
	v_lshlrev_b32_e32 v52, 16, v55
	v_and_b32_e32 v53, 0xffff0000, v55
	v_and_b32_e32 v51, 0xffff0000, v54
	v_add_f32_e32 v50, 1.0, v50
	v_div_scale_f32 v55, s[6:7], v50, v50, 1.0
	v_rcp_f32_e32 v60, v55
	v_lshlrev_b32_e32 v54, 16, v56
	v_mul_f32_e32 v54, 0xbfb8aa3b, v54
	v_exp_f32_e32 v54, v54
	v_fma_f32 v62, -v55, v60, 1.0
	v_fmac_f32_e32 v60, v62, v60
	v_div_scale_f32 v62, vcc, 1.0, v50, 1.0
	v_mul_f32_e32 v63, v62, v60
	v_fma_f32 v64, -v55, v63, v62
	v_fmac_f32_e32 v63, v64, v60
	v_add_f32_e32 v54, 1.0, v54
	v_fma_f32 v55, -v55, v63, v62
	v_div_scale_f32 v62, s[6:7], v54, v54, 1.0
	v_rcp_f32_e32 v64, v62
	v_div_fmas_f32 v55, v55, v60, v63
	v_mul_f32_e32 v51, 0xbfb8aa3b, v51
	v_div_fixup_f32 v50, v55, v50, 1.0
	v_exp_f32_e32 v51, v51
	v_mul_f32_e32 v44, v44, v50
	v_fma_f32 v50, -v62, v64, 1.0
	v_fmac_f32_e32 v64, v50, v64
	v_div_scale_f32 v50, vcc, 1.0, v54, 1.0
	v_mul_f32_e32 v55, v50, v64
	v_fma_f32 v60, -v62, v55, v50
	v_add_f32_e32 v51, 1.0, v51
	v_fmac_f32_e32 v55, v60, v64
	v_div_scale_f32 v60, s[6:7], v51, v51, 1.0
	v_fma_f32 v50, -v62, v55, v50
	v_rcp_f32_e32 v62, v60
	v_and_b32_e32 v56, 0xffff0000, v56
	v_div_fmas_f32 v50, v50, v64, v55
	v_mul_f32_e32 v55, 0xbfb8aa3b, v56
	v_div_fixup_f32 v50, v50, v54, 1.0
	v_exp_f32_e32 v55, v55
	v_mul_f32_e32 v50, v40, v50
	v_fma_f32 v40, -v60, v62, 1.0
	v_fmac_f32_e32 v62, v40, v62
	v_div_scale_f32 v40, vcc, 1.0, v51, 1.0
	v_mul_f32_e32 v54, v40, v62
	v_fma_f32 v56, -v60, v54, v40
	v_add_f32_e32 v55, 1.0, v55
	v_fmac_f32_e32 v54, v56, v62
	v_div_scale_f32 v56, s[6:7], v55, v55, 1.0
	v_fma_f32 v40, -v60, v54, v40
	v_rcp_f32_e32 v60, v56
	v_div_fmas_f32 v40, v40, v62, v54
	v_mul_f32_e32 v52, 0xbfb8aa3b, v52
	v_div_fixup_f32 v40, v40, v51, 1.0
	v_exp_f32_e32 v52, v52
	v_mul_f32_e32 v40, v45, v40
	v_fma_f32 v45, -v56, v60, 1.0
	v_fmac_f32_e32 v60, v45, v60
	v_div_scale_f32 v45, vcc, 1.0, v55, 1.0
	v_mul_f32_e32 v51, v45, v60
	v_fma_f32 v54, -v56, v51, v45
	v_add_f32_e32 v52, 1.0, v52
	v_fmac_f32_e32 v51, v54, v60
	v_div_scale_f32 v54, s[6:7], v52, v52, 1.0
	v_fma_f32 v45, -v56, v51, v45
	v_rcp_f32_e32 v56, v54
	v_div_fmas_f32 v45, v45, v60, v51
	v_lshlrev_b32_e32 v61, 16, v57
	v_div_fixup_f32 v45, v45, v55, 1.0
	v_mul_f32_e32 v45, v41, v45
	v_fma_f32 v41, -v54, v56, 1.0
	v_mul_f32_e32 v55, 0xbfb8aa3b, v61
	v_fmac_f32_e32 v56, v41, v56
	v_div_scale_f32 v41, vcc, 1.0, v52, 1.0
	v_exp_f32_e32 v55, v55
	v_mul_f32_e32 v51, v41, v56
	v_fma_f32 v60, -v54, v51, v41
	v_fmac_f32_e32 v51, v60, v56
	v_fma_f32 v41, -v54, v51, v41
	v_add_f32_e32 v54, 1.0, v55
	v_div_scale_f32 v55, s[6:7], v54, v54, 1.0
	v_rcp_f32_e32 v60, v55
	v_div_fmas_f32 v41, v41, v56, v51
	v_div_fixup_f32 v41, v41, v52, 1.0
	v_mul_f32_e32 v52, 0xbfb8aa3b, v53
	v_exp_f32_e32 v52, v52
	v_mul_f32_e32 v41, v46, v41
	v_fma_f32 v46, -v55, v60, 1.0
	v_fmac_f32_e32 v60, v46, v60
	v_div_scale_f32 v46, vcc, 1.0, v54, 1.0
	v_mul_f32_e32 v51, v46, v60
	v_fma_f32 v53, -v55, v51, v46
	v_add_f32_e32 v52, 1.0, v52
	v_fmac_f32_e32 v51, v53, v60
	v_div_scale_f32 v53, s[6:7], v52, v52, 1.0
	v_fma_f32 v46, -v55, v51, v46
	v_rcp_f32_e32 v55, v53
	v_div_fmas_f32 v46, v46, v60, v51
	v_and_b32_e32 v57, 0xffff0000, v57
	v_div_fixup_f32 v46, v46, v54, 1.0
	v_mul_f32_e32 v46, v42, v46
	v_fma_f32 v42, -v53, v55, 1.0
	v_mul_f32_e32 v54, 0xbfb8aa3b, v57
	v_fmac_f32_e32 v55, v42, v55
	v_div_scale_f32 v42, vcc, 1.0, v52, 1.0
	v_exp_f32_e32 v54, v54
	v_mul_f32_e32 v51, v42, v55
	v_fma_f32 v56, -v53, v51, v42
	v_fmac_f32_e32 v51, v56, v55
	v_fma_f32 v42, -v53, v51, v42
	v_add_f32_e32 v53, 1.0, v54
	v_div_scale_f32 v54, s[6:7], v53, v53, 1.0
	v_rcp_f32_e32 v56, v54
	v_div_fmas_f32 v42, v42, v55, v51
	v_div_fixup_f32 v42, v42, v52, 1.0
	v_mul_f32_e32 v42, v47, v42
	v_fma_f32 v47, -v54, v56, 1.0
	v_fmac_f32_e32 v56, v47, v56
	v_div_scale_f32 v47, vcc, 1.0, v53, 1.0
	v_mul_f32_e32 v51, v47, v56
	v_fma_f32 v52, -v54, v51, v47
	v_fmac_f32_e32 v51, v52, v56
	v_fma_f32 v47, -v54, v51, v47
	v_div_fmas_f32 v47, v47, v56, v51
	v_div_fixup_f32 v47, v47, v53, 1.0
	v_mul_f32_e32 v43, v43, v47
	v_cvt_pk_bf16_f32 v40, v44, v40
	v_cvt_pk_bf16_f32 v41, v41, v42
	v_cvt_pk_bf16_f32 v42, v50, v45
	v_cvt_pk_bf16_f32 v43, v46, v43
	s_waitcnt vmcnt(14)
; __device__ __forceinline__ u32x4 pack8(const f32x4 v0, const f32x4 v1) { u32x4 w; w.x = pk2(v0[0], v0[1]); w.y = pk2(v0[2], v0[3]); w.z = pk2(v1[0], v1[1]); w.w = pk2(v1[2], v1[3]); return w; }
; __device__ __forceinline__ void unpack8(const u32x4 w, f32x4& v0, f32x4& v1) { v0 = (f32x4){bflo(w.x), bfhi(w.x), bflo(w.y), bfhi(w.y)}; v1 = (f32x4){bflo(w.z), bfhi(w.z), bflo(w.w), bfhi(w.w)}; }
; __device__ __forceinline__ float sigmoidf_(float x) { return 1.0f / (1.0f + __expf(-x)); }
;     __device__ __forceinline__ void operator()(const f32x4 (&acc)[2][2][4][2], const Unit& u, int wr, int wc, int fr, int fq) const {
;     ...
;                 bf16_t* rowp = z + (size_t)(row0 + ai * 128 + m * 16) * DIN + col0;
; #pragma unroll
;                 for (int bj = 0; bj < 2; ++bj) {
;                     const u32x4 gw = *(const u32x4*)(rowp + (MODE == 0 ? O_GB : O_GA) + bj * 128);
;                     f32x4 g0, g1; unpack8(gw, g0, g1);
;                     f32x4 v0, v1;
; #pragma unroll
;                     for (int j = 0; j < 4; ++j) { v0[j] = sigmoidf_(g0[j]) * acc[ai][bj][m][0][j]; v1[j] = sigmoidf_(g1[j]) * acc[ai][bj][m][1][j]; }
;                     if (MODE == 1) { const u32x4 mw = *(const u32x4*)(rowp + bj * 128); f32x4 m0, m1; unpack8(mw, m0, m1); v0 += m0; v1 += m1; }
;                     *(u32x4*)(rowp + bj * 128) = pack8(v0, v1); }
	v_mov_b32_e32 v44, v200
	v_mov_b32_e32 v45, v201
	v_mov_b32_e32 v46, v202
	v_mov_b32_e32 v47, v203
	v_lshlrev_b32_e32 v51, 16, v47
	global_store_dwordx4 v[48:49], v[40:43], off
	v_and_b32_e32 v47, 0xffff0000, v47
	s_nop 0
	v_lshlrev_b32_e32 v40, 16, v44
	v_mul_f32_e32 v40, 0xbfb8aa3b, v40
	v_exp_f32_e32 v40, v40
	v_lshlrev_b32_e32 v42, 16, v45
	v_and_b32_e32 v43, 0xffff0000, v45
	v_and_b32_e32 v41, 0xffff0000, v44
	v_add_f32_e32 v40, 1.0, v40
	v_div_scale_f32 v45, s[6:7], v40, v40, 1.0
	v_rcp_f32_e32 v50, v45
	v_lshlrev_b32_e32 v44, 16, v46
	v_mul_f32_e32 v44, 0xbfb8aa3b, v44
	v_exp_f32_e32 v44, v44
	v_fma_f32 v52, -v45, v50, 1.0
	v_fmac_f32_e32 v50, v52, v50
	v_div_scale_f32 v52, vcc, 1.0, v40, 1.0
	v_mul_f32_e32 v53, v52, v50
	v_fma_f32 v54, -v45, v53, v52
	v_fmac_f32_e32 v53, v54, v50
	v_add_f32_e32 v44, 1.0, v44
	v_fma_f32 v45, -v45, v53, v52
	v_div_scale_f32 v52, s[6:7], v44, v44, 1.0
	v_rcp_f32_e32 v54, v52
	v_div_fmas_f32 v45, v45, v50, v53
	v_mul_f32_e32 v41, 0xbfb8aa3b, v41
	v_div_fixup_f32 v40, v45, v40, 1.0
	v_exp_f32_e32 v41, v41
	v_mul_f32_e32 v36, v36, v40
	v_fma_f32 v40, -v52, v54, 1.0
	v_fmac_f32_e32 v54, v40, v54
	v_div_scale_f32 v40, vcc, 1.0, v44, 1.0
	v_mul_f32_e32 v45, v40, v54
	v_fma_f32 v50, -v52, v45, v40
	v_add_f32_e32 v41, 1.0, v41
	v_fmac_f32_e32 v45, v50, v54
	v_div_scale_f32 v50, s[6:7], v41, v41, 1.0
	v_fma_f32 v40, -v52, v45, v40
	v_rcp_f32_e32 v52, v50
	v_and_b32_e32 v46, 0xffff0000, v46
	v_div_fmas_f32 v40, v40, v54, v45
	v_mul_f32_e32 v45, 0xbfb8aa3b, v46
	v_div_fixup_f32 v40, v40, v44, 1.0
	v_exp_f32_e32 v45, v45
	v_mul_f32_e32 v32, v32, v40
	v_fma_f32 v40, -v50, v52, 1.0
	v_fmac_f32_e32 v52, v40, v52
	v_div_scale_f32 v40, vcc, 1.0, v41, 1.0
	v_mul_f32_e32 v44, v40, v52
	v_fma_f32 v46, -v50, v44, v40
	v_add_f32_e32 v45, 1.0, v45
	v_fmac_f32_e32 v44, v46, v52
	v_div_scale_f32 v46, s[6:7], v45, v45, 1.0
	v_fma_f32 v40, -v50, v44, v40
	v_rcp_f32_e32 v50, v46
	v_div_fmas_f32 v40, v40, v52, v44
	v_mul_f32_e32 v42, 0xbfb8aa3b, v42
	v_div_fixup_f32 v40, v40, v41, 1.0
	v_exp_f32_e32 v42, v42
	v_mul_f32_e32 v37, v37, v40
	v_fma_f32 v40, -v46, v50, 1.0
	v_fmac_f32_e32 v50, v40, v50
	v_div_scale_f32 v40, vcc, 1.0, v45, 1.0
	v_mul_f32_e32 v41, v40, v50
	v_fma_f32 v44, -v46, v41, v40
	v_add_f32_e32 v42, 1.0, v42
	v_fmac_f32_e32 v41, v44, v50
	v_div_scale_f32 v44, s[6:7], v42, v42, 1.0
	v_fma_f32 v40, -v46, v41, v40
	v_rcp_f32_e32 v46, v44
	v_div_fmas_f32 v40, v40, v50, v41
	v_div_fixup_f32 v40, v40, v45, 1.0
	v_mul_f32_e32 v33, v33, v40
	v_fma_f32 v40, -v44, v46, 1.0
	v_mul_f32_e32 v45, 0xbfb8aa3b, v51
	v_fmac_f32_e32 v46, v40, v46
	v_div_scale_f32 v40, vcc, 1.0, v42, 1.0
	v_exp_f32_e32 v45, v45
	v_mul_f32_e32 v41, v40, v46
	v_fma_f32 v50, -v44, v41, v40
	v_fmac_f32_e32 v41, v50, v46
	v_fma_f32 v40, -v44, v41, v40
	v_add_f32_e32 v44, 1.0, v45
	v_div_scale_f32 v45, s[6:7], v44, v44, 1.0
	v_rcp_f32_e32 v50, v45
	v_div_fmas_f32 v40, v40, v46, v41
	v_div_fixup_f32 v40, v40, v42, 1.0
	v_mul_f32_e32 v42, 0xbfb8aa3b, v43
	v_exp_f32_e32 v42, v42
	v_mul_f32_e32 v38, v38, v40
	v_fma_f32 v40, -v45, v50, 1.0
	v_fmac_f32_e32 v50, v40, v50
	v_div_scale_f32 v40, vcc, 1.0, v44, 1.0
	v_mul_f32_e32 v41, v40, v50
	v_fma_f32 v43, -v45, v41, v40
	v_add_f32_e32 v42, 1.0, v42
	v_fmac_f32_e32 v41, v43, v50
	v_div_scale_f32 v43, s[6:7], v42, v42, 1.0
	v_fma_f32 v40, -v45, v41, v40
	v_rcp_f32_e32 v45, v43
	v_div_fmas_f32 v40, v40, v50, v41
	v_div_fixup_f32 v40, v40, v44, 1.0
	v_mul_f32_e32 v40, v34, v40
	v_fma_f32 v34, -v43, v45, 1.0
	v_mul_f32_e32 v44, 0xbfb8aa3b, v47
	v_fmac_f32_e32 v45, v34, v45
	v_div_scale_f32 v34, vcc, 1.0, v42, 1.0
	v_exp_f32_e32 v44, v44
	v_mul_f32_e32 v41, v34, v45
	v_fma_f32 v46, -v43, v41, v34
	v_fmac_f32_e32 v41, v46, v45
	v_fma_f32 v34, -v43, v41, v34
	v_add_f32_e32 v43, 1.0, v44
	v_div_scale_f32 v44, s[6:7], v43, v43, 1.0
	v_rcp_f32_e32 v46, v44
	v_div_fmas_f32 v34, v34, v45, v41
	v_div_fixup_f32 v34, v34, v42, 1.0
	v_mul_f32_e32 v39, v39, v34
	v_fma_f32 v34, -v44, v46, 1.0
	v_fmac_f32_e32 v46, v34, v46
	v_div_scale_f32 v34, vcc, 1.0, v43, 1.0
	v_mul_f32_e32 v41, v34, v46
	v_fma_f32 v42, -v44, v41, v34
	v_fmac_f32_e32 v41, v42, v46
	v_fma_f32 v34, -v44, v41, v34
	v_div_fmas_f32 v34, v34, v46, v41
	v_div_fixup_f32 v34, v34, v43, 1.0
	v_mul_f32_e32 v41, v35, v34
	v_cvt_pk_bf16_f32 v34, v36, v37
	v_cvt_pk_bf16_f32 v35, v38, v39
	v_cvt_pk_bf16_f32 v36, v32, v33
	v_add_u32_e32 v32, 0xa0, v160
	v_mad_i64_i32 v[32:33], s[6:7], v32, s57, v[146:147]
	v_lshl_add_u64 v[32:33], v[32:33], 0, v[148:149]
	v_add_co_u32_e32 v42, vcc, s58, v32
	v_cvt_pk_bf16_f32 v37, v40, v41
	global_store_dwordx4 v[48:49], v[34:37], off offset:256
	s_nop 0
	v_addc_co_u32_e32 v43, vcc, 0, v33, vcc
	s_waitcnt vmcnt(14)
; __device__ __forceinline__ u32x4 pack8(const f32x4 v0, const f32x4 v1) { u32x4 w; w.x = pk2(v0[0], v0[1]); w.y = pk2(v0[2], v0[3]); w.z = pk2(v1[0], v1[1]); w.w = pk2(v1[2], v1[3]); return w; }
; __device__ __forceinline__ void unpack8(const u32x4 w, f32x4& v0, f32x4& v1) { v0 = (f32x4){bflo(w.x), bfhi(w.x), bflo(w.y), bfhi(w.y)}; v1 = (f32x4){bflo(w.z), bfhi(w.z), bflo(w.w), bfhi(w.w)}; }
; __device__ __forceinline__ float sigmoidf_(float x) { return 1.0f / (1.0f + __expf(-x)); }
;     __device__ __forceinline__ void operator()(const f32x4 (&acc)[2][2][4][2], const Unit& u, int wr, int wc, int fr, int fq) const {
;     ...
;                 bf16_t* rowp = z + (size_t)(row0 + ai * 128 + m * 16) * DIN + col0;
; #pragma unroll
;                 for (int bj = 0; bj < 2; ++bj) {
;                     const u32x4 gw = *(const u32x4*)(rowp + (MODE == 0 ? O_GB : O_GA) + bj * 128);
;                     f32x4 g0, g1; unpack8(gw, g0, g1);
;                     f32x4 v0, v1;
; #pragma unroll
;                     for (int j = 0; j < 4; ++j) { v0[j] = sigmoidf_(g0[j]) * acc[ai][bj][m][0][j]; v1[j] = sigmoidf_(g1[j]) * acc[ai][bj][m][1][j]; }
;                     if (MODE == 1) { const u32x4 mw = *(const u32x4*)(rowp + bj * 128); f32x4 m0, m1; unpack8(mw, m0, m1); v0 += m0; v1 += m1; }
;                     *(u32x4*)(rowp + bj * 128) = pack8(v0, v1); }
	v_mov_b32_e32 v38, v204
	v_mov_b32_e32 v39, v205
	v_mov_b32_e32 v40, v206
	v_mov_b32_e32 v41, v207
	v_lshlrev_b32_e32 v34, 16, v38
	v_mul_f32_e32 v34, 0xbfb8aa3b, v34
	v_exp_f32_e32 v34, v34
	v_lshlrev_b32_e32 v36, 16, v39
	v_and_b32_e32 v37, 0xffff0000, v39
	v_and_b32_e32 v35, 0xffff0000, v38
	v_add_f32_e32 v34, 1.0, v34
	v_div_scale_f32 v39, s[6:7], v34, v34, 1.0
	v_rcp_f32_e32 v44, v39
	v_lshlrev_b32_e32 v38, 16, v40
	v_mul_f32_e32 v38, 0xbfb8aa3b, v38
	v_exp_f32_e32 v38, v38
	v_fma_f32 v46, -v39, v44, 1.0
	v_fmac_f32_e32 v44, v46, v44
	v_div_scale_f32 v46, vcc, 1.0, v34, 1.0
	v_mul_f32_e32 v47, v46, v44
	v_fma_f32 v48, -v39, v47, v46
	v_fmac_f32_e32 v47, v48, v44
	v_add_f32_e32 v38, 1.0, v38
	v_fma_f32 v39, -v39, v47, v46
	v_div_scale_f32 v46, s[6:7], v38, v38, 1.0
	v_rcp_f32_e32 v48, v46
	v_div_fmas_f32 v39, v39, v44, v47
	v_mul_f32_e32 v35, 0xbfb8aa3b, v35
	v_div_fixup_f32 v34, v39, v34, 1.0
	v_exp_f32_e32 v35, v35
	v_mul_f32_e32 v28, v28, v34
	v_fma_f32 v34, -v46, v48, 1.0
	v_fmac_f32_e32 v48, v34, v48
	v_div_scale_f32 v34, vcc, 1.0, v38, 1.0
	v_mul_f32_e32 v39, v34, v48
	v_fma_f32 v44, -v46, v39, v34
	v_add_f32_e32 v35, 1.0, v35
	v_fmac_f32_e32 v39, v44, v48
	v_div_scale_f32 v44, s[6:7], v35, v35, 1.0
	v_fma_f32 v34, -v46, v39, v34
	v_rcp_f32_e32 v46, v44
	v_and_b32_e32 v40, 0xffff0000, v40
	v_div_fmas_f32 v34, v34, v48, v39
	v_mul_f32_e32 v39, 0xbfb8aa3b, v40
	v_div_fixup_f32 v34, v34, v38, 1.0
	v_exp_f32_e32 v39, v39
	v_mul_f32_e32 v34, v24, v34
	v_fma_f32 v24, -v44, v46, 1.0
	v_fmac_f32_e32 v46, v24, v46
	v_div_scale_f32 v24, vcc, 1.0, v35, 1.0
	v_mul_f32_e32 v38, v24, v46
	v_fma_f32 v40, -v44, v38, v24
	v_add_f32_e32 v39, 1.0, v39
	v_fmac_f32_e32 v38, v40, v46
	v_div_scale_f32 v40, s[6:7], v39, v39, 1.0
	v_fma_f32 v24, -v44, v38, v24
	v_rcp_f32_e32 v44, v40
	v_div_fmas_f32 v24, v24, v46, v38
	v_mul_f32_e32 v36, 0xbfb8aa3b, v36
	v_div_fixup_f32 v24, v24, v35, 1.0
	v_exp_f32_e32 v36, v36
	v_mul_f32_e32 v24, v29, v24
	v_fma_f32 v29, -v40, v44, 1.0
	v_fmac_f32_e32 v44, v29, v44
	v_div_scale_f32 v29, vcc, 1.0, v39, 1.0
	v_mul_f32_e32 v35, v29, v44
	v_fma_f32 v38, -v40, v35, v29
	v_add_f32_e32 v36, 1.0, v36
	v_fmac_f32_e32 v35, v38, v44
	v_div_scale_f32 v38, s[6:7], v36, v36, 1.0
	v_fma_f32 v29, -v40, v35, v29
	v_rcp_f32_e32 v40, v38
	v_div_fmas_f32 v29, v29, v44, v35
	v_lshlrev_b32_e32 v45, 16, v41
	v_div_fixup_f32 v29, v29, v39, 1.0
	v_mul_f32_e32 v29, v25, v29
	v_fma_f32 v25, -v38, v40, 1.0
	v_mul_f32_e32 v39, 0xbfb8aa3b, v45
	v_fmac_f32_e32 v40, v25, v40
	v_div_scale_f32 v25, vcc, 1.0, v36, 1.0
	v_exp_f32_e32 v39, v39
	v_mul_f32_e32 v35, v25, v40
	v_fma_f32 v44, -v38, v35, v25
	v_fmac_f32_e32 v35, v44, v40
	v_fma_f32 v25, -v38, v35, v25
	v_add_f32_e32 v38, 1.0, v39
	v_div_scale_f32 v39, s[6:7], v38, v38, 1.0
	v_rcp_f32_e32 v44, v39
	v_div_fmas_f32 v25, v25, v40, v35
	v_div_fixup_f32 v25, v25, v36, 1.0
	v_mul_f32_e32 v36, 0xbfb8aa3b, v37
	v_exp_f32_e32 v36, v36
	v_mul_f32_e32 v25, v30, v25
	v_fma_f32 v30, -v39, v44, 1.0
	v_fmac_f32_e32 v44, v30, v44
	v_div_scale_f32 v30, vcc, 1.0, v38, 1.0
	v_mul_f32_e32 v35, v30, v44
	v_fma_f32 v37, -v39, v35, v30
	v_add_f32_e32 v36, 1.0, v36
	v_fmac_f32_e32 v35, v37, v44
	v_div_scale_f32 v37, s[6:7], v36, v36, 1.0
	v_fma_f32 v30, -v39, v35, v30
	v_rcp_f32_e32 v39, v37
	v_div_fmas_f32 v30, v30, v44, v35
	v_and_b32_e32 v41, 0xffff0000, v41
	v_div_fixup_f32 v30, v30, v38, 1.0
	v_mul_f32_e32 v30, v26, v30
	v_fma_f32 v26, -v37, v39, 1.0
	v_mul_f32_e32 v38, 0xbfb8aa3b, v41
	v_fmac_f32_e32 v39, v26, v39
	v_div_scale_f32 v26, vcc, 1.0, v36, 1.0
	v_exp_f32_e32 v38, v38
	v_mul_f32_e32 v35, v26, v39
	v_fma_f32 v40, -v37, v35, v26
	v_fmac_f32_e32 v35, v40, v39
	v_fma_f32 v26, -v37, v35, v26
	v_add_f32_e32 v37, 1.0, v38
	v_div_scale_f32 v38, s[6:7], v37, v37, 1.0
	v_rcp_f32_e32 v40, v38
	v_div_fmas_f32 v26, v26, v39, v35
	v_div_fixup_f32 v26, v26, v36, 1.0
	v_mul_f32_e32 v26, v31, v26
	v_fma_f32 v31, -v38, v40, 1.0
	v_fmac_f32_e32 v40, v31, v40
	v_div_scale_f32 v31, vcc, 1.0, v37, 1.0
	v_mul_f32_e32 v35, v31, v40
	v_fma_f32 v36, -v38, v35, v31
	v_fmac_f32_e32 v35, v36, v40
	v_fma_f32 v31, -v38, v35, v31
	v_div_fmas_f32 v31, v31, v40, v35
	v_div_fixup_f32 v31, v31, v37, 1.0
	v_mul_f32_e32 v27, v27, v31
	v_cvt_pk_bf16_f32 v24, v28, v24
	v_cvt_pk_bf16_f32 v25, v25, v26
	v_cvt_pk_bf16_f32 v26, v34, v29
	v_cvt_pk_bf16_f32 v27, v30, v27
	s_waitcnt vmcnt(12)
; __device__ __forceinline__ u32x4 pack8(const f32x4 v0, const f32x4 v1) { u32x4 w; w.x = pk2(v0[0], v0[1]); w.y = pk2(v0[2], v0[3]); w.z = pk2(v1[0], v1[1]); w.w = pk2(v1[2], v1[3]); return w; }
; __device__ __forceinline__ void unpack8(const u32x4 w, f32x4& v0, f32x4& v1) { v0 = (f32x4){bflo(w.x), bfhi(w.x), bflo(w.y), bfhi(w.y)}; v1 = (f32x4){bflo(w.z), bfhi(w.z), bflo(w.w), bfhi(w.w)}; }
; __device__ __forceinline__ float sigmoidf_(float x) { return 1.0f / (1.0f + __expf(-x)); }
;     __device__ __forceinline__ void operator()(const f32x4 (&acc)[2][2][4][2], const Unit& u, int wr, int wc, int fr, int fq) const {
;     ...
;                 bf16_t* rowp = z + (size_t)(row0 + ai * 128 + m * 16) * DIN + col0;
; #pragma unroll
;                 for (int bj = 0; bj < 2; ++bj) {
;                     const u32x4 gw = *(const u32x4*)(rowp + (MODE == 0 ? O_GB : O_GA) + bj * 128);
;                     f32x4 g0, g1; unpack8(gw, g0, g1);
;                     f32x4 v0, v1;
; #pragma unroll
;                     for (int j = 0; j < 4; ++j) { v0[j] = sigmoidf_(g0[j]) * acc[ai][bj][m][0][j]; v1[j] = sigmoidf_(g1[j]) * acc[ai][bj][m][1][j]; }
;                     if (MODE == 1) { const u32x4 mw = *(const u32x4*)(rowp + bj * 128); f32x4 m0, m1; unpack8(mw, m0, m1); v0 += m0; v1 += m1; }
;                     *(u32x4*)(rowp + bj * 128) = pack8(v0, v1); }
	v_mov_b32_e32 v28, v208
	v_mov_b32_e32 v29, v209
	v_mov_b32_e32 v30, v210
	v_mov_b32_e32 v31, v211
	v_lshlrev_b32_e32 v35, 16, v31
	global_store_dwordx4 v[32:33], v[24:27], off
	v_and_b32_e32 v31, 0xffff0000, v31
	s_nop 0
	v_lshlrev_b32_e32 v24, 16, v28
	v_mul_f32_e32 v24, 0xbfb8aa3b, v24
	v_exp_f32_e32 v24, v24
	v_lshlrev_b32_e32 v26, 16, v29
	v_and_b32_e32 v27, 0xffff0000, v29
	v_and_b32_e32 v25, 0xffff0000, v28
	v_add_f32_e32 v24, 1.0, v24
	v_div_scale_f32 v29, s[6:7], v24, v24, 1.0
	v_rcp_f32_e32 v34, v29
	v_lshlrev_b32_e32 v28, 16, v30
	v_mul_f32_e32 v28, 0xbfb8aa3b, v28
	v_exp_f32_e32 v28, v28
	v_fma_f32 v36, -v29, v34, 1.0
	v_fmac_f32_e32 v34, v36, v34
	v_div_scale_f32 v36, vcc, 1.0, v24, 1.0
	v_mul_f32_e32 v37, v36, v34
	v_fma_f32 v38, -v29, v37, v36
	v_fmac_f32_e32 v37, v38, v34
	v_add_f32_e32 v28, 1.0, v28
	v_fma_f32 v29, -v29, v37, v36
	v_div_scale_f32 v36, s[6:7], v28, v28, 1.0
	v_rcp_f32_e32 v38, v36
	v_div_fmas_f32 v29, v29, v34, v37
	v_mul_f32_e32 v25, 0xbfb8aa3b, v25
	v_div_fixup_f32 v24, v29, v24, 1.0
	v_exp_f32_e32 v25, v25
	v_mul_f32_e32 v20, v20, v24
	v_fma_f32 v24, -v36, v38, 1.0
	v_fmac_f32_e32 v38, v24, v38
	v_div_scale_f32 v24, vcc, 1.0, v28, 1.0
	v_mul_f32_e32 v29, v24, v38
	v_fma_f32 v34, -v36, v29, v24
	v_add_f32_e32 v25, 1.0, v25
	v_fmac_f32_e32 v29, v34, v38
	v_div_scale_f32 v34, s[6:7], v25, v25, 1.0
	v_fma_f32 v24, -v36, v29, v24
	v_rcp_f32_e32 v36, v34
	v_and_b32_e32 v30, 0xffff0000, v30
	v_div_fmas_f32 v24, v24, v38, v29
	v_mul_f32_e32 v29, 0xbfb8aa3b, v30
	v_div_fixup_f32 v24, v24, v28, 1.0
	v_exp_f32_e32 v29, v29
	v_mul_f32_e32 v16, v16, v24
	v_fma_f32 v24, -v34, v36, 1.0
	v_fmac_f32_e32 v36, v24, v36
	v_div_scale_f32 v24, vcc, 1.0, v25, 1.0
	v_mul_f32_e32 v28, v24, v36
	v_fma_f32 v30, -v34, v28, v24
	v_add_f32_e32 v29, 1.0, v29
	v_fmac_f32_e32 v28, v30, v36
	v_div_scale_f32 v30, s[6:7], v29, v29, 1.0
	v_fma_f32 v24, -v34, v28, v24
	v_rcp_f32_e32 v34, v30
	v_div_fmas_f32 v24, v24, v36, v28
	v_mul_f32_e32 v26, 0xbfb8aa3b, v26
	v_div_fixup_f32 v24, v24, v25, 1.0
	v_exp_f32_e32 v26, v26
	v_mul_f32_e32 v21, v21, v24
	v_fma_f32 v24, -v30, v34, 1.0
	v_fmac_f32_e32 v34, v24, v34
	v_div_scale_f32 v24, vcc, 1.0, v29, 1.0
	v_mul_f32_e32 v25, v24, v34
	v_fma_f32 v28, -v30, v25, v24
	v_add_f32_e32 v26, 1.0, v26
	v_fmac_f32_e32 v25, v28, v34
	v_div_scale_f32 v28, s[6:7], v26, v26, 1.0
	v_fma_f32 v24, -v30, v25, v24
	v_rcp_f32_e32 v30, v28
	v_div_fmas_f32 v24, v24, v34, v25
	v_div_fixup_f32 v24, v24, v29, 1.0
	v_mul_f32_e32 v17, v17, v24
	v_fma_f32 v24, -v28, v30, 1.0
	v_mul_f32_e32 v29, 0xbfb8aa3b, v35
	v_fmac_f32_e32 v30, v24, v30
	v_div_scale_f32 v24, vcc, 1.0, v26, 1.0
	v_exp_f32_e32 v29, v29
	v_mul_f32_e32 v25, v24, v30
	v_fma_f32 v34, -v28, v25, v24
	v_fmac_f32_e32 v25, v34, v30
	v_fma_f32 v24, -v28, v25, v24
	v_add_f32_e32 v28, 1.0, v29
	v_div_scale_f32 v29, s[6:7], v28, v28, 1.0
	v_rcp_f32_e32 v34, v29
	v_div_fmas_f32 v24, v24, v30, v25
	v_div_fixup_f32 v24, v24, v26, 1.0
	v_mul_f32_e32 v26, 0xbfb8aa3b, v27
	v_exp_f32_e32 v26, v26
	v_mul_f32_e32 v22, v22, v24
	v_fma_f32 v24, -v29, v34, 1.0
	v_fmac_f32_e32 v34, v24, v34
	v_div_scale_f32 v24, vcc, 1.0, v28, 1.0
	v_mul_f32_e32 v25, v24, v34
	v_fma_f32 v27, -v29, v25, v24
	v_add_f32_e32 v26, 1.0, v26
	v_fmac_f32_e32 v25, v27, v34
	v_div_scale_f32 v27, s[6:7], v26, v26, 1.0
	v_fma_f32 v24, -v29, v25, v24
	v_rcp_f32_e32 v29, v27
	v_div_fmas_f32 v24, v24, v34, v25
	v_div_fixup_f32 v24, v24, v28, 1.0
	v_mul_f32_e32 v24, v18, v24
	v_fma_f32 v18, -v27, v29, 1.0
	v_mul_f32_e32 v28, 0xbfb8aa3b, v31
	v_fmac_f32_e32 v29, v18, v29
	v_div_scale_f32 v18, vcc, 1.0, v26, 1.0
	v_exp_f32_e32 v28, v28
	v_mul_f32_e32 v25, v18, v29
	v_fma_f32 v30, -v27, v25, v18
	v_fmac_f32_e32 v25, v30, v29
	v_fma_f32 v18, -v27, v25, v18
	v_add_f32_e32 v27, 1.0, v28
	v_div_scale_f32 v28, s[6:7], v27, v27, 1.0
	v_rcp_f32_e32 v30, v28
	v_div_fmas_f32 v18, v18, v29, v25
	v_div_fixup_f32 v18, v18, v26, 1.0
	v_mul_f32_e32 v23, v23, v18
	v_fma_f32 v18, -v28, v30, 1.0
	v_fmac_f32_e32 v30, v18, v30
	v_div_scale_f32 v18, vcc, 1.0, v27, 1.0
	v_mul_f32_e32 v25, v18, v30
	v_fma_f32 v26, -v28, v25, v18
	v_fmac_f32_e32 v25, v26, v30
	v_fma_f32 v18, -v28, v25, v18
	v_div_fmas_f32 v18, v18, v30, v25
	v_div_fixup_f32 v18, v18, v27, 1.0
	v_mul_f32_e32 v25, v19, v18
	v_cvt_pk_bf16_f32 v18, v20, v21
	v_cvt_pk_bf16_f32 v19, v22, v23
	v_cvt_pk_bf16_f32 v20, v16, v17
	v_add_u32_e32 v16, 0xb0, v160
	v_mad_i64_i32 v[16:17], s[6:7], v16, s57, v[146:147]
	v_lshl_add_u64 v[16:17], v[16:17], 0, v[148:149]
	v_add_co_u32_e32 v26, vcc, s58, v16
	v_cvt_pk_bf16_f32 v21, v24, v25
	global_store_dwordx4 v[32:33], v[18:21], off offset:256
	s_nop 0
	v_addc_co_u32_e32 v27, vcc, 0, v17, vcc
	s_waitcnt vmcnt(13)
; __device__ __forceinline__ u32x4 pack8(const f32x4 v0, const f32x4 v1) { u32x4 w; w.x = pk2(v0[0], v0[1]); w.y = pk2(v0[2], v0[3]); w.z = pk2(v1[0], v1[1]); w.w = pk2(v1[2], v1[3]); return w; }
; __device__ __forceinline__ void unpack8(const u32x4 w, f32x4& v0, f32x4& v1) { v0 = (f32x4){bflo(w.x), bfhi(w.x), bflo(w.y), bfhi(w.y)}; v1 = (f32x4){bflo(w.z), bfhi(w.z), bflo(w.w), bfhi(w.w)}; }
; __device__ __forceinline__ float sigmoidf_(float x) { return 1.0f / (1.0f + __expf(-x)); }
;     __device__ __forceinline__ void operator()(const f32x4 (&acc)[2][2][4][2], const Unit& u, int wr, int wc, int fr, int fq) const {
;     ...
;                 bf16_t* rowp = z + (size_t)(row0 + ai * 128 + m * 16) * DIN + col0;
; #pragma unroll
;                 for (int bj = 0; bj < 2; ++bj) {
;                     const u32x4 gw = *(const u32x4*)(rowp + (MODE == 0 ? O_GB : O_GA) + bj * 128);
;                     f32x4 g0, g1; unpack8(gw, g0, g1);
;                     f32x4 v0, v1;
; #pragma unroll
;                     for (int j = 0; j < 4; ++j) { v0[j] = sigmoidf_(g0[j]) * acc[ai][bj][m][0][j]; v1[j] = sigmoidf_(g1[j]) * acc[ai][bj][m][1][j]; }
;                     if (MODE == 1) { const u32x4 mw = *(const u32x4*)(rowp + bj * 128); f32x4 m0, m1; unpack8(mw, m0, m1); v0 += m0; v1 += m1; }
;                     *(u32x4*)(rowp + bj * 128) = pack8(v0, v1); }
	v_mov_b32_e32 v22, v212
	v_mov_b32_e32 v23, v213
	v_mov_b32_e32 v24, v214
	v_mov_b32_e32 v25, v215
	v_lshlrev_b32_e32 v18, 16, v22
	v_mul_f32_e32 v18, 0xbfb8aa3b, v18
	v_exp_f32_e32 v18, v18
	v_lshlrev_b32_e32 v20, 16, v23
	v_and_b32_e32 v21, 0xffff0000, v23
	v_and_b32_e32 v19, 0xffff0000, v22
	v_add_f32_e32 v18, 1.0, v18
	v_div_scale_f32 v23, s[6:7], v18, v18, 1.0
	v_rcp_f32_e32 v28, v23
	v_lshlrev_b32_e32 v22, 16, v24
	v_mul_f32_e32 v22, 0xbfb8aa3b, v22
	v_exp_f32_e32 v22, v22
	v_fma_f32 v30, -v23, v28, 1.0
	v_fmac_f32_e32 v28, v30, v28
	v_div_scale_f32 v30, vcc, 1.0, v18, 1.0
	v_mul_f32_e32 v31, v30, v28
	v_fma_f32 v32, -v23, v31, v30
	v_fmac_f32_e32 v31, v32, v28
	v_add_f32_e32 v22, 1.0, v22
	v_fma_f32 v23, -v23, v31, v30
	v_div_scale_f32 v30, s[6:7], v22, v22, 1.0
	v_rcp_f32_e32 v32, v30
	v_div_fmas_f32 v23, v23, v28, v31
	v_mul_f32_e32 v19, 0xbfb8aa3b, v19
	v_div_fixup_f32 v18, v23, v18, 1.0
	v_exp_f32_e32 v19, v19
	v_mul_f32_e32 v12, v12, v18
	v_fma_f32 v18, -v30, v32, 1.0
	v_fmac_f32_e32 v32, v18, v32
	v_div_scale_f32 v18, vcc, 1.0, v22, 1.0
	v_mul_f32_e32 v23, v18, v32
	v_fma_f32 v28, -v30, v23, v18
	v_add_f32_e32 v19, 1.0, v19
	v_fmac_f32_e32 v23, v28, v32
	v_div_scale_f32 v28, s[6:7], v19, v19, 1.0
	v_fma_f32 v18, -v30, v23, v18
	v_rcp_f32_e32 v30, v28
	v_and_b32_e32 v24, 0xffff0000, v24
	v_div_fmas_f32 v18, v18, v32, v23
	v_mul_f32_e32 v23, 0xbfb8aa3b, v24
	v_div_fixup_f32 v18, v18, v22, 1.0
	v_exp_f32_e32 v23, v23
	v_mul_f32_e32 v18, v8, v18
	v_fma_f32 v8, -v28, v30, 1.0
	v_fmac_f32_e32 v30, v8, v30
	v_div_scale_f32 v8, vcc, 1.0, v19, 1.0
	v_mul_f32_e32 v22, v8, v30
	v_fma_f32 v24, -v28, v22, v8
	v_add_f32_e32 v23, 1.0, v23
	v_fmac_f32_e32 v22, v24, v30
	v_div_scale_f32 v24, s[6:7], v23, v23, 1.0
	v_fma_f32 v8, -v28, v22, v8
	v_rcp_f32_e32 v28, v24
	v_div_fmas_f32 v8, v8, v30, v22
	v_mul_f32_e32 v20, 0xbfb8aa3b, v20
	v_div_fixup_f32 v8, v8, v19, 1.0
	v_exp_f32_e32 v20, v20
	v_mul_f32_e32 v8, v13, v8
	v_fma_f32 v13, -v24, v28, 1.0
	v_fmac_f32_e32 v28, v13, v28
	v_div_scale_f32 v13, vcc, 1.0, v23, 1.0
	v_mul_f32_e32 v19, v13, v28
	v_fma_f32 v22, -v24, v19, v13
	v_add_f32_e32 v20, 1.0, v20
	v_fmac_f32_e32 v19, v22, v28
	v_div_scale_f32 v22, s[6:7], v20, v20, 1.0
	v_fma_f32 v13, -v24, v19, v13
	v_rcp_f32_e32 v24, v22
	v_div_fmas_f32 v13, v13, v28, v19
	v_lshlrev_b32_e32 v29, 16, v25
	v_div_fixup_f32 v13, v13, v23, 1.0
	v_mul_f32_e32 v13, v9, v13
	v_fma_f32 v9, -v22, v24, 1.0
	v_mul_f32_e32 v23, 0xbfb8aa3b, v29
	v_fmac_f32_e32 v24, v9, v24
	v_div_scale_f32 v9, vcc, 1.0, v20, 1.0
	v_exp_f32_e32 v23, v23
	v_mul_f32_e32 v19, v9, v24
	v_fma_f32 v28, -v22, v19, v9
	v_fmac_f32_e32 v19, v28, v24
	v_fma_f32 v9, -v22, v19, v9
	v_add_f32_e32 v22, 1.0, v23
	v_div_scale_f32 v23, s[6:7], v22, v22, 1.0
	v_rcp_f32_e32 v28, v23
	v_div_fmas_f32 v9, v9, v24, v19
	v_div_fixup_f32 v9, v9, v20, 1.0
	v_mul_f32_e32 v20, 0xbfb8aa3b, v21
	v_exp_f32_e32 v20, v20
	v_mul_f32_e32 v9, v14, v9
	v_fma_f32 v14, -v23, v28, 1.0
	v_fmac_f32_e32 v28, v14, v28
	v_div_scale_f32 v14, vcc, 1.0, v22, 1.0
	v_mul_f32_e32 v19, v14, v28
	v_fma_f32 v21, -v23, v19, v14
	v_add_f32_e32 v20, 1.0, v20
	v_fmac_f32_e32 v19, v21, v28
	v_div_scale_f32 v21, s[6:7], v20, v20, 1.0
	v_fma_f32 v14, -v23, v19, v14
	v_rcp_f32_e32 v23, v21
	v_div_fmas_f32 v14, v14, v28, v19
	v_and_b32_e32 v25, 0xffff0000, v25
	v_div_fixup_f32 v14, v14, v22, 1.0
	v_mul_f32_e32 v14, v10, v14
	v_fma_f32 v10, -v21, v23, 1.0
	v_mul_f32_e32 v22, 0xbfb8aa3b, v25
	v_fmac_f32_e32 v23, v10, v23
	v_div_scale_f32 v10, vcc, 1.0, v20, 1.0
	v_exp_f32_e32 v22, v22
	v_mul_f32_e32 v19, v10, v23
	v_fma_f32 v24, -v21, v19, v10
	v_fmac_f32_e32 v19, v24, v23
	v_fma_f32 v10, -v21, v19, v10
	v_add_f32_e32 v21, 1.0, v22
	v_div_scale_f32 v22, s[6:7], v21, v21, 1.0
	v_rcp_f32_e32 v24, v22
	v_div_fmas_f32 v10, v10, v23, v19
	v_div_fixup_f32 v10, v10, v20, 1.0
	v_mul_f32_e32 v10, v15, v10
	v_fma_f32 v15, -v22, v24, 1.0
	v_fmac_f32_e32 v24, v15, v24
	v_div_scale_f32 v15, vcc, 1.0, v21, 1.0
	v_mul_f32_e32 v19, v15, v24
	v_fma_f32 v20, -v22, v19, v15
	v_fmac_f32_e32 v19, v20, v24
	v_fma_f32 v15, -v22, v19, v15
	v_div_fmas_f32 v15, v15, v24, v19
	v_div_fixup_f32 v15, v15, v21, 1.0
	v_mul_f32_e32 v11, v11, v15
	v_cvt_pk_bf16_f32 v8, v12, v8
	v_cvt_pk_bf16_f32 v9, v9, v10
	v_cvt_pk_bf16_f32 v10, v18, v13
	v_cvt_pk_bf16_f32 v11, v14, v11
	s_waitcnt vmcnt(10)
; __device__ __forceinline__ float sigmoidf_(float x) { return 1.0f / (1.0f + __expf(-x)); }
; #define PG8_WAIT_V(n) asm volatile("s_waitcnt vmcnt(" #n ")" ::: "memory")
; #define PG8_BAR __builtin_amdgcn_s_barrier()
; __device__ __forceinline__ u32x4 pack8(const f32x4 v0, const f32x4 v1) { u32x4 w; w.x = pk2(v0[0], v0[1]); w.y = pk2(v0[2], v0[3]); w.z = pk2(v1[0], v1[1]); w.w = pk2(v1[2], v1[3]); return w; }
; __device__ __forceinline__ void unpack8(const u32x4 w, f32x4& v0, f32x4& v1) { v0 = (f32x4){bflo(w.x), bfhi(w.x), bflo(w.y), bfhi(w.y)}; v1 = (f32x4){bflo(w.z), bfhi(w.z), bflo(w.w), bfhi(w.w)}; }
;     ...
;         if (!has_next) break;
;     ...
;     PG8_WAIT_V(0);
;     if (wr == 0) PG8_BAR;
;     PG8_BAR;
;     __device__ __forceinline__ void operator()(const f32x4 (&acc)[2][2][4][2], const Unit& u, int wr, int wc, int fr, int fq) const {
;     ...
;                 bf16_t* rowp = z + (size_t)(row0 + ai * 128 + m * 16) * DIN + col0;
; #pragma unroll
;                 for (int bj = 0; bj < 2; ++bj) {
;                     const u32x4 gw = *(const u32x4*)(rowp + (MODE == 0 ? O_GB : O_GA) + bj * 128);
;                     f32x4 g0, g1; unpack8(gw, g0, g1);
;                     f32x4 v0, v1;
; #pragma unroll
;                     for (int j = 0; j < 4; ++j) { v0[j] = sigmoidf_(g0[j]) * acc[ai][bj][m][0][j]; v1[j] = sigmoidf_(g1[j]) * acc[ai][bj][m][1][j]; }
;                     if (MODE == 1) { const u32x4 mw = *(const u32x4*)(rowp + bj * 128); f32x4 m0, m1; unpack8(mw, m0, m1); v0 += m0; v1 += m1; }
;                     *(u32x4*)(rowp + bj * 128) = pack8(v0, v1); }
	v_mov_b32_e32 v12, v216
	v_mov_b32_e32 v13, v217
	v_mov_b32_e32 v14, v218
	v_mov_b32_e32 v15, v219
	v_lshlrev_b32_e32 v19, 16, v15
	global_store_dwordx4 v[16:17], v[8:11], off
	v_and_b32_e32 v15, 0xffff0000, v15
	s_nop 0
	v_lshlrev_b32_e32 v8, 16, v12
	v_mul_f32_e32 v8, 0xbfb8aa3b, v8
	v_exp_f32_e32 v8, v8
	v_lshlrev_b32_e32 v10, 16, v13
	v_and_b32_e32 v11, 0xffff0000, v13
	v_and_b32_e32 v9, 0xffff0000, v12
	v_add_f32_e32 v8, 1.0, v8
	v_div_scale_f32 v13, s[6:7], v8, v8, 1.0
	v_rcp_f32_e32 v18, v13
	v_lshlrev_b32_e32 v12, 16, v14
	v_mul_f32_e32 v12, 0xbfb8aa3b, v12
	v_exp_f32_e32 v12, v12
	v_fma_f32 v20, -v13, v18, 1.0
	v_fmac_f32_e32 v18, v20, v18
	v_div_scale_f32 v20, vcc, 1.0, v8, 1.0
	v_mul_f32_e32 v21, v20, v18
	v_fma_f32 v22, -v13, v21, v20
	v_fmac_f32_e32 v21, v22, v18
	v_add_f32_e32 v12, 1.0, v12
	v_fma_f32 v13, -v13, v21, v20
	v_div_scale_f32 v20, s[6:7], v12, v12, 1.0
	v_rcp_f32_e32 v22, v20
	v_div_fmas_f32 v13, v13, v18, v21
	v_mul_f32_e32 v9, 0xbfb8aa3b, v9
	v_div_fixup_f32 v8, v13, v8, 1.0
	v_exp_f32_e32 v9, v9
	v_mul_f32_e32 v4, v4, v8
	v_fma_f32 v8, -v20, v22, 1.0
	v_fmac_f32_e32 v22, v8, v22
	v_div_scale_f32 v8, vcc, 1.0, v12, 1.0
	v_mul_f32_e32 v13, v8, v22
	v_fma_f32 v18, -v20, v13, v8
	v_add_f32_e32 v9, 1.0, v9
	v_fmac_f32_e32 v13, v18, v22
	v_div_scale_f32 v18, s[6:7], v9, v9, 1.0
	v_fma_f32 v8, -v20, v13, v8
	v_rcp_f32_e32 v20, v18
	v_and_b32_e32 v14, 0xffff0000, v14
	v_div_fmas_f32 v8, v8, v22, v13
	v_mul_f32_e32 v13, 0xbfb8aa3b, v14
	v_div_fixup_f32 v8, v8, v12, 1.0
	v_exp_f32_e32 v13, v13
	v_mul_f32_e32 v8, v0, v8
	v_fma_f32 v0, -v18, v20, 1.0
	v_fmac_f32_e32 v20, v0, v20
	v_div_scale_f32 v0, vcc, 1.0, v9, 1.0
	v_mul_f32_e32 v12, v0, v20
	v_fma_f32 v14, -v18, v12, v0
	v_add_f32_e32 v13, 1.0, v13
	v_fmac_f32_e32 v12, v14, v20
	v_div_scale_f32 v14, s[6:7], v13, v13, 1.0
	v_fma_f32 v0, -v18, v12, v0
	v_rcp_f32_e32 v18, v14
	v_div_fmas_f32 v0, v0, v20, v12
	v_mul_f32_e32 v10, 0xbfb8aa3b, v10
	v_div_fixup_f32 v0, v0, v9, 1.0
	v_exp_f32_e32 v10, v10
	v_mul_f32_e32 v0, v5, v0
	v_fma_f32 v5, -v14, v18, 1.0
	v_fmac_f32_e32 v18, v5, v18
	v_div_scale_f32 v5, vcc, 1.0, v13, 1.0
	v_mul_f32_e32 v9, v5, v18
	v_fma_f32 v12, -v14, v9, v5
	v_add_f32_e32 v10, 1.0, v10
	v_fmac_f32_e32 v9, v12, v18
	v_div_scale_f32 v12, s[6:7], v10, v10, 1.0
	v_fma_f32 v5, -v14, v9, v5
	v_rcp_f32_e32 v14, v12
	v_div_fmas_f32 v5, v5, v18, v9
	v_div_fixup_f32 v5, v5, v13, 1.0
	v_mul_f32_e32 v5, v1, v5
	v_fma_f32 v1, -v12, v14, 1.0
	v_mul_f32_e32 v13, 0xbfb8aa3b, v19
	v_fmac_f32_e32 v14, v1, v14
	v_div_scale_f32 v1, vcc, 1.0, v10, 1.0
	v_exp_f32_e32 v13, v13
	v_mul_f32_e32 v9, v1, v14
	v_fma_f32 v18, -v12, v9, v1
	v_fmac_f32_e32 v9, v18, v14
	v_fma_f32 v1, -v12, v9, v1
	v_add_f32_e32 v12, 1.0, v13
	v_div_scale_f32 v13, s[6:7], v12, v12, 1.0
	v_rcp_f32_e32 v18, v13
	v_div_fmas_f32 v1, v1, v14, v9
	v_div_fixup_f32 v1, v1, v10, 1.0
	v_mul_f32_e32 v10, 0xbfb8aa3b, v11
	v_exp_f32_e32 v10, v10
	v_mul_f32_e32 v1, v6, v1
	v_fma_f32 v6, -v13, v18, 1.0
	v_fmac_f32_e32 v18, v6, v18
	v_div_scale_f32 v6, vcc, 1.0, v12, 1.0
	v_mul_f32_e32 v9, v6, v18
	v_fma_f32 v11, -v13, v9, v6
	v_add_f32_e32 v10, 1.0, v10
	v_fmac_f32_e32 v9, v11, v18
	v_div_scale_f32 v11, s[6:7], v10, v10, 1.0
	v_fma_f32 v6, -v13, v9, v6
	v_rcp_f32_e32 v13, v11
	v_div_fmas_f32 v6, v6, v18, v9
	v_div_fixup_f32 v6, v6, v12, 1.0
	v_mul_f32_e32 v6, v2, v6
	v_fma_f32 v2, -v11, v13, 1.0
	v_mul_f32_e32 v12, 0xbfb8aa3b, v15
	v_fmac_f32_e32 v13, v2, v13
	v_div_scale_f32 v2, vcc, 1.0, v10, 1.0
	v_exp_f32_e32 v12, v12
	v_mul_f32_e32 v9, v2, v13
	v_fma_f32 v14, -v11, v9, v2
	v_fmac_f32_e32 v9, v14, v13
	v_fma_f32 v2, -v11, v9, v2
	v_add_f32_e32 v11, 1.0, v12
	v_div_scale_f32 v12, s[6:7], v11, v11, 1.0
	v_rcp_f32_e32 v14, v12
	v_div_fmas_f32 v2, v2, v13, v9
	v_div_fixup_f32 v2, v2, v10, 1.0
	v_mul_f32_e32 v2, v7, v2
	v_fma_f32 v7, -v12, v14, 1.0
	v_fmac_f32_e32 v14, v7, v14
	v_div_scale_f32 v7, vcc, 1.0, v11, 1.0
	v_mul_f32_e32 v9, v7, v14
	v_fma_f32 v10, -v12, v9, v7
	v_fmac_f32_e32 v9, v10, v14
	v_fma_f32 v7, -v12, v9, v7
	v_div_fmas_f32 v7, v7, v14, v9
	v_div_fixup_f32 v7, v7, v11, 1.0
	v_mul_f32_e32 v3, v3, v7
	s_and_b64 vcc, exec, s[8:9]
	s_mov_b32 s7, s26
	s_mov_b32 s6, s59
	v_cvt_pk_bf16_f32 v0, v4, v0
	v_cvt_pk_bf16_f32 v1, v1, v2
	v_cvt_pk_bf16_f32 v2, v8, v5
	v_cvt_pk_bf16_f32 v3, v6, v3
	global_store_dwordx4 v[16:17], v[0:3], off offset:256
	s_cbranch_vccz .LBB0_1763
	s_waitcnt vmcnt(0)
	s_cmpk_gt_u32 s34, 0xff
	s_cbranch_scc1 .LBB0_1772
	s_barrier

; __global__ __launch_bounds__(512, 2) void mega_kernel(Params P) {
;     extern __shared__ __attribute__((aligned(16))) unsigned char shm[];
	.amdhsa_kernel _Z11mega_kernel6Params
		.amdhsa_group_segment_fixed_size 0
		.amdhsa_private_segment_fixed_size 0
		.amdhsa_kernarg_size 616
		.amdhsa_user_sgpr_count 2
		.amdhsa_user_sgpr_dispatch_ptr 0
		.amdhsa_user_sgpr_queue_ptr 0
		.amdhsa_user_sgpr_kernarg_segment_ptr 1
		.amdhsa_user_sgpr_dispatch_id 0
		.amdhsa_user_sgpr_kernarg_preload_length 0
		.amdhsa_user_sgpr_kernarg_preload_offset 0
		.amdhsa_user_sgpr_private_segment_size 0
		.amdhsa_uses_dynamic_stack 0
		.amdhsa_enable_private_segment 0
		.amdhsa_system_sgpr_workgroup_id_x 1
		.amdhsa_system_sgpr_workgroup_id_y 0
		.amdhsa_system_sgpr_workgroup_id_z 0
		.amdhsa_system_sgpr_workgroup_info 0
		.amdhsa_system_vgpr_workitem_id 2
		.amdhsa_next_free_vgpr 256
		.amdhsa_next_free_sgpr 98
		.amdhsa_accum_offset 256
		.amdhsa_reserve_vcc 1
		.amdhsa_float_round_mode_32 0
		.amdhsa_float_round_mode_16_64 0
		.amdhsa_float_denorm_mode_32 3
		.amdhsa_float_denorm_mode_16_64 3
		.amdhsa_dx10_clamp 1
		.amdhsa_ieee_mode 1
		.amdhsa_fp16_overflow 0
		.amdhsa_tg_split 0
		.amdhsa_exception_fp_ieee_invalid_op 0
		.amdhsa_exception_fp_denorm_src 0
		.amdhsa_exception_fp_ieee_div_zero 0
		.amdhsa_exception_fp_ieee_overflow 0
		.amdhsa_exception_fp_ieee_underflow 0
		.amdhsa_exception_fp_ieee_inexact 0
		.amdhsa_exception_int_div_zero 0
	.end_amdhsa_kernel

; __global__ __launch_bounds__(512, 2) void mega_kernel(Params P) {
;     extern __shared__ __attribute__((aligned(16))) unsigned char shm[];
amdhsa.kernels:
  - .agpr_count:     0
    .args:
      - .offset:         0
        .size:           360
        .value_kind:     by_value
      - .offset:         360
        .size:           4
        .value_kind:     hidden_block_count_x
      - .offset:         364
        .size:           4
        .value_kind:     hidden_block_count_y
      - .offset:         368
        .size:           4
        .value_kind:     hidden_block_count_z
      - .offset:         372
        .size:           2
        .value_kind:     hidden_group_size_x
      - .offset:         374
        .size:           2
        .value_kind:     hidden_group_size_y
      - .offset:         376
        .size:           2
        .value_kind:     hidden_group_size_z
      - .offset:         378
        .size:           2
        .value_kind:     hidden_remainder_x
      - .offset:         380
        .size:           2
        .value_kind:     hidden_remainder_y
      - .offset:         382
        .size:           2
        .value_kind:     hidden_remainder_z
      - .offset:         400
        .size:           8
        .value_kind:     hidden_global_offset_x
      - .offset:         408
        .size:           8
        .value_kind:     hidden_global_offset_y
      - .offset:         416
        .size:           8
        .value_kind:     hidden_global_offset_z
      - .offset:         424
        .size:           2
        .value_kind:     hidden_grid_dims
      - .offset:         448
        .size:           8
        .value_kind:     hidden_multigrid_sync_arg
      - .offset:         480
        .size:           4
        .value_kind:     hidden_dynamic_lds_size
    .group_segment_fixed_size: 0
    .kernarg_segment_align: 8
    .kernarg_segment_size: 616
    .language:       OpenCL C
    .language_version:
      - 2
      - 0
    .max_flat_workgroup_size: 512
    .name:           _Z11mega_kernel6Params
    .private_segment_fixed_size: 0
    .sgpr_count:     104
    .sgpr_spill_count: 10
    .symbol:         _Z11mega_kernel6Params.kd
    .uniform_work_group_size: 1
    .uses_dynamic_stack: false
    .vgpr_count:     256
    .vgpr_spill_count: 0
    .wavefront_size: 64
